# v17 plus: proj_a/proj_b barrier removed, GEMM K-loop A-half stage moved seg2->seg3 (vmcnt 8->6), 4-row interleaved combine loop with prefetch
# baseline (speedup 1.0000x reference)
; #define PG8_STAGE(bufoff, gbase, voff) do { _Pragma("unroll") for (int _i = 0; _i < 2; ++_i) \
;         __builtin_amdgcn_global_load_lds((const unsigned*)((const char*)(gbase) + (voff)[_i]), (LAS unsigned*)(lds + (bufoff) + ldsw + _i * 8192), 16, 0, 0); } while (0)
; #define PG8_LDA(dst, b, h) do { _Pragma("unroll") for (int m = 0; m < 4; ++m) _Pragma("unroll") for (int k = 0; k < 2; ++k) dst[m][k] = *(const LAS bf16x8*)(lds + PG8_SA(b, h) + aoff + m * 2048 + k * 1024); } while (0)
; #define PG8_LDB(dst, b, h) do { _Pragma("unroll") for (int n = 0; n < 2; ++n) _Pragma("unroll") for (int k = 0; k < 2; ++k) dst[n][k] = *(const LAS bf16x8*)(lds + PG8_SB(b, h) + boff + n * 2048 + k * 1024); } while (0)
; #define PG8_MMA(ai, bj, At, Bt) do { __builtin_amdgcn_s_setprio(1); _Pragma("unroll") for (int m = 0; m < 4; ++m) _Pragma("unroll") for (int n = 0; n < 2; ++n) _Pragma("unroll") for (int k = 0; k < 2; ++k) \
;         acc[ai][bj][m][n] = __builtin_amdgcn_mfma_f32_16x16x32_bf16(Bt[n][k], At[m][k], acc[ai][bj][m][n], 0, 0, 0); __builtin_amdgcn_s_setprio(0); } while (0)
; #define PG8_WAIT_V(n) asm volatile("s_waitcnt vmcnt(" #n ")" ::: "memory")
; #define PG8_WAIT_L(n) asm volatile("s_waitcnt lgkmcnt(" #n ")" ::: "memory")
; #define PG8_BAR __builtin_amdgcn_s_barrier()
; template <class Epi, class Sched, bool ALIGN_EPI = false, bool SP2 = false>
; __device__ __forceinline__ void gemm_phase(LAS unsigned char* lds, const Gemm g, const Sched& S, const Epi& E) {
;     ...
;             const bool last = (t == nt - 2);
;             const char* a1 = cA + (size_t)(t + 1) * kstep;
;             const char* a2 = last ? nA : cA + (size_t)(t + 2) * kstep; const char* b2 = last ? nB : cB + (size_t)(t + 2) * kstep;
;             const char* a3 = a2 + kstep; const char* b3 = b2 + kstep;
;             if (last && has_next) S.a_ready(nxt);
;             if constexpr (SP2) {
;             PG8_LDB(B0, 0, 0); PG8_LDB(B1, 0, 1); PG8_SCHED; PG8_LDA(At, 0, 0); PG8_STAGE(PG8_SA(1, 1), a1 + hstep, voffA);
;             PG8_WAIT_V(8); PG8_WAIT_L(0); PG8_BAR; PG8_MMA(0, 0, At, B0); PG8_MMA(0, 1, At, B1); PG8_BAR; PG8_SCHED;
;             PG8_LDA(At, 0, 1); PG8_STAGE(PG8_SB(0, 0), b2, voffB); PG8_STAGE(PG8_SB(0, 1), b2 + hstep, voffB); PG8_STAGE(PG8_SA(0, 0), a2, voffA);
;             PG8_WAIT_V(8); PG8_WAIT_L(0); PG8_BAR; PG8_MMA(1, 0, At, B0); PG8_MMA(1, 1, At, B1); PG8_BAR; PG8_SCHED;
.LBB0_73:
	s_add_u32 s8, s0, 0xfff80080
	s_addc_u32 s9, s1, -1
	s_add_i32 s14, 0, 0x10000
	s_cmp_eq_u32 s68, 28
	s_cselect_b32 s39, s7, s9
	s_cselect_b32 s38, s26, s8
	s_cselect_b32 s9, s43, s67
	s_cselect_b32 s8, s59, s66
	s_add_i32 s15, 0, 0x14000
	v_add_u32_e32 v142, s14, v179
	v_add_u32_e32 v158, s15, v179
	ds_read_b128 v[130:133], v142
	ds_read_b128 v[134:137], v142 offset:1024
	ds_read_b128 v[138:141], v142 offset:2048
	ds_read_b128 v[142:145], v142 offset:3072
	ds_read_b128 v[146:149], v158
	ds_read_b128 v[150:153], v158 offset:1024
	ds_read_b128 v[154:157], v158 offset:2048
	ds_read_b128 v[158:161], v158 offset:3072
	v_lshl_add_u64 v[176:177], s[0:1], 0, v[172:173]
	s_add_i32 m0, s71, 0xc000
	ds_read_b128 v[180:183], v200
	ds_read_b128 v[202:205], v200 offset:1024
	ds_read_b128 v[206:209], v200 offset:2048
	ds_read_b128 v[210:213], v200 offset:3072
	ds_read_b128 v[214:217], v200 offset:4096
	ds_read_b128 v[218:221], v200 offset:5120
	ds_read_b128 v[236:239], v200 offset:6144
	ds_read_b128 v[240:243], v200 offset:7168
	global_load_lds_dwordx4 v[176:177], off
	v_lshl_add_u64 v[176:177], s[0:1], 0, v[174:175]
	s_add_i32 m0, s71, 0xe000
	s_nop 0
	global_load_lds_dwordx4 v[176:177], off
	s_waitcnt vmcnt(8)
	s_waitcnt lgkmcnt(0)
	s_barrier
	s_setprio 1
	s_waitcnt lgkmcnt(0)
	v_mfma_f32_16x16x32_bf16 v[126:129], v[130:133], v[180:183], v[126:129]
	v_mfma_f32_16x16x32_bf16 v[122:125], v[138:141], v[180:183], v[122:125]
	v_mfma_f32_16x16x32_bf16 v[110:113], v[130:133], v[206:209], v[110:113]
	v_mfma_f32_16x16x32_bf16 v[106:109], v[138:141], v[206:209], v[106:109]
	v_mfma_f32_16x16x32_bf16 v[94:97], v[130:133], v[214:217], v[94:97]
	v_mfma_f32_16x16x32_bf16 v[90:93], v[138:141], v[214:217], v[90:93]
	v_mfma_f32_16x16x32_bf16 v[78:81], v[130:133], v[236:239], v[78:81]
	v_mfma_f32_16x16x32_bf16 v[74:77], v[138:141], v[236:239], v[74:77]
	v_mfma_f32_16x16x32_bf16 v[126:129], v[134:137], v[202:205], v[126:129]
	v_mfma_f32_16x16x32_bf16 v[122:125], v[142:145], v[202:205], v[122:125]
	v_mfma_f32_16x16x32_bf16 v[110:113], v[134:137], v[210:213], v[110:113]
	v_mfma_f32_16x16x32_bf16 v[106:109], v[142:145], v[210:213], v[106:109]
	v_mfma_f32_16x16x32_bf16 v[94:97], v[134:137], v[218:221], v[94:97]
	v_mfma_f32_16x16x32_bf16 v[90:93], v[142:145], v[218:221], v[90:93]
	v_mfma_f32_16x16x32_bf16 v[78:81], v[134:137], v[240:243], v[78:81]
	v_mfma_f32_16x16x32_bf16 v[74:77], v[142:145], v[240:243], v[74:77]
	s_setprio 0
	s_setprio 1
	v_mfma_f32_16x16x32_bf16 v[118:121], v[146:149], v[180:183], v[118:121]
	v_mfma_f32_16x16x32_bf16 v[114:117], v[154:157], v[180:183], v[114:117]
	v_mfma_f32_16x16x32_bf16 v[102:105], v[146:149], v[206:209], v[102:105]
	v_mfma_f32_16x16x32_bf16 v[98:101], v[154:157], v[206:209], v[98:101]
	v_mfma_f32_16x16x32_bf16 v[86:89], v[146:149], v[214:217], v[86:89]
	v_mfma_f32_16x16x32_bf16 v[82:85], v[154:157], v[214:217], v[82:85]
	v_mfma_f32_16x16x32_bf16 v[70:73], v[146:149], v[236:239], v[70:73]
	v_mfma_f32_16x16x32_bf16 v[66:69], v[154:157], v[236:239], v[66:69]
	v_mfma_f32_16x16x32_bf16 v[118:121], v[150:153], v[202:205], v[118:121]
	v_mfma_f32_16x16x32_bf16 v[114:117], v[158:161], v[202:205], v[114:117]
	v_mfma_f32_16x16x32_bf16 v[102:105], v[150:153], v[210:213], v[102:105]
	v_mfma_f32_16x16x32_bf16 v[98:101], v[158:161], v[210:213], v[98:101]
	v_mfma_f32_16x16x32_bf16 v[86:89], v[150:153], v[218:221], v[86:89]
	v_mfma_f32_16x16x32_bf16 v[82:85], v[158:161], v[218:221], v[82:85]
	v_mfma_f32_16x16x32_bf16 v[70:73], v[150:153], v[240:243], v[70:73]
	v_mfma_f32_16x16x32_bf16 v[66:69], v[158:161], v[240:243], v[66:69]
	s_setprio 0
	s_barrier
	s_add_i32 s14, s14, s70
	v_lshl_add_u64 v[176:177], s[8:9], 0, v[166:167]
	s_mov_b32 m0, s14
	ds_read_b128 v[180:183], v200 offset:16384
	ds_read_b128 v[202:205], v200 offset:17408
	ds_read_b128 v[206:209], v200 offset:18432
	ds_read_b128 v[210:213], v200 offset:19456
	ds_read_b128 v[214:217], v200 offset:20480
	ds_read_b128 v[218:221], v200 offset:21504
	ds_read_b128 v[236:239], v200 offset:22528
	ds_read_b128 v[240:243], v200 offset:23552
	global_load_lds_dwordx4 v[176:177], off
	s_add_i32 m0, s14, 0x2000
	s_add_u32 s20, s8, 0x80000
	v_lshl_add_u64 v[184:185], s[8:9], 0, v[162:163]
	s_addc_u32 s21, s9, 0
	s_add_i32 s14, s15, s70
	global_load_lds_dwordx4 v[184:185], off
	v_lshl_add_u64 v[198:199], s[20:21], 0, v[166:167]
	s_mov_b32 m0, s14
	global_load_lds_dwordx4 v[198:199], off
	v_lshl_add_u64 v[198:199], s[20:21], 0, v[162:163]
	s_add_i32 m0, s14, 0x2000
	s_nop 0
	global_load_lds_dwordx4 v[198:199], off
	s_waitcnt vmcnt(6)
	s_waitcnt lgkmcnt(0)
	s_barrier
; #define PG8_STAGE(bufoff, gbase, voff) do { _Pragma("unroll") for (int _i = 0; _i < 2; ++_i) \
;         __builtin_amdgcn_global_load_lds((const unsigned*)((const char*)(gbase) + (voff)[_i]), (LAS unsigned*)(lds + (bufoff) + ldsw + _i * 8192), 16, 0, 0); } while (0)
; #define PG8_LDA(dst, b, h) do { _Pragma("unroll") for (int m = 0; m < 4; ++m) _Pragma("unroll") for (int k = 0; k < 2; ++k) dst[m][k] = *(const LAS bf16x8*)(lds + PG8_SA(b, h) + aoff + m * 2048 + k * 1024); } while (0)
; #define PG8_LDB(dst, b, h) do { _Pragma("unroll") for (int n = 0; n < 2; ++n) _Pragma("unroll") for (int k = 0; k < 2; ++k) dst[n][k] = *(const LAS bf16x8*)(lds + PG8_SB(b, h) + boff + n * 2048 + k * 1024); } while (0)
; #define PG8_MMA(ai, bj, At, Bt) do { __builtin_amdgcn_s_setprio(1); _Pragma("unroll") for (int m = 0; m < 4; ++m) _Pragma("unroll") for (int n = 0; n < 2; ++n) _Pragma("unroll") for (int k = 0; k < 2; ++k) \
;         acc[ai][bj][m][n] = __builtin_amdgcn_mfma_f32_16x16x32_bf16(Bt[n][k], At[m][k], acc[ai][bj][m][n], 0, 0, 0); __builtin_amdgcn_s_setprio(0); } while (0)
; #define PG8_WAIT_V(n) asm volatile("s_waitcnt vmcnt(" #n ")" ::: "memory")
; #define PG8_WAIT_L(n) asm volatile("s_waitcnt lgkmcnt(" #n ")" ::: "memory")
; #define PG8_BAR __builtin_amdgcn_s_barrier()
; #define PG8_SCHED __builtin_amdgcn_sched_barrier(0)
; template <class Epi, class Sched, bool ALIGN_EPI = false, bool SP2 = false>
; __device__ __forceinline__ void gemm_phase(LAS unsigned char* lds, const Gemm g, const Sched& S, const Epi& E) {
;     ...
;             PG8_WAIT_V(8); PG8_WAIT_L(0); PG8_BAR; PG8_MMA(1, 0, At, B0); PG8_MMA(1, 1, At, B1); PG8_BAR; PG8_SCHED;
;             PG8_LDB(B0, 1, 0); PG8_LDB(B1, 1, 1); PG8_SCHED; PG8_LDA(At, 1, 0); PG8_STAGE(PG8_SA(0, 1), a2 + hstep, voffA);
;             PG8_WAIT_V(8); PG8_WAIT_L(0); PG8_BAR; PG8_MMA(0, 0, At, B0); PG8_MMA(0, 1, At, B1); PG8_BAR; PG8_SCHED;
	s_setprio 1
	s_waitcnt lgkmcnt(0)
	v_mfma_f32_16x16x32_bf16 v[62:65], v[130:133], v[180:183], v[62:65]
	v_mfma_f32_16x16x32_bf16 v[58:61], v[138:141], v[180:183], v[58:61]
	v_mfma_f32_16x16x32_bf16 v[46:49], v[130:133], v[206:209], v[46:49]
	v_mfma_f32_16x16x32_bf16 v[42:45], v[138:141], v[206:209], v[42:45]
	v_mfma_f32_16x16x32_bf16 v[30:33], v[130:133], v[214:217], v[30:33]
	v_mfma_f32_16x16x32_bf16 v[26:29], v[138:141], v[214:217], v[26:29]
	v_mfma_f32_16x16x32_bf16 v[14:17], v[130:133], v[236:239], v[14:17]
	v_mfma_f32_16x16x32_bf16 v[10:13], v[138:141], v[236:239], v[10:13]
	v_mfma_f32_16x16x32_bf16 v[62:65], v[134:137], v[202:205], v[62:65]
	v_mfma_f32_16x16x32_bf16 v[58:61], v[142:145], v[202:205], v[58:61]
	v_mfma_f32_16x16x32_bf16 v[46:49], v[134:137], v[210:213], v[46:49]
	v_mfma_f32_16x16x32_bf16 v[42:45], v[142:145], v[210:213], v[42:45]
	v_mfma_f32_16x16x32_bf16 v[30:33], v[134:137], v[218:221], v[30:33]
	v_mfma_f32_16x16x32_bf16 v[26:29], v[142:145], v[218:221], v[26:29]
	v_mfma_f32_16x16x32_bf16 v[14:17], v[134:137], v[240:243], v[14:17]
	v_mfma_f32_16x16x32_bf16 v[10:13], v[142:145], v[240:243], v[10:13]
	s_setprio 0
	s_setprio 1
	v_mfma_f32_16x16x32_bf16 v[54:57], v[146:149], v[180:183], v[54:57]
	v_mfma_f32_16x16x32_bf16 v[50:53], v[154:157], v[180:183], v[50:53]
	v_mfma_f32_16x16x32_bf16 v[38:41], v[146:149], v[206:209], v[38:41]
	v_mfma_f32_16x16x32_bf16 v[34:37], v[154:157], v[206:209], v[34:37]
	v_mfma_f32_16x16x32_bf16 v[22:25], v[146:149], v[214:217], v[22:25]
	v_mfma_f32_16x16x32_bf16 v[18:21], v[154:157], v[214:217], v[18:21]
	v_mfma_f32_16x16x32_bf16 v[6:9], v[146:149], v[236:239], v[6:9]
	v_mfma_f32_16x16x32_bf16 v[2:5], v[154:157], v[236:239], v[2:5]
	v_mfma_f32_16x16x32_bf16 v[54:57], v[150:153], v[202:205], v[54:57]
	v_mfma_f32_16x16x32_bf16 v[50:53], v[158:161], v[202:205], v[50:53]
	v_mfma_f32_16x16x32_bf16 v[38:41], v[150:153], v[210:213], v[38:41]
	v_mfma_f32_16x16x32_bf16 v[34:37], v[158:161], v[210:213], v[34:37]
	v_mfma_f32_16x16x32_bf16 v[22:25], v[150:153], v[218:221], v[22:25]
	v_mfma_f32_16x16x32_bf16 v[18:21], v[158:161], v[218:221], v[18:21]
	v_mfma_f32_16x16x32_bf16 v[6:9], v[150:153], v[240:243], v[6:9]
	v_mfma_f32_16x16x32_bf16 v[2:5], v[158:161], v[240:243], v[2:5]
	s_setprio 0
	s_barrier
	s_add_i32 s14, 0, 0x18000
	s_add_i32 s15, 0, 0x1c000
	v_add_u32_e32 v142, s14, v179
	v_add_u32_e32 v158, s15, v179
	ds_read_b128 v[130:133], v142
	ds_read_b128 v[134:137], v142 offset:1024
	ds_read_b128 v[138:141], v142 offset:2048
	ds_read_b128 v[142:145], v142 offset:3072
	ds_read_b128 v[146:149], v158
	ds_read_b128 v[150:153], v158 offset:1024
	ds_read_b128 v[154:157], v158 offset:2048
	ds_read_b128 v[158:161], v158 offset:3072
	s_add_u32 s20, s38, 0x80000
	s_addc_u32 s21, s39, 0
	s_mov_b32 m0, s27
	v_lshl_add_u64 v[246:247], s[20:21], 0, v[168:169]
	ds_read_b128 v[180:183], v200 offset:32768
	ds_read_b128 v[202:205], v200 offset:33792
	ds_read_b128 v[206:209], v200 offset:34816
	ds_read_b128 v[210:213], v200 offset:35840
	ds_read_b128 v[214:217], v200 offset:36864
	ds_read_b128 v[218:221], v200 offset:37888
	ds_read_b128 v[236:239], v200 offset:38912
	ds_read_b128 v[240:243], v200 offset:39936
	v_lshl_add_u64 v[198:199], s[38:39], 0, v[168:169]
	s_mov_b32 m0, s71
	v_lshl_add_u64 v[244:245], s[38:39], 0, v[164:165]
	global_load_lds_dwordx4 v[198:199], off
	s_mov_b32 m0, s93
	s_nop 0
	global_load_lds_dwordx4 v[244:245], off
	s_mov_b32 m0, s27
	s_nop 0
	global_load_lds_dwordx4 v[246:247], off
	v_lshl_add_u64 v[246:247], s[20:21], 0, v[164:165]
	s_mov_b32 m0, s94
	s_nop 0
	global_load_lds_dwordx4 v[246:247], off
	s_waitcnt vmcnt(8)
	s_waitcnt lgkmcnt(0)
	s_barrier
	s_setprio 1
	s_waitcnt lgkmcnt(0)
	v_mfma_f32_16x16x32_bf16 v[126:129], v[130:133], v[180:183], v[126:129]
	v_mfma_f32_16x16x32_bf16 v[122:125], v[138:141], v[180:183], v[122:125]
	v_mfma_f32_16x16x32_bf16 v[110:113], v[130:133], v[206:209], v[110:113]
	v_mfma_f32_16x16x32_bf16 v[106:109], v[138:141], v[206:209], v[106:109]
	v_mfma_f32_16x16x32_bf16 v[94:97], v[130:133], v[214:217], v[94:97]
	v_mfma_f32_16x16x32_bf16 v[90:93], v[138:141], v[214:217], v[90:93]
	v_mfma_f32_16x16x32_bf16 v[78:81], v[130:133], v[236:239], v[78:81]
	v_mfma_f32_16x16x32_bf16 v[74:77], v[138:141], v[236:239], v[74:77]
	v_mfma_f32_16x16x32_bf16 v[126:129], v[134:137], v[202:205], v[126:129]
	v_mfma_f32_16x16x32_bf16 v[122:125], v[142:145], v[202:205], v[122:125]
	v_mfma_f32_16x16x32_bf16 v[110:113], v[134:137], v[210:213], v[110:113]
	v_mfma_f32_16x16x32_bf16 v[106:109], v[142:145], v[210:213], v[106:109]
	v_mfma_f32_16x16x32_bf16 v[94:97], v[134:137], v[218:221], v[94:97]
	v_mfma_f32_16x16x32_bf16 v[90:93], v[142:145], v[218:221], v[90:93]
	v_mfma_f32_16x16x32_bf16 v[78:81], v[134:137], v[240:243], v[78:81]
	v_mfma_f32_16x16x32_bf16 v[74:77], v[142:145], v[240:243], v[74:77]
	s_setprio 0
	s_setprio 1
	v_mfma_f32_16x16x32_bf16 v[118:121], v[146:149], v[180:183], v[118:121]
	v_mfma_f32_16x16x32_bf16 v[114:117], v[154:157], v[180:183], v[114:117]
	v_mfma_f32_16x16x32_bf16 v[102:105], v[146:149], v[206:209], v[102:105]
	v_mfma_f32_16x16x32_bf16 v[98:101], v[154:157], v[206:209], v[98:101]
	v_mfma_f32_16x16x32_bf16 v[86:89], v[146:149], v[214:217], v[86:89]
	v_mfma_f32_16x16x32_bf16 v[82:85], v[154:157], v[214:217], v[82:85]
	v_mfma_f32_16x16x32_bf16 v[70:73], v[146:149], v[236:239], v[70:73]
	v_mfma_f32_16x16x32_bf16 v[66:69], v[154:157], v[236:239], v[66:69]
	v_mfma_f32_16x16x32_bf16 v[118:121], v[150:153], v[202:205], v[118:121]
	v_mfma_f32_16x16x32_bf16 v[114:117], v[158:161], v[202:205], v[114:117]
	v_mfma_f32_16x16x32_bf16 v[102:105], v[150:153], v[210:213], v[102:105]
	v_mfma_f32_16x16x32_bf16 v[98:101], v[158:161], v[210:213], v[98:101]
	v_mfma_f32_16x16x32_bf16 v[86:89], v[150:153], v[218:221], v[86:89]
	v_mfma_f32_16x16x32_bf16 v[82:85], v[158:161], v[218:221], v[82:85]
	v_mfma_f32_16x16x32_bf16 v[70:73], v[150:153], v[240:243], v[70:73]
	v_mfma_f32_16x16x32_bf16 v[66:69], v[158:161], v[240:243], v[66:69]
	s_setprio 0
	s_barrier
; #define PG8_STAGE(bufoff, gbase, voff) do { _Pragma("unroll") for (int _i = 0; _i < 2; ++_i) \
;         __builtin_amdgcn_global_load_lds((const unsigned*)((const char*)(gbase) + (voff)[_i]), (LAS unsigned*)(lds + (bufoff) + ldsw + _i * 8192), 16, 0, 0); } while (0)
; #define PG8_LDA(dst, b, h) do { _Pragma("unroll") for (int m = 0; m < 4; ++m) _Pragma("unroll") for (int k = 0; k < 2; ++k) dst[m][k] = *(const LAS bf16x8*)(lds + PG8_SA(b, h) + aoff + m * 2048 + k * 1024); } while (0)
; #define PG8_MMA(ai, bj, At, Bt) do { __builtin_amdgcn_s_setprio(1); _Pragma("unroll") for (int m = 0; m < 4; ++m) _Pragma("unroll") for (int n = 0; n < 2; ++n) _Pragma("unroll") for (int k = 0; k < 2; ++k) \
;         acc[ai][bj][m][n] = __builtin_amdgcn_mfma_f32_16x16x32_bf16(Bt[n][k], At[m][k], acc[ai][bj][m][n], 0, 0, 0); __builtin_amdgcn_s_setprio(0); } while (0)
; #define PG8_WAIT_V(n) asm volatile("s_waitcnt vmcnt(" #n ")" ::: "memory")
; #define PG8_WAIT_L(n) asm volatile("s_waitcnt lgkmcnt(" #n ")" ::: "memory")
; #define PG8_BAR __builtin_amdgcn_s_barrier()
; #define PG8_SCHED __builtin_amdgcn_sched_barrier(0)
; template <class Epi, class Sched, bool ALIGN_EPI = false, bool SP2 = false>
; __device__ __forceinline__ void gemm_phase(LAS unsigned char* lds, const Gemm g, const Sched& S, const Epi& E) {
;     ...
;             PG8_LDA(At, 1, 1); PG8_STAGE(PG8_SB(1, 0), b3, voffB); PG8_STAGE(PG8_SB(1, 1), b3 + hstep, voffB); PG8_STAGE(PG8_SA(1, 0), a3, voffA);
;             PG8_WAIT_V(8); PG8_WAIT_L(0); PG8_BAR; PG8_MMA(1, 0, At, B0); PG8_MMA(1, 1, At, B1); PG8_BAR; PG8_SCHED;
	s_add_i32 s14, s14, s70
	v_lshl_add_u64 v[176:177], v[176:177], 0, s[18:19]
	s_mov_b32 m0, s14
	ds_read_b128 v[180:183], v200 offset:49152
	ds_read_b128 v[202:205], v200 offset:50176
	ds_read_b128 v[206:209], v200 offset:51200
	ds_read_b128 v[210:213], v200 offset:52224
	ds_read_b128 v[214:217], v200 offset:53248
	ds_read_b128 v[218:221], v200 offset:54272
	ds_read_b128 v[236:239], v200 offset:55296
	ds_read_b128 v[240:243], v200 offset:56320
	global_load_lds_dwordx4 v[176:177], off
	s_add_i32 m0, s14, 0x2000
	s_add_u32 s8, s8, 0x80080
	v_lshl_add_u64 v[176:177], v[184:185], 0, s[18:19]
	s_addc_u32 s9, s9, 0
	s_add_i32 s14, s15, s70
	global_load_lds_dwordx4 v[176:177], off
	v_lshl_add_u64 v[176:177], s[8:9], 0, v[166:167]
	s_mov_b32 m0, s14
	s_nop 0
	global_load_lds_dwordx4 v[176:177], off
	v_lshl_add_u64 v[176:177], s[8:9], 0, v[162:163]
	s_add_i32 m0, s14, 0x2000
	s_nop 0
	global_load_lds_dwordx4 v[176:177], off
	v_lshl_add_u64 v[176:177], v[198:199], 0, s[18:19]
	s_mov_b32 m0, s95
	s_nop 0
	global_load_lds_dwordx4 v[176:177], off
	v_lshl_add_u64 v[176:177], v[244:245], 0, s[18:19]
	s_mov_b32 m0, s96
	s_nop 0
	global_load_lds_dwordx4 v[176:177], off
	s_waitcnt vmcnt(8)
	s_waitcnt lgkmcnt(0)
	s_barrier
	s_setprio 1
	s_waitcnt lgkmcnt(0)
	v_mfma_f32_16x16x32_bf16 v[62:65], v[130:133], v[180:183], v[62:65]
	v_mfma_f32_16x16x32_bf16 v[58:61], v[138:141], v[180:183], v[58:61]
	v_mfma_f32_16x16x32_bf16 v[46:49], v[130:133], v[206:209], v[46:49]
	v_mfma_f32_16x16x32_bf16 v[42:45], v[138:141], v[206:209], v[42:45]
	v_mfma_f32_16x16x32_bf16 v[30:33], v[130:133], v[214:217], v[30:33]
	v_mfma_f32_16x16x32_bf16 v[26:29], v[138:141], v[214:217], v[26:29]
	v_mfma_f32_16x16x32_bf16 v[14:17], v[130:133], v[236:239], v[14:17]
	v_mfma_f32_16x16x32_bf16 v[10:13], v[138:141], v[236:239], v[10:13]
	v_mfma_f32_16x16x32_bf16 v[62:65], v[134:137], v[202:205], v[62:65]
	v_mfma_f32_16x16x32_bf16 v[58:61], v[142:145], v[202:205], v[58:61]
	v_mfma_f32_16x16x32_bf16 v[46:49], v[134:137], v[210:213], v[46:49]
	v_mfma_f32_16x16x32_bf16 v[42:45], v[142:145], v[210:213], v[42:45]
	v_mfma_f32_16x16x32_bf16 v[30:33], v[134:137], v[218:221], v[30:33]
	v_mfma_f32_16x16x32_bf16 v[26:29], v[142:145], v[218:221], v[26:29]
	v_mfma_f32_16x16x32_bf16 v[14:17], v[134:137], v[240:243], v[14:17]
	v_mfma_f32_16x16x32_bf16 v[10:13], v[142:145], v[240:243], v[10:13]
	s_setprio 0
	s_setprio 1
	v_mfma_f32_16x16x32_bf16 v[54:57], v[146:149], v[180:183], v[54:57]
	v_mfma_f32_16x16x32_bf16 v[50:53], v[154:157], v[180:183], v[50:53]
	v_mfma_f32_16x16x32_bf16 v[38:41], v[146:149], v[206:209], v[38:41]
	v_mfma_f32_16x16x32_bf16 v[34:37], v[154:157], v[206:209], v[34:37]
	v_mfma_f32_16x16x32_bf16 v[22:25], v[146:149], v[214:217], v[22:25]
	v_mfma_f32_16x16x32_bf16 v[18:21], v[154:157], v[214:217], v[18:21]
	v_mfma_f32_16x16x32_bf16 v[6:9], v[146:149], v[236:239], v[6:9]
	v_mfma_f32_16x16x32_bf16 v[2:5], v[154:157], v[236:239], v[2:5]
	v_mfma_f32_16x16x32_bf16 v[54:57], v[150:153], v[202:205], v[54:57]
	v_mfma_f32_16x16x32_bf16 v[50:53], v[158:161], v[202:205], v[50:53]
	v_mfma_f32_16x16x32_bf16 v[38:41], v[150:153], v[210:213], v[38:41]
	v_mfma_f32_16x16x32_bf16 v[34:37], v[158:161], v[210:213], v[34:37]
	v_mfma_f32_16x16x32_bf16 v[22:25], v[150:153], v[218:221], v[22:25]
	v_mfma_f32_16x16x32_bf16 v[18:21], v[158:161], v[218:221], v[18:21]
	v_mfma_f32_16x16x32_bf16 v[6:9], v[150:153], v[240:243], v[6:9]
	v_mfma_f32_16x16x32_bf16 v[2:5], v[158:161], v[240:243], v[2:5]
	s_setprio 0
	s_barrier
	s_add_i32 s68, s68, 2
	s_add_u32 s0, s0, 0x100
	s_addc_u32 s1, s1, 0
	s_add_u32 s66, s66, 0x100
	s_addc_u32 s67, s67, 0
	s_cmp_gt_u32 s68, 29
	s_cbranch_scc0 .LBB0_73
	s_and_b64 vcc, exec, s[46:47]
	s_cbranch_vccz .LBB0_76
	s_barrier

; __device__ __forceinline__ float bf_lo(unsigned w) { return __uint_as_float(w << 16); }
; __device__ __forceinline__ float bf_hi(unsigned w) { return __uint_as_float(w & 0xffff0000u); }
; #define INP(i) inptr(lds, (i))
; __device__ __forceinline__ void attn_phase(LAS unsigned char* lds, unsigned char* ws, int l) {
;     ...
;             __builtin_amdgcn_fence(__ATOMIC_RELEASE, "workgroup"); __syncthreads(); __builtin_amdgcn_fence(__ATOMIC_ACQUIRE, "workgroup");
;             int tid = threadIdx.x; asm volatile("" : "+v"(tid));
;             const int lane = tid & 63, wv = tid >> 6;
;             const float lam_init = 0.8f - 0.6f * expf(-0.3f * (float)l);
;             const float* q1 = INP(3) + l * 128; const float* k1 = INP(4) + l * 128; const float* q2 = INP(5) + l * 128; const float* k2 = INP(6) + l * 128;
;             const float d1 = wave_sum(q1[lane] * k1[lane] + q1[lane + 64] * k1[lane + 64]), d2 = wave_sum(q2[lane] * k2[lane] + q2[lane + 64] * k2[lane + 64]);
;             const float lam = expf(d1) - expf(d2) + lam_init;
;             const f32x4 g = *(const f32x4*)(INP(7) + l * 256 + 4 * lane) * (1.0f - lam_init);
;             for (int r = 0; r < 32; ++r) { const size_t t = (size_t)b * SEQ + qblk * 256 + wv * 32 + r;
;                 const u32x2 a = *(const u32x2*)(O12 + t * 4096 + h * 256 + 4 * lane), bb = *(const u32x2*)(O12 + t * 4096 + 2048 + h * 256 + 4 * lane);
;                 f32x4 o = (f32x4){bf_lo(a.x), bf_hi(a.x), bf_lo(a.y), bf_hi(a.y)} - (f32x4){bf_lo(bb.x), bf_hi(bb.x), bf_lo(bb.y), bf_hi(bb.y)} * lam;
;                 const float ss = wave_sum(o[0] * o[0] + o[1] * o[1] + o[2] * o[2] + o[3] * o[3]);
.LBB0_284:
	v_mov_b32_e32 v20, v222
	v_mov_b32_e32 v0, s88
	s_waitcnt vmcnt(0)
	s_barrier
	ds_read2_b64 v[2:5], v0 offset1:1
	v_mov_b32_e32 v0, s89
	ds_read2_b64 v[6:9], v0 offset1:1
	v_and_b32_e32 v21, 63, v20
	v_lshlrev_b32_e32 v0, 2, v21
	s_waitcnt lgkmcnt(1)
	v_readfirstlane_b32 s0, v2
	v_readfirstlane_b32 s1, v3
	s_add_u32 s0, s0, s6
	s_addc_u32 s1, s1, s7
	v_readfirstlane_b32 s13, v4
	v_readfirstlane_b32 s14, v5
	s_add_u32 s20, s13, s6
	s_addc_u32 s21, s14, s7
	s_waitcnt lgkmcnt(0)
	v_readfirstlane_b32 s13, v6
	v_readfirstlane_b32 s14, v7
	s_add_u32 s24, s13, s6
	v_lshl_add_u64 v[2:3], s[0:1], 0, v[0:1]
	s_addc_u32 s25, s14, s7
	v_readfirstlane_b32 s13, v8
	v_lshl_add_u64 v[4:5], s[20:21], 0, v[0:1]
	flat_load_dword v6, v[2:3]
	flat_load_dword v7, v[2:3] offset:256
	s_nop 0
	flat_load_dword v2, v[4:5]
	flat_load_dword v3, v[4:5] offset:256
	v_readfirstlane_b32 s14, v9
	s_add_u32 s28, s13, s6
	s_addc_u32 s29, s14, s7
	v_lshl_add_u64 v[4:5], s[24:25], 0, v[0:1]
	v_lshl_add_u64 v[8:9], s[28:29], 0, v[0:1]
	flat_load_dword v18, v[4:5]
	flat_load_dword v19, v[4:5] offset:256
	s_nop 0
	flat_load_dword v4, v[8:9]
	flat_load_dword v5, v[8:9] offset:256
	v_mov_b32_e32 v0, s90
	ds_read_b64 v[8:9], v0
	v_lshlrev_b32_e32 v0, 4, v21
	v_xor_b32_e32 v14, 8, v230
	v_xor_b32_e32 v15, 16, v230
	v_mov_b32_e32 v115, v114
	s_waitcnt lgkmcnt(0)
	v_readfirstlane_b32 s0, v8
	v_readfirstlane_b32 s1, v9
	s_add_u32 s0, s0, s30
	s_addc_u32 s1, s1, s31
	v_lshl_add_u64 v[8:9], s[0:1], 0, v[0:1]
	flat_load_dwordx4 v[10:13], v[8:9]
	v_xor_b32_e32 v0, 1, v230
	v_cmp_lt_i32_e32 vcc, v0, v132
	v_xor_b32_e32 v8, 2, v230
	v_xor_b32_e32 v9, 4, v230
	v_cndmask_b32_e32 v0, v230, v0, vcc
	v_lshlrev_b32_e32 v0, 2, v0
	v_cmp_lt_i32_e32 vcc, v8, v132
	s_mov_b32 s1, s35
	s_or_b32 s0, s34, s47
	v_cndmask_b32_e32 v8, v230, v8, vcc
	v_cmp_lt_i32_e32 vcc, v9, v132
	s_mov_b64 s[36:37], 0
	s_waitcnt vmcnt(0)
	v_pk_mul_f32 v[2:3], v[6:7], v[2:3]
	s_nop 0
	v_add_f32_e32 v6, v2, v3
	ds_bpermute_b32 v7, v0, v6
	v_cndmask_b32_e32 v9, v230, v9, vcc
	v_cmp_lt_i32_e32 vcc, v14, v132
	v_pk_mul_f32 v[2:3], v[18:19], v[4:5]
	s_nop 0
	v_add_f32_e32 v4, v2, v3
	ds_bpermute_b32 v5, v0, v4
	v_cndmask_b32_e32 v16, v230, v14, vcc
	v_lshlrev_b32_e32 v14, 2, v8
	v_ashrrev_i32_e32 v8, 2, v20
	s_waitcnt lgkmcnt(0)
	v_add_f32_e32 v6, v6, v7
	v_cmp_lt_i32_e32 vcc, v15, v132
	v_and_b32_e32 v8, 0xfffffff0, v8
	ds_bpermute_b32 v7, v14, v6
	v_cndmask_b32_e32 v17, v230, v15, vcc
	v_lshlrev_b32_e32 v15, 2, v9
	v_ashrrev_i32_e32 v9, 31, v8
	v_lshl_add_u64 v[2:3], s[0:1], 0, v[8:9]
	v_add_f32_e32 v8, v4, v5
	ds_bpermute_b32 v9, v14, v8
	s_waitcnt lgkmcnt(1)
	v_add_f32_e32 v6, v6, v7
	ds_bpermute_b32 v7, v15, v6
	v_lshlrev_b32_e32 v16, 2, v16
	v_lshlrev_b32_e32 v17, 2, v17
	s_waitcnt lgkmcnt(1)
	v_add_f32_e32 v8, v8, v9
	ds_bpermute_b32 v9, v15, v8
	s_waitcnt lgkmcnt(1)
	v_add_f32_e32 v6, v6, v7
	ds_bpermute_b32 v7, v16, v6
	v_lshlrev_b32_e32 v20, 3, v21
	v_lshlrev_b64 v[4:5], 12, v[2:3]
	s_waitcnt lgkmcnt(1)
	v_add_f32_e32 v8, v8, v9
	ds_bpermute_b32 v9, v16, v8
	s_waitcnt lgkmcnt(1)
	v_add_f32_e32 v18, v6, v7
	v_lshlrev_b64 v[2:3], 13, v[2:3]
	ds_bpermute_b32 v19, v17, v18
	v_or_b32_e32 v2, v2, v20
	v_lshl_add_u64 v[6:7], s[8:9], 0, v[2:3]
	s_waitcnt lgkmcnt(1)
	v_add_f32_e32 v2, v8, v9
	ds_bpermute_b32 v3, v17, v2
	s_waitcnt lgkmcnt(1)
	v_add_f32_e32 v18, v18, v19
	ds_bpermute_b32 v19, v131, v18
	v_pk_mul_f32 v[8:9], v[114:115], v[12:13]
	v_or_b32_e32 v4, v4, v20
	s_waitcnt lgkmcnt(1)
	v_add_f32_e32 v2, v2, v3
	ds_bpermute_b32 v3, v131, v2
	s_waitcnt lgkmcnt(1)
	v_add_f32_e32 v12, v18, v19
	v_mul_f32_e32 v13, 0x3fb8aa3b, v12
	v_fma_f32 v18, v12, s83, -v13
	v_rndne_f32_e32 v19, v13
	v_fmac_f32_e32 v18, 0x32a5705f, v12
	v_sub_f32_e32 v13, v13, v19
	s_waitcnt lgkmcnt(0)
	v_add_f32_e32 v2, v2, v3
	v_add_f32_e32 v3, v13, v18
	v_mul_f32_e32 v13, 0x3fb8aa3b, v2
	v_fma_f32 v18, v2, s83, -v13
	v_rndne_f32_e32 v20, v13
	v_cvt_i32_f32_e32 v19, v19
	v_exp_f32_e32 v3, v3
	v_fmac_f32_e32 v18, 0x32a5705f, v2
	v_sub_f32_e32 v13, v13, v20
	v_add_f32_e32 v13, v13, v18
	v_cvt_i32_f32_e32 v20, v20
	v_exp_f32_e32 v13, v13
	v_ldexp_f32 v3, v3, v19
	v_cmp_ngt_f32_e32 vcc, s84, v12
	v_lshl_add_u64 v[4:5], s[66:67], 0, v[4:5]
	v_pk_mul_f32 v[10:11], v[116:117], v[10:11]
	v_cndmask_b32_e32 v3, 0, v3, vcc
	v_cmp_nlt_f32_e32 vcc, s85, v12
	v_ldexp_f32 v12, v13, v20
	s_nop 0
	v_cndmask_b32_e32 v3, v231, v3, vcc
	v_cmp_ngt_f32_e32 vcc, s84, v2
	s_nop 1
	v_cndmask_b32_e32 v12, 0, v12, vcc
	v_cmp_nlt_f32_e32 vcc, s85, v2
	s_nop 1
	v_cndmask_b32_e32 v2, v231, v12, vcc
	v_sub_f32_e32 v2, v3, v2
	v_add_f32_e32 v12, v130, v2
	v_mov_b32_e32 v13, v12
	v_mov_b32_e32 v2, v12
	v_mov_b32_e32 v3, v12
	v_xor_b32_e32 v27, 0x80000000, v3
	v_xor_b32_e32 v26, 0x80000000, v2
	global_load_dwordx2 v[44:45], v[6:7], off
	s_mov_b64 s[0:1], 0x1000
	v_lshl_add_u64 v[18:19], v[6:7], 0, s[0:1]
	global_load_dwordx2 v[46:47], v[18:19], off
	s_mov_b64 s[0:1], 0x2000
	v_lshl_add_u64 v[18:19], v[6:7], 0, s[0:1]
	global_load_dwordx2 v[48:49], v[18:19], off
	s_mov_b64 s[0:1], 0x3000
	v_lshl_add_u64 v[18:19], v[6:7], 0, s[0:1]
	global_load_dwordx2 v[50:51], v[18:19], off
	s_mov_b64 s[0:1], 0x4000
	v_lshl_add_u64 v[18:19], v[6:7], 0, s[0:1]
	global_load_dwordx2 v[52:53], v[18:19], off
	s_mov_b64 s[0:1], 0x5000
	v_lshl_add_u64 v[18:19], v[6:7], 0, s[0:1]
	global_load_dwordx2 v[54:55], v[18:19], off
	s_mov_b64 s[0:1], 0x6000
	v_lshl_add_u64 v[18:19], v[6:7], 0, s[0:1]
	global_load_dwordx2 v[56:57], v[18:19], off
	s_mov_b64 s[0:1], 0x7000
	v_lshl_add_u64 v[18:19], v[6:7], 0, s[0:1]
	global_load_dwordx2 v[58:59], v[18:19], off
	s_waitcnt vmcnt(0)
	s_branch .Lcomb_body
; __device__ __forceinline__ float bf_lo(unsigned w) { return __uint_as_float(w << 16); }
; __device__ __forceinline__ float bf_hi(unsigned w) { return __uint_as_float(w & 0xffff0000u); }
; __device__ __forceinline__ void attn_phase(LAS unsigned char* lds, unsigned char* ws, int l) {
;     ...
;             for (int r = 0; r < 32; ++r) { const size_t t = (size_t)b * SEQ + qblk * 256 + wv * 32 + r;
;                 const u32x2 a = *(const u32x2*)(O12 + t * 4096 + h * 256 + 4 * lane), bb = *(const u32x2*)(O12 + t * 4096 + 2048 + h * 256 + 4 * lane);
;                 f32x4 o = (f32x4){bf_lo(a.x), bf_hi(a.x), bf_lo(a.y), bf_hi(a.y)} - (f32x4){bf_lo(bb.x), bf_hi(bb.x), bf_lo(bb.y), bf_hi(bb.y)} * lam;
;                 const float ss = wave_sum(o[0] * o[0] + o[1] * o[1] + o[2] * o[2] + o[3] * o[3]);
.Lcomb_loop:
	s_waitcnt vmcnt(4)
.Lcomb_body:
	v_mov_b64_e32 v[28:29], v[44:45]
	v_mov_b64_e32 v[30:31], v[46:47]
	v_mov_b64_e32 v[32:33], v[48:49]
	v_mov_b64_e32 v[34:35], v[50:51]
	v_mov_b64_e32 v[36:37], v[52:53]
	v_mov_b64_e32 v[38:39], v[54:55]
	v_mov_b64_e32 v[40:41], v[56:57]
	v_mov_b64_e32 v[42:43], v[58:59]
	s_mov_b64 s[0:1], 0x8000
	v_lshl_add_u64 v[6:7], v[6:7], 0, s[0:1]
	s_cmp_eq_u32 s36, 0xc000
	s_cbranch_scc1 .Lcomb_nopf
	global_load_dwordx2 v[44:45], v[6:7], off
	s_mov_b64 s[0:1], 0x1000
	v_lshl_add_u64 v[18:19], v[6:7], 0, s[0:1]
	global_load_dwordx2 v[46:47], v[18:19], off
	s_mov_b64 s[0:1], 0x2000
	v_lshl_add_u64 v[18:19], v[6:7], 0, s[0:1]
	global_load_dwordx2 v[48:49], v[18:19], off
	s_mov_b64 s[0:1], 0x3000
	v_lshl_add_u64 v[18:19], v[6:7], 0, s[0:1]
	global_load_dwordx2 v[50:51], v[18:19], off
	s_mov_b64 s[0:1], 0x4000
	v_lshl_add_u64 v[18:19], v[6:7], 0, s[0:1]
	global_load_dwordx2 v[52:53], v[18:19], off
	s_mov_b64 s[0:1], 0x5000
	v_lshl_add_u64 v[18:19], v[6:7], 0, s[0:1]
	global_load_dwordx2 v[54:55], v[18:19], off
	s_mov_b64 s[0:1], 0x6000
	v_lshl_add_u64 v[18:19], v[6:7], 0, s[0:1]
	global_load_dwordx2 v[56:57], v[18:19], off
	s_mov_b64 s[0:1], 0x7000
	v_lshl_add_u64 v[18:19], v[6:7], 0, s[0:1]
	global_load_dwordx2 v[58:59], v[18:19], off
.Lcomb_nopf:
	v_lshlrev_b32_e32 v18, 16, v28
	v_and_b32_e32 v19, 0xffff0000, v28
	v_lshlrev_b32_e32 v20, 16, v29
	v_and_b32_e32 v21, 0xffff0000, v29
	v_lshlrev_b32_e32 v22, 16, v30
	v_and_b32_e32 v23, 0xffff0000, v30
	v_lshlrev_b32_e32 v24, 16, v31
	v_and_b32_e32 v25, 0xffff0000, v31
	v_pk_fma_f32 v[30:31], v[26:27], v[24:25], v[20:21]
	v_pk_fma_f32 v[28:29], v[12:13], v[22:23], v[18:19] neg_lo:[1,0,0] neg_hi:[1,0,0]
	v_pk_mul_f32 v[18:19], v[30:31], v[30:31]
	v_mul_f32_e32 v20, v29, v29
	v_fmac_f32_e32 v20, v28, v28
	v_add_f32_e32 v18, v18, v20
	v_add_f32_e32 v60, v19, v18
	v_lshlrev_b32_e32 v18, 16, v32
	v_and_b32_e32 v19, 0xffff0000, v32
	v_lshlrev_b32_e32 v20, 16, v33
	v_and_b32_e32 v21, 0xffff0000, v33
	v_lshlrev_b32_e32 v22, 16, v34
	v_and_b32_e32 v23, 0xffff0000, v34
	v_lshlrev_b32_e32 v24, 16, v35
	v_and_b32_e32 v25, 0xffff0000, v35
	v_pk_fma_f32 v[34:35], v[26:27], v[24:25], v[20:21]
	v_pk_fma_f32 v[32:33], v[12:13], v[22:23], v[18:19] neg_lo:[1,0,0] neg_hi:[1,0,0]
	v_pk_mul_f32 v[18:19], v[34:35], v[34:35]
	v_mul_f32_e32 v20, v33, v33
	v_fmac_f32_e32 v20, v32, v32
	v_add_f32_e32 v18, v18, v20
	v_add_f32_e32 v61, v19, v18
	v_lshlrev_b32_e32 v18, 16, v36
	v_and_b32_e32 v19, 0xffff0000, v36
	v_lshlrev_b32_e32 v20, 16, v37
	v_and_b32_e32 v21, 0xffff0000, v37
	v_lshlrev_b32_e32 v22, 16, v38
	v_and_b32_e32 v23, 0xffff0000, v38
	v_lshlrev_b32_e32 v24, 16, v39
	v_and_b32_e32 v25, 0xffff0000, v39
	v_pk_fma_f32 v[38:39], v[26:27], v[24:25], v[20:21]
	v_pk_fma_f32 v[36:37], v[12:13], v[22:23], v[18:19] neg_lo:[1,0,0] neg_hi:[1,0,0]
	v_pk_mul_f32 v[18:19], v[38:39], v[38:39]
	v_mul_f32_e32 v20, v37, v37
	v_fmac_f32_e32 v20, v36, v36
	v_add_f32_e32 v18, v18, v20
	v_add_f32_e32 v62, v19, v18
	v_lshlrev_b32_e32 v18, 16, v40
	v_and_b32_e32 v19, 0xffff0000, v40
	v_lshlrev_b32_e32 v20, 16, v41
	v_and_b32_e32 v21, 0xffff0000, v41
	v_lshlrev_b32_e32 v22, 16, v42
	v_and_b32_e32 v23, 0xffff0000, v42
	v_lshlrev_b32_e32 v24, 16, v43
	v_and_b32_e32 v25, 0xffff0000, v43
	v_pk_fma_f32 v[42:43], v[26:27], v[24:25], v[20:21]
	v_pk_fma_f32 v[40:41], v[12:13], v[22:23], v[18:19] neg_lo:[1,0,0] neg_hi:[1,0,0]
	v_pk_mul_f32 v[18:19], v[42:43], v[42:43]
	v_mul_f32_e32 v20, v41, v41
	v_fmac_f32_e32 v20, v40, v40
	v_add_f32_e32 v18, v18, v20
	v_add_f32_e32 v63, v19, v18
	ds_bpermute_b32 v18, v0, v60
	ds_bpermute_b32 v19, v0, v61
	ds_bpermute_b32 v20, v0, v62
	ds_bpermute_b32 v21, v0, v63
	s_waitcnt lgkmcnt(0)
	v_add_f32_e32 v60, v60, v18
	v_add_f32_e32 v61, v61, v19
	v_add_f32_e32 v62, v62, v20
	v_add_f32_e32 v63, v63, v21
	ds_bpermute_b32 v18, v14, v60
	ds_bpermute_b32 v19, v14, v61
	ds_bpermute_b32 v20, v14, v62
	ds_bpermute_b32 v21, v14, v63
	s_waitcnt lgkmcnt(0)
	v_add_f32_e32 v60, v60, v18
	v_add_f32_e32 v61, v61, v19
	v_add_f32_e32 v62, v62, v20
	v_add_f32_e32 v63, v63, v21
	ds_bpermute_b32 v18, v15, v60
	ds_bpermute_b32 v19, v15, v61
	ds_bpermute_b32 v20, v15, v62
	ds_bpermute_b32 v21, v15, v63
	s_waitcnt lgkmcnt(0)
	v_add_f32_e32 v60, v60, v18
	v_add_f32_e32 v61, v61, v19
	v_add_f32_e32 v62, v62, v20
	v_add_f32_e32 v63, v63, v21
	ds_bpermute_b32 v18, v16, v60
	ds_bpermute_b32 v19, v16, v61
	ds_bpermute_b32 v20, v16, v62
	ds_bpermute_b32 v21, v16, v63
	s_waitcnt lgkmcnt(0)
	v_add_f32_e32 v60, v60, v18
	v_add_f32_e32 v61, v61, v19
	v_add_f32_e32 v62, v62, v20
	v_add_f32_e32 v63, v63, v21
	ds_bpermute_b32 v18, v17, v60
	ds_bpermute_b32 v19, v17, v61
	ds_bpermute_b32 v20, v17, v62
	ds_bpermute_b32 v21, v17, v63
	s_waitcnt lgkmcnt(0)
	v_add_f32_e32 v60, v60, v18
	v_add_f32_e32 v61, v61, v19
	v_add_f32_e32 v62, v62, v20
	v_add_f32_e32 v63, v63, v21
	ds_bpermute_b32 v18, v131, v60
	ds_bpermute_b32 v19, v131, v61
	ds_bpermute_b32 v20, v131, v62
	ds_bpermute_b32 v21, v131, v63
	s_waitcnt lgkmcnt(0)
; __device__ __forceinline__ unsigned pk2(float lo, float hi) { f32x2 v = {lo, hi}; bf16x2_t b = __builtin_convertvector(v, bf16x2_t); return __builtin_bit_cast(unsigned, b); }
; __device__ __forceinline__ void attn_phase(LAS unsigned char* lds, unsigned char* ws, int l) {
;     ...
;                 const float ss = wave_sum(o[0] * o[0] + o[1] * o[1] + o[2] * o[2] + o[3] * o[3]);
;                 const float rs = 1.0f / sqrtf(ss * (1.0f / 256.0f) + SUBLN_EPS);
;                 o = o * rs * g;
;                 u32x2 w; w.x = pk2(o[0], o[1]); w.y = pk2(o[2], o[3]);
;                 *(u32x2*)(OB + t * DM + h * 256 + 4 * lane) = w; }
	v_add_f32_e32 v60, v60, v18
	v_add_f32_e32 v61, v61, v19
	v_add_f32_e32 v62, v62, v20
	v_add_f32_e32 v63, v63, v21
	v_fmamk_f32 v22, v60, 0x3b800000, v225
	v_cmp_gt_f32_e32 vcc, s91, v22
	v_mul_f32_e32 v23, 0x4f800000, v22
	s_nop 0
	v_cndmask_b32_e32 v22, v22, v23, vcc
	v_sqrt_f32_e32 v23, v22
	s_nop 0
	v_add_u32_e32 v24, -1, v23
	v_fma_f32 v25, -v24, v23, v22
	v_cmp_ge_f32_e64 s[0:1], 0, v25
	v_add_u32_e32 v25, 1, v23
	s_nop 0
	v_cndmask_b32_e64 v24, v23, v24, s[0:1]
	v_fma_f32 v23, -v25, v23, v22
	v_cmp_lt_f32_e64 s[0:1], 0, v23
	s_nop 1
	v_cndmask_b32_e64 v23, v24, v25, s[0:1]
	v_mul_f32_e32 v24, 0x37800000, v23
	v_cndmask_b32_e32 v23, v23, v24, vcc
	v_cmp_class_f32_e32 vcc, v22, v226
	s_nop 1
	v_cndmask_b32_e32 v22, v23, v22, vcc
	v_div_scale_f32 v23, s[0:1], v22, v22, 1.0
	v_rcp_f32_e32 v24, v23
	s_nop 1
	v_fma_f32 v25, -v23, v24, 1.0
	v_fmac_f32_e32 v24, v25, v24
	v_div_scale_f32 v25, vcc, 1.0, v22, 1.0
	v_mul_f32_e32 v64, v25, v24
	v_fma_f32 v65, -v23, v64, v25
	v_fmac_f32_e32 v64, v65, v24
	v_fma_f32 v23, -v23, v64, v25
	v_div_fmas_f32 v23, v23, v24, v64
	v_div_fixup_f32 v22, v23, v22, 1.0
	v_pk_mul_f32 v[28:29], v[28:29], v[22:23] op_sel_hi:[1,0]
	v_pk_mul_f32 v[30:31], v[30:31], v[22:23] op_sel_hi:[1,0]
	v_pk_mul_f32 v[28:29], v[10:11], v[28:29]
	v_pk_mul_f32 v[30:31], v[8:9], v[30:31]
	v_cvt_pk_bf16_f32 v28, v28, v29
	v_cvt_pk_bf16_f32 v29, v30, v31
	v_lshl_add_u64 v[18:19], v[4:5], 0, s[36:37]
	global_store_dwordx2 v[18:19], v[28:29], off
	v_fmamk_f32 v22, v61, 0x3b800000, v225
	v_cmp_gt_f32_e32 vcc, s91, v22
	v_mul_f32_e32 v23, 0x4f800000, v22
	s_nop 0
	v_cndmask_b32_e32 v22, v22, v23, vcc
	v_sqrt_f32_e32 v23, v22
	s_nop 0
	v_add_u32_e32 v24, -1, v23
	v_fma_f32 v25, -v24, v23, v22
	v_cmp_ge_f32_e64 s[0:1], 0, v25
	v_add_u32_e32 v25, 1, v23
	s_nop 0
	v_cndmask_b32_e64 v24, v23, v24, s[0:1]
	v_fma_f32 v23, -v25, v23, v22
	v_cmp_lt_f32_e64 s[0:1], 0, v23
	s_nop 1
	v_cndmask_b32_e64 v23, v24, v25, s[0:1]
	v_mul_f32_e32 v24, 0x37800000, v23
	v_cndmask_b32_e32 v23, v23, v24, vcc
	v_cmp_class_f32_e32 vcc, v22, v226
	s_nop 1
	v_cndmask_b32_e32 v22, v23, v22, vcc
	v_div_scale_f32 v23, s[0:1], v22, v22, 1.0
	v_rcp_f32_e32 v24, v23
	s_nop 1
	v_fma_f32 v25, -v23, v24, 1.0
	v_fmac_f32_e32 v24, v25, v24
	v_div_scale_f32 v25, vcc, 1.0, v22, 1.0
	v_mul_f32_e32 v64, v25, v24
	v_fma_f32 v65, -v23, v64, v25
	v_fmac_f32_e32 v64, v65, v24
	v_fma_f32 v23, -v23, v64, v25
	v_div_fmas_f32 v23, v23, v24, v64
	v_div_fixup_f32 v22, v23, v22, 1.0
	v_pk_mul_f32 v[32:33], v[32:33], v[22:23] op_sel_hi:[1,0]
	v_pk_mul_f32 v[34:35], v[34:35], v[22:23] op_sel_hi:[1,0]
	v_pk_mul_f32 v[32:33], v[10:11], v[32:33]
	v_pk_mul_f32 v[34:35], v[8:9], v[34:35]
	v_cvt_pk_bf16_f32 v32, v32, v33
	v_cvt_pk_bf16_f32 v33, v34, v35
	s_add_u32 s0, s36, 0x1000
	s_addc_u32 s1, s37, 0
	v_lshl_add_u64 v[18:19], v[4:5], 0, s[0:1]
	global_store_dwordx2 v[18:19], v[32:33], off
	v_fmamk_f32 v22, v62, 0x3b800000, v225
	v_cmp_gt_f32_e32 vcc, s91, v22
	v_mul_f32_e32 v23, 0x4f800000, v22
	s_nop 0
	v_cndmask_b32_e32 v22, v22, v23, vcc
	v_sqrt_f32_e32 v23, v22
	s_nop 0
	v_add_u32_e32 v24, -1, v23
	v_fma_f32 v25, -v24, v23, v22
	v_cmp_ge_f32_e64 s[0:1], 0, v25
	v_add_u32_e32 v25, 1, v23
	s_nop 0
	v_cndmask_b32_e64 v24, v23, v24, s[0:1]
	v_fma_f32 v23, -v25, v23, v22
	v_cmp_lt_f32_e64 s[0:1], 0, v23
	s_nop 1
	v_cndmask_b32_e64 v23, v24, v25, s[0:1]
	v_mul_f32_e32 v24, 0x37800000, v23
	v_cndmask_b32_e32 v23, v23, v24, vcc
	v_cmp_class_f32_e32 vcc, v22, v226
	s_nop 1
	v_cndmask_b32_e32 v22, v23, v22, vcc
	v_div_scale_f32 v23, s[0:1], v22, v22, 1.0
	v_rcp_f32_e32 v24, v23
	s_nop 1
	v_fma_f32 v25, -v23, v24, 1.0
	v_fmac_f32_e32 v24, v25, v24
	v_div_scale_f32 v25, vcc, 1.0, v22, 1.0
	v_mul_f32_e32 v64, v25, v24
	v_fma_f32 v65, -v23, v64, v25
	v_fmac_f32_e32 v64, v65, v24
	v_fma_f32 v23, -v23, v64, v25
	v_div_fmas_f32 v23, v23, v24, v64
	v_div_fixup_f32 v22, v23, v22, 1.0
	v_pk_mul_f32 v[36:37], v[36:37], v[22:23] op_sel_hi:[1,0]
	v_pk_mul_f32 v[38:39], v[38:39], v[22:23] op_sel_hi:[1,0]
	v_pk_mul_f32 v[36:37], v[10:11], v[36:37]
	v_pk_mul_f32 v[38:39], v[8:9], v[38:39]
	v_cvt_pk_bf16_f32 v36, v36, v37
	v_cvt_pk_bf16_f32 v37, v38, v39
	s_add_u32 s0, s36, 0x2000
	s_addc_u32 s1, s37, 0
	v_lshl_add_u64 v[18:19], v[4:5], 0, s[0:1]
	global_store_dwordx2 v[18:19], v[36:37], off
	v_fmamk_f32 v22, v63, 0x3b800000, v225
	v_cmp_gt_f32_e32 vcc, s91, v22
	v_mul_f32_e32 v23, 0x4f800000, v22
	s_nop 0
	v_cndmask_b32_e32 v22, v22, v23, vcc
	v_sqrt_f32_e32 v23, v22
	s_nop 0
	v_add_u32_e32 v24, -1, v23
	v_fma_f32 v25, -v24, v23, v22
	v_cmp_ge_f32_e64 s[0:1], 0, v25
	v_add_u32_e32 v25, 1, v23
	s_nop 0
	v_cndmask_b32_e64 v24, v23, v24, s[0:1]
	v_fma_f32 v23, -v25, v23, v22
	v_cmp_lt_f32_e64 s[0:1], 0, v23
	s_nop 1
	v_cndmask_b32_e64 v23, v24, v25, s[0:1]
	v_mul_f32_e32 v24, 0x37800000, v23
	v_cndmask_b32_e32 v23, v23, v24, vcc
	v_cmp_class_f32_e32 vcc, v22, v226
	s_nop 1
	v_cndmask_b32_e32 v22, v23, v22, vcc
	v_div_scale_f32 v23, s[0:1], v22, v22, 1.0
	v_rcp_f32_e32 v24, v23
	s_nop 1
	v_fma_f32 v25, -v23, v24, 1.0
	v_fmac_f32_e32 v24, v25, v24
	v_div_scale_f32 v25, vcc, 1.0, v22, 1.0
	v_mul_f32_e32 v64, v25, v24
	v_fma_f32 v65, -v23, v64, v25
	v_fmac_f32_e32 v64, v65, v24
	v_fma_f32 v23, -v23, v64, v25
	v_div_fmas_f32 v23, v23, v24, v64
	v_div_fixup_f32 v22, v23, v22, 1.0
	v_pk_mul_f32 v[40:41], v[40:41], v[22:23] op_sel_hi:[1,0]
	v_pk_mul_f32 v[42:43], v[42:43], v[22:23] op_sel_hi:[1,0]
	v_pk_mul_f32 v[40:41], v[10:11], v[40:41]
	v_pk_mul_f32 v[42:43], v[8:9], v[42:43]
	v_cvt_pk_bf16_f32 v40, v40, v41
	v_cvt_pk_bf16_f32 v41, v42, v43
	s_add_u32 s0, s36, 0x3000
	s_addc_u32 s1, s37, 0
	v_lshl_add_u64 v[18:19], v[4:5], 0, s[0:1]
	global_store_dwordx2 v[18:19], v[40:41], off
	s_add_u32 s36, s36, 0x4000
	s_addc_u32 s37, s37, 0
	s_cmp_eq_u32 s36, 0x10000
	s_cbranch_scc0 .Lcomb_loop
	s_add_i32 s98, s98, 1
	s_cmp_lt_u32 s98, 4
	s_cbranch_scc1 .LBB0_249
	s_setprio 0
	v_readlane_b32 s48, v255, 6
	v_readlane_b32 s49, v255, 7
	v_readlane_b32 s93, v255, 12
	s_mov_b32 s40, s50

; #define PG8_STAGE(bufoff, gbase, voff) do { _Pragma("unroll") for (int _i = 0; _i < 2; ++_i) \
;         __builtin_amdgcn_global_load_lds((const unsigned*)((const char*)(gbase) + (voff)[_i]), (LAS unsigned*)(lds + (bufoff) + ldsw + _i * 8192), 16, 0, 0); } while (0)
; #define PG8_LDA(dst, b, h) do { _Pragma("unroll") for (int m = 0; m < 4; ++m) _Pragma("unroll") for (int k = 0; k < 2; ++k) dst[m][k] = *(const LAS bf16x8*)(lds + PG8_SA(b, h) + aoff + m * 2048 + k * 1024); } while (0)
; #define PG8_LDB(dst, b, h) do { _Pragma("unroll") for (int n = 0; n < 2; ++n) _Pragma("unroll") for (int k = 0; k < 2; ++k) dst[n][k] = *(const LAS bf16x8*)(lds + PG8_SB(b, h) + boff + n * 2048 + k * 1024); } while (0)
; #define PG8_MMA(ai, bj, At, Bt) do { __builtin_amdgcn_s_setprio(1); _Pragma("unroll") for (int m = 0; m < 4; ++m) _Pragma("unroll") for (int n = 0; n < 2; ++n) _Pragma("unroll") for (int k = 0; k < 2; ++k) \
;         acc[ai][bj][m][n] = __builtin_amdgcn_mfma_f32_16x16x32_bf16(Bt[n][k], At[m][k], acc[ai][bj][m][n], 0, 0, 0); __builtin_amdgcn_s_setprio(0); } while (0)
; #define PG8_WAIT_V(n) asm volatile("s_waitcnt vmcnt(" #n ")" ::: "memory")
; #define PG8_WAIT_L(n) asm volatile("s_waitcnt lgkmcnt(" #n ")" ::: "memory")
; #define PG8_BAR __builtin_amdgcn_s_barrier()
; template <class Epi, class Sched, bool ALIGN_EPI = false, bool SP2 = false>
; __device__ __forceinline__ void gemm_phase(LAS unsigned char* lds, const Gemm g, const Sched& S, const Epi& E) {
;     ...
;             const bool last = (t == nt - 2);
;             const char* a1 = cA + (size_t)(t + 1) * kstep;
;             const char* a2 = last ? nA : cA + (size_t)(t + 2) * kstep; const char* b2 = last ? nB : cB + (size_t)(t + 2) * kstep;
;             const char* a3 = a2 + kstep; const char* b3 = b2 + kstep;
;             if (last && has_next) S.a_ready(nxt);
;             if constexpr (SP2) {
;             PG8_LDB(B0, 0, 0); PG8_LDB(B1, 0, 1); PG8_SCHED; PG8_LDA(At, 0, 0); PG8_STAGE(PG8_SA(1, 1), a1 + hstep, voffA);
;             PG8_WAIT_V(8); PG8_WAIT_L(0); PG8_BAR; PG8_MMA(0, 0, At, B0); PG8_MMA(0, 1, At, B1); PG8_BAR; PG8_SCHED;
;             PG8_LDA(At, 0, 1); PG8_STAGE(PG8_SB(0, 0), b2, voffB); PG8_STAGE(PG8_SB(0, 1), b2 + hstep, voffB); PG8_STAGE(PG8_SA(0, 0), a2, voffA);
;             PG8_WAIT_V(8); PG8_WAIT_L(0); PG8_BAR; PG8_MMA(1, 0, At, B0); PG8_MMA(1, 1, At, B1); PG8_BAR; PG8_SCHED;
.LBB0_356:
	s_add_u32 s14, s42, 0xfff80080
	s_addc_u32 s15, s43, -1
	s_add_i32 s20, 0, 0x10000
	s_cmp_eq_u32 s73, 28
	s_cselect_b32 s59, s31, s15
	s_cselect_b32 s58, s69, s14
	s_cselect_b32 s47, s9, s72
	s_cselect_b32 s46, s70, s71
	s_add_i32 s21, 0, 0x14000
	v_add_u32_e32 v142, s20, v177
	v_add_u32_e32 v168, s21, v177
	ds_read_b128 v[130:133], v142
	ds_read_b128 v[134:137], v142 offset:1024
	ds_read_b128 v[138:141], v142 offset:2048
	ds_read_b128 v[142:145], v142 offset:3072
	ds_read_b128 v[146:149], v168
	ds_read_b128 v[150:153], v168 offset:1024
	ds_read_b128 v[164:167], v168 offset:2048
	ds_read_b128 v[168:171], v168 offset:3072
	v_lshl_add_u64 v[184:185], s[42:43], 0, v[160:161]
	s_add_i32 m0, s13, 0xc000
	ds_read_b128 v[172:175], v179
	ds_read_b128 v[180:183], v179 offset:1024
	ds_read_b128 v[198:201], v179 offset:2048
	ds_read_b128 v[202:205], v179 offset:3072
	ds_read_b128 v[206:209], v179 offset:4096
	ds_read_b128 v[210:213], v179 offset:5120
	ds_read_b128 v[214:217], v179 offset:6144
	ds_read_b128 v[218:221], v179 offset:7168
	global_load_lds_dwordx4 v[184:185], off
	v_lshl_add_u64 v[184:185], s[42:43], 0, v[162:163]
	s_add_i32 m0, s13, 0xe000
	s_nop 0
	global_load_lds_dwordx4 v[184:185], off
	s_waitcnt vmcnt(8)
	s_waitcnt lgkmcnt(0)
	s_barrier
	s_setprio 1
	s_waitcnt lgkmcnt(0)
	v_mfma_f32_16x16x32_bf16 v[126:129], v[130:133], v[172:175], v[126:129]
	v_mfma_f32_16x16x32_bf16 v[122:125], v[138:141], v[172:175], v[122:125]
	v_mfma_f32_16x16x32_bf16 v[110:113], v[130:133], v[198:201], v[110:113]
	v_mfma_f32_16x16x32_bf16 v[106:109], v[138:141], v[198:201], v[106:109]
	v_mfma_f32_16x16x32_bf16 v[94:97], v[130:133], v[206:209], v[94:97]
	v_mfma_f32_16x16x32_bf16 v[90:93], v[138:141], v[206:209], v[90:93]
	v_mfma_f32_16x16x32_bf16 v[78:81], v[130:133], v[214:217], v[78:81]
	v_mfma_f32_16x16x32_bf16 v[74:77], v[138:141], v[214:217], v[74:77]
	v_mfma_f32_16x16x32_bf16 v[126:129], v[134:137], v[180:183], v[126:129]
	v_mfma_f32_16x16x32_bf16 v[122:125], v[142:145], v[180:183], v[122:125]
	v_mfma_f32_16x16x32_bf16 v[110:113], v[134:137], v[202:205], v[110:113]
	v_mfma_f32_16x16x32_bf16 v[106:109], v[142:145], v[202:205], v[106:109]
	v_mfma_f32_16x16x32_bf16 v[94:97], v[134:137], v[210:213], v[94:97]
	v_mfma_f32_16x16x32_bf16 v[90:93], v[142:145], v[210:213], v[90:93]
	v_mfma_f32_16x16x32_bf16 v[78:81], v[134:137], v[218:221], v[78:81]
	v_mfma_f32_16x16x32_bf16 v[74:77], v[142:145], v[218:221], v[74:77]
	s_setprio 0
	s_setprio 1
	v_mfma_f32_16x16x32_bf16 v[118:121], v[146:149], v[172:175], v[118:121]
	v_mfma_f32_16x16x32_bf16 v[114:117], v[164:167], v[172:175], v[114:117]
	v_mfma_f32_16x16x32_bf16 v[102:105], v[146:149], v[198:201], v[102:105]
	v_mfma_f32_16x16x32_bf16 v[98:101], v[164:167], v[198:201], v[98:101]
	v_mfma_f32_16x16x32_bf16 v[86:89], v[146:149], v[206:209], v[86:89]
	v_mfma_f32_16x16x32_bf16 v[82:85], v[164:167], v[206:209], v[82:85]
	v_mfma_f32_16x16x32_bf16 v[70:73], v[146:149], v[214:217], v[70:73]
	v_mfma_f32_16x16x32_bf16 v[66:69], v[164:167], v[214:217], v[66:69]
	v_mfma_f32_16x16x32_bf16 v[118:121], v[150:153], v[180:183], v[118:121]
	v_mfma_f32_16x16x32_bf16 v[114:117], v[168:171], v[180:183], v[114:117]
	v_mfma_f32_16x16x32_bf16 v[102:105], v[150:153], v[202:205], v[102:105]
	v_mfma_f32_16x16x32_bf16 v[98:101], v[168:171], v[202:205], v[98:101]
	v_mfma_f32_16x16x32_bf16 v[86:89], v[150:153], v[210:213], v[86:89]
	v_mfma_f32_16x16x32_bf16 v[82:85], v[168:171], v[210:213], v[82:85]
	v_mfma_f32_16x16x32_bf16 v[70:73], v[150:153], v[218:221], v[70:73]
	v_mfma_f32_16x16x32_bf16 v[66:69], v[168:171], v[218:221], v[66:69]
	s_setprio 0
	s_barrier
	s_add_i32 s14, s20, s4
	v_lshl_add_u64 v[184:185], s[46:47], 0, v[0:1]
	s_mov_b32 m0, s14
	ds_read_b128 v[172:175], v179 offset:16384
	ds_read_b128 v[180:183], v179 offset:17408
	ds_read_b128 v[198:201], v179 offset:18432
	ds_read_b128 v[202:205], v179 offset:19456
	ds_read_b128 v[206:209], v179 offset:20480
	ds_read_b128 v[210:213], v179 offset:21504
	ds_read_b128 v[214:217], v179 offset:22528
	ds_read_b128 v[218:221], v179 offset:23552
	global_load_lds_dwordx4 v[184:185], off
	s_add_i32 m0, s14, 0x2000
	s_add_u32 s14, s46, 0x80000
	v_lshl_add_u64 v[236:237], s[46:47], 0, v[154:155]
	s_addc_u32 s15, s47, 0
	s_add_i32 s20, s21, s4
	global_load_lds_dwordx4 v[236:237], off
	v_lshl_add_u64 v[238:239], s[14:15], 0, v[0:1]
	s_mov_b32 m0, s20
	global_load_lds_dwordx4 v[238:239], off
	v_lshl_add_u64 v[238:239], s[14:15], 0, v[154:155]
	s_add_i32 m0, s20, 0x2000
	s_nop 0
	global_load_lds_dwordx4 v[238:239], off
	s_waitcnt vmcnt(6)
	s_waitcnt lgkmcnt(0)
	s_barrier
; #define PG8_STAGE(bufoff, gbase, voff) do { _Pragma("unroll") for (int _i = 0; _i < 2; ++_i) \
;         __builtin_amdgcn_global_load_lds((const unsigned*)((const char*)(gbase) + (voff)[_i]), (LAS unsigned*)(lds + (bufoff) + ldsw + _i * 8192), 16, 0, 0); } while (0)
; #define PG8_LDA(dst, b, h) do { _Pragma("unroll") for (int m = 0; m < 4; ++m) _Pragma("unroll") for (int k = 0; k < 2; ++k) dst[m][k] = *(const LAS bf16x8*)(lds + PG8_SA(b, h) + aoff + m * 2048 + k * 1024); } while (0)
; #define PG8_LDB(dst, b, h) do { _Pragma("unroll") for (int n = 0; n < 2; ++n) _Pragma("unroll") for (int k = 0; k < 2; ++k) dst[n][k] = *(const LAS bf16x8*)(lds + PG8_SB(b, h) + boff + n * 2048 + k * 1024); } while (0)
; #define PG8_MMA(ai, bj, At, Bt) do { __builtin_amdgcn_s_setprio(1); _Pragma("unroll") for (int m = 0; m < 4; ++m) _Pragma("unroll") for (int n = 0; n < 2; ++n) _Pragma("unroll") for (int k = 0; k < 2; ++k) \
;         acc[ai][bj][m][n] = __builtin_amdgcn_mfma_f32_16x16x32_bf16(Bt[n][k], At[m][k], acc[ai][bj][m][n], 0, 0, 0); __builtin_amdgcn_s_setprio(0); } while (0)
; #define PG8_WAIT_V(n) asm volatile("s_waitcnt vmcnt(" #n ")" ::: "memory")
; #define PG8_WAIT_L(n) asm volatile("s_waitcnt lgkmcnt(" #n ")" ::: "memory")
; #define PG8_BAR __builtin_amdgcn_s_barrier()
; #define PG8_SCHED __builtin_amdgcn_sched_barrier(0)
; template <class Epi, class Sched, bool ALIGN_EPI = false, bool SP2 = false>
; __device__ __forceinline__ void gemm_phase(LAS unsigned char* lds, const Gemm g, const Sched& S, const Epi& E) {
;     ...
;             PG8_WAIT_V(8); PG8_WAIT_L(0); PG8_BAR; PG8_MMA(1, 0, At, B0); PG8_MMA(1, 1, At, B1); PG8_BAR; PG8_SCHED;
;             PG8_LDB(B0, 1, 0); PG8_LDB(B1, 1, 1); PG8_SCHED; PG8_LDA(At, 1, 0); PG8_STAGE(PG8_SA(0, 1), a2 + hstep, voffA);
;             PG8_WAIT_V(8); PG8_WAIT_L(0); PG8_BAR; PG8_MMA(0, 0, At, B0); PG8_MMA(0, 1, At, B1); PG8_BAR; PG8_SCHED;
	s_setprio 1
	s_waitcnt lgkmcnt(0)
	v_mfma_f32_16x16x32_bf16 v[62:65], v[130:133], v[172:175], v[62:65]
	v_mfma_f32_16x16x32_bf16 v[58:61], v[138:141], v[172:175], v[58:61]
	v_mfma_f32_16x16x32_bf16 v[50:53], v[130:133], v[198:201], v[50:53]
	v_mfma_f32_16x16x32_bf16 v[42:45], v[138:141], v[198:201], v[42:45]
	v_mfma_f32_16x16x32_bf16 v[34:37], v[130:133], v[206:209], v[34:37]
	v_mfma_f32_16x16x32_bf16 v[26:29], v[138:141], v[206:209], v[26:29]
	v_mfma_f32_16x16x32_bf16 v[18:21], v[130:133], v[214:217], v[18:21]
	v_mfma_f32_16x16x32_bf16 v[10:13], v[138:141], v[214:217], v[10:13]
	v_mfma_f32_16x16x32_bf16 v[62:65], v[134:137], v[180:183], v[62:65]
	v_mfma_f32_16x16x32_bf16 v[58:61], v[142:145], v[180:183], v[58:61]
	v_mfma_f32_16x16x32_bf16 v[50:53], v[134:137], v[202:205], v[50:53]
	v_mfma_f32_16x16x32_bf16 v[42:45], v[142:145], v[202:205], v[42:45]
	v_mfma_f32_16x16x32_bf16 v[34:37], v[134:137], v[210:213], v[34:37]
	v_mfma_f32_16x16x32_bf16 v[26:29], v[142:145], v[210:213], v[26:29]
	v_mfma_f32_16x16x32_bf16 v[18:21], v[134:137], v[218:221], v[18:21]
	v_mfma_f32_16x16x32_bf16 v[10:13], v[142:145], v[218:221], v[10:13]
	s_setprio 0
	s_setprio 1
	v_mfma_f32_16x16x32_bf16 v[54:57], v[146:149], v[172:175], v[54:57]
	v_mfma_f32_16x16x32_bf16 v[46:49], v[164:167], v[172:175], v[46:49]
	v_mfma_f32_16x16x32_bf16 v[38:41], v[146:149], v[198:201], v[38:41]
	v_mfma_f32_16x16x32_bf16 v[30:33], v[164:167], v[198:201], v[30:33]
	v_mfma_f32_16x16x32_bf16 v[22:25], v[146:149], v[206:209], v[22:25]
	v_mfma_f32_16x16x32_bf16 v[14:17], v[164:167], v[206:209], v[14:17]
	v_mfma_f32_16x16x32_bf16 v[6:9], v[146:149], v[214:217], v[6:9]
	v_mfma_f32_16x16x32_bf16 v[2:5], v[164:167], v[214:217], v[2:5]
	v_mfma_f32_16x16x32_bf16 v[54:57], v[150:153], v[180:183], v[54:57]
	v_mfma_f32_16x16x32_bf16 v[46:49], v[168:171], v[180:183], v[46:49]
	v_mfma_f32_16x16x32_bf16 v[38:41], v[150:153], v[202:205], v[38:41]
	v_mfma_f32_16x16x32_bf16 v[30:33], v[168:171], v[202:205], v[30:33]
	v_mfma_f32_16x16x32_bf16 v[22:25], v[150:153], v[210:213], v[22:25]
	v_mfma_f32_16x16x32_bf16 v[14:17], v[168:171], v[210:213], v[14:17]
	v_mfma_f32_16x16x32_bf16 v[6:9], v[150:153], v[218:221], v[6:9]
	v_mfma_f32_16x16x32_bf16 v[2:5], v[168:171], v[218:221], v[2:5]
	s_setprio 0
	s_barrier
	s_add_i32 s20, 0, 0x18000
	s_add_i32 s21, 0, 0x1c000
	v_add_u32_e32 v142, s20, v177
	v_add_u32_e32 v168, s21, v177
	ds_read_b128 v[130:133], v142
	ds_read_b128 v[134:137], v142 offset:1024
	ds_read_b128 v[138:141], v142 offset:2048
	ds_read_b128 v[142:145], v142 offset:3072
	ds_read_b128 v[146:149], v168
	ds_read_b128 v[150:153], v168 offset:1024
	ds_read_b128 v[164:167], v168 offset:2048
	ds_read_b128 v[168:171], v168 offset:3072
	s_add_u32 s14, s58, 0x80000
	s_addc_u32 s15, s59, 0
	s_mov_b32 m0, s44
	v_lshl_add_u64 v[242:243], s[14:15], 0, v[158:159]
	ds_read_b128 v[172:175], v179 offset:32768
	ds_read_b128 v[180:183], v179 offset:33792
	ds_read_b128 v[198:201], v179 offset:34816
	ds_read_b128 v[202:205], v179 offset:35840
	ds_read_b128 v[206:209], v179 offset:36864
	ds_read_b128 v[210:213], v179 offset:37888
	ds_read_b128 v[214:217], v179 offset:38912
	ds_read_b128 v[218:221], v179 offset:39936
	v_lshl_add_u64 v[238:239], s[58:59], 0, v[158:159]
	s_mov_b32 m0, s13
	v_lshl_add_u64 v[240:241], s[58:59], 0, v[156:157]
	global_load_lds_dwordx4 v[238:239], off
	s_mov_b32 m0, s27
	s_nop 0
	global_load_lds_dwordx4 v[240:241], off
	s_mov_b32 m0, s44
	s_nop 0
	global_load_lds_dwordx4 v[242:243], off
	v_lshl_add_u64 v[242:243], s[14:15], 0, v[156:157]
	s_mov_b32 m0, s33
	s_nop 0
	global_load_lds_dwordx4 v[242:243], off
	s_waitcnt vmcnt(8)
	s_waitcnt lgkmcnt(0)
	s_barrier
	s_setprio 1
	s_waitcnt lgkmcnt(0)
	v_mfma_f32_16x16x32_bf16 v[126:129], v[130:133], v[172:175], v[126:129]
	v_mfma_f32_16x16x32_bf16 v[122:125], v[138:141], v[172:175], v[122:125]
	v_mfma_f32_16x16x32_bf16 v[110:113], v[130:133], v[198:201], v[110:113]
	v_mfma_f32_16x16x32_bf16 v[106:109], v[138:141], v[198:201], v[106:109]
	v_mfma_f32_16x16x32_bf16 v[94:97], v[130:133], v[206:209], v[94:97]
	v_mfma_f32_16x16x32_bf16 v[90:93], v[138:141], v[206:209], v[90:93]
	v_mfma_f32_16x16x32_bf16 v[78:81], v[130:133], v[214:217], v[78:81]
	v_mfma_f32_16x16x32_bf16 v[74:77], v[138:141], v[214:217], v[74:77]
	v_mfma_f32_16x16x32_bf16 v[126:129], v[134:137], v[180:183], v[126:129]
	v_mfma_f32_16x16x32_bf16 v[122:125], v[142:145], v[180:183], v[122:125]
	v_mfma_f32_16x16x32_bf16 v[110:113], v[134:137], v[202:205], v[110:113]
	v_mfma_f32_16x16x32_bf16 v[106:109], v[142:145], v[202:205], v[106:109]
	v_mfma_f32_16x16x32_bf16 v[94:97], v[134:137], v[210:213], v[94:97]
	v_mfma_f32_16x16x32_bf16 v[90:93], v[142:145], v[210:213], v[90:93]
	v_mfma_f32_16x16x32_bf16 v[78:81], v[134:137], v[218:221], v[78:81]
	v_mfma_f32_16x16x32_bf16 v[74:77], v[142:145], v[218:221], v[74:77]
	s_setprio 0
	s_setprio 1
	v_mfma_f32_16x16x32_bf16 v[118:121], v[146:149], v[172:175], v[118:121]
	v_mfma_f32_16x16x32_bf16 v[114:117], v[164:167], v[172:175], v[114:117]
	v_mfma_f32_16x16x32_bf16 v[102:105], v[146:149], v[198:201], v[102:105]
	v_mfma_f32_16x16x32_bf16 v[98:101], v[164:167], v[198:201], v[98:101]
	v_mfma_f32_16x16x32_bf16 v[86:89], v[146:149], v[206:209], v[86:89]
	v_mfma_f32_16x16x32_bf16 v[82:85], v[164:167], v[206:209], v[82:85]
	v_mfma_f32_16x16x32_bf16 v[70:73], v[146:149], v[214:217], v[70:73]
	v_mfma_f32_16x16x32_bf16 v[66:69], v[164:167], v[214:217], v[66:69]
	v_mfma_f32_16x16x32_bf16 v[118:121], v[150:153], v[180:183], v[118:121]
	v_mfma_f32_16x16x32_bf16 v[114:117], v[168:171], v[180:183], v[114:117]
	v_mfma_f32_16x16x32_bf16 v[102:105], v[150:153], v[202:205], v[102:105]
	v_mfma_f32_16x16x32_bf16 v[98:101], v[168:171], v[202:205], v[98:101]
	v_mfma_f32_16x16x32_bf16 v[86:89], v[150:153], v[210:213], v[86:89]
	v_mfma_f32_16x16x32_bf16 v[82:85], v[168:171], v[210:213], v[82:85]
	v_mfma_f32_16x16x32_bf16 v[70:73], v[150:153], v[218:221], v[70:73]
	v_mfma_f32_16x16x32_bf16 v[66:69], v[168:171], v[218:221], v[66:69]
	s_setprio 0
	s_barrier
; #define PG8_STAGE(bufoff, gbase, voff) do { _Pragma("unroll") for (int _i = 0; _i < 2; ++_i) \
;         __builtin_amdgcn_global_load_lds((const unsigned*)((const char*)(gbase) + (voff)[_i]), (LAS unsigned*)(lds + (bufoff) + ldsw + _i * 8192), 16, 0, 0); } while (0)
; #define PG8_LDA(dst, b, h) do { _Pragma("unroll") for (int m = 0; m < 4; ++m) _Pragma("unroll") for (int k = 0; k < 2; ++k) dst[m][k] = *(const LAS bf16x8*)(lds + PG8_SA(b, h) + aoff + m * 2048 + k * 1024); } while (0)
; #define PG8_MMA(ai, bj, At, Bt) do { __builtin_amdgcn_s_setprio(1); _Pragma("unroll") for (int m = 0; m < 4; ++m) _Pragma("unroll") for (int n = 0; n < 2; ++n) _Pragma("unroll") for (int k = 0; k < 2; ++k) \
;         acc[ai][bj][m][n] = __builtin_amdgcn_mfma_f32_16x16x32_bf16(Bt[n][k], At[m][k], acc[ai][bj][m][n], 0, 0, 0); __builtin_amdgcn_s_setprio(0); } while (0)
; #define PG8_WAIT_V(n) asm volatile("s_waitcnt vmcnt(" #n ")" ::: "memory")
; #define PG8_WAIT_L(n) asm volatile("s_waitcnt lgkmcnt(" #n ")" ::: "memory")
; #define PG8_BAR __builtin_amdgcn_s_barrier()
; #define PG8_SCHED __builtin_amdgcn_sched_barrier(0)
; template <class Epi, class Sched, bool ALIGN_EPI = false, bool SP2 = false>
; __device__ __forceinline__ void gemm_phase(LAS unsigned char* lds, const Gemm g, const Sched& S, const Epi& E) {
;     ...
;             PG8_LDA(At, 1, 1); PG8_STAGE(PG8_SB(1, 0), b3, voffB); PG8_STAGE(PG8_SB(1, 1), b3 + hstep, voffB); PG8_STAGE(PG8_SA(1, 0), a3, voffA);
;             PG8_WAIT_V(8); PG8_WAIT_L(0); PG8_BAR; PG8_MMA(1, 0, At, B0); PG8_MMA(1, 1, At, B1); PG8_BAR; PG8_SCHED;
	s_add_i32 s14, s20, s4
	v_lshl_add_u64 v[184:185], v[184:185], 0, s[18:19]
	s_mov_b32 m0, s14
	ds_read_b128 v[172:175], v179 offset:49152
	ds_read_b128 v[180:183], v179 offset:50176
	ds_read_b128 v[198:201], v179 offset:51200
	ds_read_b128 v[202:205], v179 offset:52224
	ds_read_b128 v[206:209], v179 offset:53248
	ds_read_b128 v[210:213], v179 offset:54272
	ds_read_b128 v[214:217], v179 offset:55296
	ds_read_b128 v[218:221], v179 offset:56320
	global_load_lds_dwordx4 v[184:185], off
	s_add_i32 m0, s14, 0x2000
	s_add_u32 s14, s46, 0x80080
	v_lshl_add_u64 v[184:185], v[236:237], 0, s[18:19]
	s_addc_u32 s15, s47, 0
	s_add_i32 s20, s21, s4
	global_load_lds_dwordx4 v[184:185], off
	v_lshl_add_u64 v[184:185], s[14:15], 0, v[0:1]
	s_mov_b32 m0, s20
	s_nop 0
	global_load_lds_dwordx4 v[184:185], off
	v_lshl_add_u64 v[184:185], s[14:15], 0, v[154:155]
	s_add_i32 m0, s20, 0x2000
	s_nop 0
	global_load_lds_dwordx4 v[184:185], off
	v_lshl_add_u64 v[184:185], v[238:239], 0, s[18:19]
	s_mov_b32 m0, s45
	s_nop 0
	global_load_lds_dwordx4 v[184:185], off
	v_lshl_add_u64 v[184:185], v[240:241], 0, s[18:19]
	s_mov_b32 m0, s66
	s_nop 0
	global_load_lds_dwordx4 v[184:185], off
	s_waitcnt vmcnt(8)
	s_waitcnt lgkmcnt(0)
	s_barrier
	s_setprio 1
	s_waitcnt lgkmcnt(0)
	v_mfma_f32_16x16x32_bf16 v[62:65], v[130:133], v[172:175], v[62:65]
	v_mfma_f32_16x16x32_bf16 v[58:61], v[138:141], v[172:175], v[58:61]
	v_mfma_f32_16x16x32_bf16 v[50:53], v[130:133], v[198:201], v[50:53]
	v_mfma_f32_16x16x32_bf16 v[42:45], v[138:141], v[198:201], v[42:45]
	v_mfma_f32_16x16x32_bf16 v[34:37], v[130:133], v[206:209], v[34:37]
	v_mfma_f32_16x16x32_bf16 v[26:29], v[138:141], v[206:209], v[26:29]
	v_mfma_f32_16x16x32_bf16 v[18:21], v[130:133], v[214:217], v[18:21]
	v_mfma_f32_16x16x32_bf16 v[10:13], v[138:141], v[214:217], v[10:13]
	v_mfma_f32_16x16x32_bf16 v[62:65], v[134:137], v[180:183], v[62:65]
	v_mfma_f32_16x16x32_bf16 v[58:61], v[142:145], v[180:183], v[58:61]
	v_mfma_f32_16x16x32_bf16 v[50:53], v[134:137], v[202:205], v[50:53]
	v_mfma_f32_16x16x32_bf16 v[42:45], v[142:145], v[202:205], v[42:45]
	v_mfma_f32_16x16x32_bf16 v[34:37], v[134:137], v[210:213], v[34:37]
	v_mfma_f32_16x16x32_bf16 v[26:29], v[142:145], v[210:213], v[26:29]
	v_mfma_f32_16x16x32_bf16 v[18:21], v[134:137], v[218:221], v[18:21]
	v_mfma_f32_16x16x32_bf16 v[10:13], v[142:145], v[218:221], v[10:13]
	s_setprio 0
	s_setprio 1
	v_mfma_f32_16x16x32_bf16 v[54:57], v[146:149], v[172:175], v[54:57]
	v_mfma_f32_16x16x32_bf16 v[46:49], v[164:167], v[172:175], v[46:49]
	v_mfma_f32_16x16x32_bf16 v[38:41], v[146:149], v[198:201], v[38:41]
	v_mfma_f32_16x16x32_bf16 v[30:33], v[164:167], v[198:201], v[30:33]
	v_mfma_f32_16x16x32_bf16 v[22:25], v[146:149], v[206:209], v[22:25]
	v_mfma_f32_16x16x32_bf16 v[14:17], v[164:167], v[206:209], v[14:17]
	v_mfma_f32_16x16x32_bf16 v[6:9], v[146:149], v[214:217], v[6:9]
	v_mfma_f32_16x16x32_bf16 v[2:5], v[164:167], v[214:217], v[2:5]
	v_mfma_f32_16x16x32_bf16 v[54:57], v[150:153], v[180:183], v[54:57]
	v_mfma_f32_16x16x32_bf16 v[46:49], v[168:171], v[180:183], v[46:49]
	v_mfma_f32_16x16x32_bf16 v[38:41], v[150:153], v[202:205], v[38:41]
	v_mfma_f32_16x16x32_bf16 v[30:33], v[168:171], v[202:205], v[30:33]
	v_mfma_f32_16x16x32_bf16 v[22:25], v[150:153], v[210:213], v[22:25]
	v_mfma_f32_16x16x32_bf16 v[14:17], v[168:171], v[210:213], v[14:17]
	v_mfma_f32_16x16x32_bf16 v[6:9], v[150:153], v[218:221], v[6:9]
	v_mfma_f32_16x16x32_bf16 v[2:5], v[168:171], v[218:221], v[2:5]
	s_setprio 0
	s_barrier
	s_add_i32 s73, s73, 2
	s_add_u32 s42, s42, 0x100
	s_addc_u32 s43, s43, 0
	s_add_u32 s71, s71, 0x100
	s_addc_u32 s72, s72, 0
	s_cmp_gt_u32 s73, 29
	s_cbranch_scc0 .LBB0_356
	s_and_b64 vcc, exec, s[6:7]
	s_cbranch_vccz .LBB0_359
	s_barrier

; #define PG8_STAGE(bufoff, gbase, voff) do { _Pragma("unroll") for (int _i = 0; _i < 2; ++_i) \
;         __builtin_amdgcn_global_load_lds((const unsigned*)((const char*)(gbase) + (voff)[_i]), (LAS unsigned*)(lds + (bufoff) + ldsw + _i * 8192), 16, 0, 0); } while (0)
; #define PG8_LDA(dst, b, h) do { _Pragma("unroll") for (int m = 0; m < 4; ++m) _Pragma("unroll") for (int k = 0; k < 2; ++k) dst[m][k] = *(const LAS bf16x8*)(lds + PG8_SA(b, h) + aoff + m * 2048 + k * 1024); } while (0)
; #define PG8_LDB(dst, b, h) do { _Pragma("unroll") for (int n = 0; n < 2; ++n) _Pragma("unroll") for (int k = 0; k < 2; ++k) dst[n][k] = *(const LAS bf16x8*)(lds + PG8_SB(b, h) + boff + n * 2048 + k * 1024); } while (0)
; #define PG8_MMA(ai, bj, At, Bt) do { __builtin_amdgcn_s_setprio(1); _Pragma("unroll") for (int m = 0; m < 4; ++m) _Pragma("unroll") for (int n = 0; n < 2; ++n) _Pragma("unroll") for (int k = 0; k < 2; ++k) \
;         acc[ai][bj][m][n] = __builtin_amdgcn_mfma_f32_16x16x32_bf16(Bt[n][k], At[m][k], acc[ai][bj][m][n], 0, 0, 0); __builtin_amdgcn_s_setprio(0); } while (0)
; #define PG8_WAIT_V(n) asm volatile("s_waitcnt vmcnt(" #n ")" ::: "memory")
; #define PG8_WAIT_L(n) asm volatile("s_waitcnt lgkmcnt(" #n ")" ::: "memory")
; #define PG8_BAR __builtin_amdgcn_s_barrier()
; template <class Epi, class Sched, bool ALIGN_EPI = false, bool SP2 = false>
; __device__ __forceinline__ void gemm_phase(LAS unsigned char* lds, const Gemm g, const Sched& S, const Epi& E) {
;     ...
;             const bool last = (t == nt - 2);
;             const char* a1 = cA + (size_t)(t + 1) * kstep;
;             const char* a2 = last ? nA : cA + (size_t)(t + 2) * kstep; const char* b2 = last ? nB : cB + (size_t)(t + 2) * kstep;
;             const char* a3 = a2 + kstep; const char* b3 = b2 + kstep;
;             if (last && has_next) S.a_ready(nxt);
;             if constexpr (SP2) {
;             PG8_LDB(B0, 0, 0); PG8_LDB(B1, 0, 1); PG8_SCHED; PG8_LDA(At, 0, 0); PG8_STAGE(PG8_SA(1, 1), a1 + hstep, voffA);
;             PG8_WAIT_V(8); PG8_WAIT_L(0); PG8_BAR; PG8_MMA(0, 0, At, B0); PG8_MMA(0, 1, At, B1); PG8_BAR; PG8_SCHED;
;             PG8_LDA(At, 0, 1); PG8_STAGE(PG8_SB(0, 0), b2, voffB); PG8_STAGE(PG8_SB(0, 1), b2 + hstep, voffB); PG8_STAGE(PG8_SA(0, 0), a2, voffA);
;             PG8_WAIT_V(8); PG8_WAIT_L(0); PG8_BAR; PG8_MMA(1, 0, At, B0); PG8_MMA(1, 1, At, B1); PG8_BAR; PG8_SCHED;
.LBB0_429:
	s_add_u32 s14, s42, 0xfff80080
	s_addc_u32 s15, s43, -1
	s_add_i32 s20, 0, 0x10000
	s_cmp_eq_u32 s73, 28
	s_cselect_b32 s59, s31, s15
	s_cselect_b32 s58, s33, s14
	s_cselect_b32 s47, s9, s72
	s_cselect_b32 s46, s70, s71
	s_add_i32 s21, 0, 0x14000
	v_add_u32_e32 v142, s20, v236
	v_add_u32_e32 v158, s21, v236
	ds_read_b128 v[130:133], v142
	ds_read_b128 v[134:137], v142 offset:1024
	ds_read_b128 v[138:141], v142 offset:2048
	ds_read_b128 v[142:145], v142 offset:3072
	ds_read_b128 v[146:149], v158
	ds_read_b128 v[150:153], v158 offset:1024
	ds_read_b128 v[154:157], v158 offset:2048
	ds_read_b128 v[158:161], v158 offset:3072
	v_lshl_add_u64 v[216:217], s[42:43], 0, v[204:205]
	s_add_i32 m0, s27, 0xc000
	ds_read_b128 v[162:165], v238
	ds_read_b128 v[166:169], v238 offset:1024
	ds_read_b128 v[170:173], v238 offset:2048
	ds_read_b128 v[174:177], v238 offset:3072
	ds_read_b128 v[178:181], v238 offset:4096
	ds_read_b128 v[182:185], v238 offset:5120
	ds_read_b128 v[208:211], v238 offset:6144
	ds_read_b128 v[212:215], v238 offset:7168
	global_load_lds_dwordx4 v[216:217], off
	v_lshl_add_u64 v[216:217], s[42:43], 0, v[206:207]
	s_add_i32 m0, s27, 0xe000
	s_nop 0
	global_load_lds_dwordx4 v[216:217], off
	s_waitcnt vmcnt(8)
	s_waitcnt lgkmcnt(0)
	s_barrier
	s_setprio 1
	s_waitcnt lgkmcnt(0)
	v_mfma_f32_16x16x32_bf16 v[126:129], v[130:133], v[162:165], v[126:129]
	v_mfma_f32_16x16x32_bf16 v[122:125], v[138:141], v[162:165], v[122:125]
	v_mfma_f32_16x16x32_bf16 v[110:113], v[130:133], v[170:173], v[110:113]
	v_mfma_f32_16x16x32_bf16 v[106:109], v[138:141], v[170:173], v[106:109]
	v_mfma_f32_16x16x32_bf16 v[94:97], v[130:133], v[178:181], v[94:97]
	v_mfma_f32_16x16x32_bf16 v[90:93], v[138:141], v[178:181], v[90:93]
	v_mfma_f32_16x16x32_bf16 v[78:81], v[130:133], v[208:211], v[78:81]
	v_mfma_f32_16x16x32_bf16 v[74:77], v[138:141], v[208:211], v[74:77]
	v_mfma_f32_16x16x32_bf16 v[126:129], v[134:137], v[166:169], v[126:129]
	v_mfma_f32_16x16x32_bf16 v[122:125], v[142:145], v[166:169], v[122:125]
	v_mfma_f32_16x16x32_bf16 v[110:113], v[134:137], v[174:177], v[110:113]
	v_mfma_f32_16x16x32_bf16 v[106:109], v[142:145], v[174:177], v[106:109]
	v_mfma_f32_16x16x32_bf16 v[94:97], v[134:137], v[182:185], v[94:97]
	v_mfma_f32_16x16x32_bf16 v[90:93], v[142:145], v[182:185], v[90:93]
	v_mfma_f32_16x16x32_bf16 v[78:81], v[134:137], v[212:215], v[78:81]
	v_mfma_f32_16x16x32_bf16 v[74:77], v[142:145], v[212:215], v[74:77]
	s_setprio 0
	s_setprio 1
	v_mfma_f32_16x16x32_bf16 v[118:121], v[146:149], v[162:165], v[118:121]
	v_mfma_f32_16x16x32_bf16 v[114:117], v[154:157], v[162:165], v[114:117]
	v_mfma_f32_16x16x32_bf16 v[102:105], v[146:149], v[170:173], v[102:105]
	v_mfma_f32_16x16x32_bf16 v[98:101], v[154:157], v[170:173], v[98:101]
	v_mfma_f32_16x16x32_bf16 v[86:89], v[146:149], v[178:181], v[86:89]
	v_mfma_f32_16x16x32_bf16 v[82:85], v[154:157], v[178:181], v[82:85]
	v_mfma_f32_16x16x32_bf16 v[70:73], v[146:149], v[208:211], v[70:73]
	v_mfma_f32_16x16x32_bf16 v[66:69], v[154:157], v[208:211], v[66:69]
	v_mfma_f32_16x16x32_bf16 v[118:121], v[150:153], v[166:169], v[118:121]
	v_mfma_f32_16x16x32_bf16 v[114:117], v[158:161], v[166:169], v[114:117]
	v_mfma_f32_16x16x32_bf16 v[102:105], v[150:153], v[174:177], v[102:105]
	v_mfma_f32_16x16x32_bf16 v[98:101], v[158:161], v[174:177], v[98:101]
	v_mfma_f32_16x16x32_bf16 v[86:89], v[150:153], v[182:185], v[86:89]
	v_mfma_f32_16x16x32_bf16 v[82:85], v[158:161], v[182:185], v[82:85]
	v_mfma_f32_16x16x32_bf16 v[70:73], v[150:153], v[212:215], v[70:73]
	v_mfma_f32_16x16x32_bf16 v[66:69], v[158:161], v[212:215], v[66:69]
	s_setprio 0
	s_barrier
	s_add_i32 s14, s20, s4
	v_lshl_add_u64 v[216:217], s[46:47], 0, v[0:1]
	s_mov_b32 m0, s14
	ds_read_b128 v[162:165], v238 offset:16384
	ds_read_b128 v[166:169], v238 offset:17408
	ds_read_b128 v[170:173], v238 offset:18432
	ds_read_b128 v[174:177], v238 offset:19456
	ds_read_b128 v[178:181], v238 offset:20480
	ds_read_b128 v[182:185], v238 offset:21504
	ds_read_b128 v[208:211], v238 offset:22528
	ds_read_b128 v[212:215], v238 offset:23552
	global_load_lds_dwordx4 v[216:217], off
	s_add_i32 m0, s14, 0x2000
	s_add_u32 s14, s46, 0x80000
	v_lshl_add_u64 v[218:219], s[46:47], 0, v[198:199]
	s_addc_u32 s15, s47, 0
	s_add_i32 s20, s21, s4
	global_load_lds_dwordx4 v[218:219], off
	v_lshl_add_u64 v[220:221], s[14:15], 0, v[0:1]
	s_mov_b32 m0, s20
	global_load_lds_dwordx4 v[220:221], off
	v_lshl_add_u64 v[220:221], s[14:15], 0, v[198:199]
	s_add_i32 m0, s20, 0x2000
	s_nop 0
	global_load_lds_dwordx4 v[220:221], off
	s_waitcnt vmcnt(6)
	s_waitcnt lgkmcnt(0)
	s_barrier
; #define PG8_STAGE(bufoff, gbase, voff) do { _Pragma("unroll") for (int _i = 0; _i < 2; ++_i) \
;         __builtin_amdgcn_global_load_lds((const unsigned*)((const char*)(gbase) + (voff)[_i]), (LAS unsigned*)(lds + (bufoff) + ldsw + _i * 8192), 16, 0, 0); } while (0)
; #define PG8_LDA(dst, b, h) do { _Pragma("unroll") for (int m = 0; m < 4; ++m) _Pragma("unroll") for (int k = 0; k < 2; ++k) dst[m][k] = *(const LAS bf16x8*)(lds + PG8_SA(b, h) + aoff + m * 2048 + k * 1024); } while (0)
; #define PG8_LDB(dst, b, h) do { _Pragma("unroll") for (int n = 0; n < 2; ++n) _Pragma("unroll") for (int k = 0; k < 2; ++k) dst[n][k] = *(const LAS bf16x8*)(lds + PG8_SB(b, h) + boff + n * 2048 + k * 1024); } while (0)
; #define PG8_MMA(ai, bj, At, Bt) do { __builtin_amdgcn_s_setprio(1); _Pragma("unroll") for (int m = 0; m < 4; ++m) _Pragma("unroll") for (int n = 0; n < 2; ++n) _Pragma("unroll") for (int k = 0; k < 2; ++k) \
;         acc[ai][bj][m][n] = __builtin_amdgcn_mfma_f32_16x16x32_bf16(Bt[n][k], At[m][k], acc[ai][bj][m][n], 0, 0, 0); __builtin_amdgcn_s_setprio(0); } while (0)
; #define PG8_WAIT_V(n) asm volatile("s_waitcnt vmcnt(" #n ")" ::: "memory")
; #define PG8_WAIT_L(n) asm volatile("s_waitcnt lgkmcnt(" #n ")" ::: "memory")
; #define PG8_BAR __builtin_amdgcn_s_barrier()
; #define PG8_SCHED __builtin_amdgcn_sched_barrier(0)
; template <class Epi, class Sched, bool ALIGN_EPI = false, bool SP2 = false>
; __device__ __forceinline__ void gemm_phase(LAS unsigned char* lds, const Gemm g, const Sched& S, const Epi& E) {
;     ...
;             PG8_WAIT_V(8); PG8_WAIT_L(0); PG8_BAR; PG8_MMA(1, 0, At, B0); PG8_MMA(1, 1, At, B1); PG8_BAR; PG8_SCHED;
;             PG8_LDB(B0, 1, 0); PG8_LDB(B1, 1, 1); PG8_SCHED; PG8_LDA(At, 1, 0); PG8_STAGE(PG8_SA(0, 1), a2 + hstep, voffA);
;             PG8_WAIT_V(8); PG8_WAIT_L(0); PG8_BAR; PG8_MMA(0, 0, At, B0); PG8_MMA(0, 1, At, B1); PG8_BAR; PG8_SCHED;
	s_setprio 1
	s_waitcnt lgkmcnt(0)
	v_mfma_f32_16x16x32_bf16 v[62:65], v[130:133], v[162:165], v[62:65]
	v_mfma_f32_16x16x32_bf16 v[58:61], v[138:141], v[162:165], v[58:61]
	v_mfma_f32_16x16x32_bf16 v[46:49], v[130:133], v[170:173], v[46:49]
	v_mfma_f32_16x16x32_bf16 v[42:45], v[138:141], v[170:173], v[42:45]
	v_mfma_f32_16x16x32_bf16 v[30:33], v[130:133], v[178:181], v[30:33]
	v_mfma_f32_16x16x32_bf16 v[26:29], v[138:141], v[178:181], v[26:29]
	v_mfma_f32_16x16x32_bf16 v[14:17], v[130:133], v[208:211], v[14:17]
	v_mfma_f32_16x16x32_bf16 v[10:13], v[138:141], v[208:211], v[10:13]
	v_mfma_f32_16x16x32_bf16 v[62:65], v[134:137], v[166:169], v[62:65]
	v_mfma_f32_16x16x32_bf16 v[58:61], v[142:145], v[166:169], v[58:61]
	v_mfma_f32_16x16x32_bf16 v[46:49], v[134:137], v[174:177], v[46:49]
	v_mfma_f32_16x16x32_bf16 v[42:45], v[142:145], v[174:177], v[42:45]
	v_mfma_f32_16x16x32_bf16 v[30:33], v[134:137], v[182:185], v[30:33]
	v_mfma_f32_16x16x32_bf16 v[26:29], v[142:145], v[182:185], v[26:29]
	v_mfma_f32_16x16x32_bf16 v[14:17], v[134:137], v[212:215], v[14:17]
	v_mfma_f32_16x16x32_bf16 v[10:13], v[142:145], v[212:215], v[10:13]
	s_setprio 0
	s_setprio 1
	v_mfma_f32_16x16x32_bf16 v[54:57], v[146:149], v[162:165], v[54:57]
	v_mfma_f32_16x16x32_bf16 v[50:53], v[154:157], v[162:165], v[50:53]
	v_mfma_f32_16x16x32_bf16 v[38:41], v[146:149], v[170:173], v[38:41]
	v_mfma_f32_16x16x32_bf16 v[34:37], v[154:157], v[170:173], v[34:37]
	v_mfma_f32_16x16x32_bf16 v[22:25], v[146:149], v[178:181], v[22:25]
	v_mfma_f32_16x16x32_bf16 v[18:21], v[154:157], v[178:181], v[18:21]
	v_mfma_f32_16x16x32_bf16 v[6:9], v[146:149], v[208:211], v[6:9]
	v_mfma_f32_16x16x32_bf16 v[2:5], v[154:157], v[208:211], v[2:5]
	v_mfma_f32_16x16x32_bf16 v[54:57], v[150:153], v[166:169], v[54:57]
	v_mfma_f32_16x16x32_bf16 v[50:53], v[158:161], v[166:169], v[50:53]
	v_mfma_f32_16x16x32_bf16 v[38:41], v[150:153], v[174:177], v[38:41]
	v_mfma_f32_16x16x32_bf16 v[34:37], v[158:161], v[174:177], v[34:37]
	v_mfma_f32_16x16x32_bf16 v[22:25], v[150:153], v[182:185], v[22:25]
	v_mfma_f32_16x16x32_bf16 v[18:21], v[158:161], v[182:185], v[18:21]
	v_mfma_f32_16x16x32_bf16 v[6:9], v[150:153], v[212:215], v[6:9]
	v_mfma_f32_16x16x32_bf16 v[2:5], v[158:161], v[212:215], v[2:5]
	s_setprio 0
	s_barrier
	s_add_i32 s20, 0, 0x18000
	s_add_i32 s21, 0, 0x1c000
	v_add_u32_e32 v142, s20, v236
	v_add_u32_e32 v158, s21, v236
	ds_read_b128 v[130:133], v142
	ds_read_b128 v[134:137], v142 offset:1024
	ds_read_b128 v[138:141], v142 offset:2048
	ds_read_b128 v[142:145], v142 offset:3072
	ds_read_b128 v[146:149], v158
	ds_read_b128 v[150:153], v158 offset:1024
	ds_read_b128 v[154:157], v158 offset:2048
	ds_read_b128 v[158:161], v158 offset:3072
	s_add_u32 s14, s58, 0x80000
	s_addc_u32 s15, s59, 0
	s_mov_b32 m0, s45
	v_lshl_add_u64 v[242:243], s[14:15], 0, v[202:203]
	ds_read_b128 v[162:165], v238 offset:32768
	ds_read_b128 v[166:169], v238 offset:33792
	ds_read_b128 v[170:173], v238 offset:34816
	ds_read_b128 v[174:177], v238 offset:35840
	ds_read_b128 v[178:181], v238 offset:36864
	ds_read_b128 v[182:185], v238 offset:37888
	ds_read_b128 v[208:211], v238 offset:38912
	ds_read_b128 v[212:215], v238 offset:39936
	v_lshl_add_u64 v[220:221], s[58:59], 0, v[202:203]
	s_mov_b32 m0, s27
	v_lshl_add_u64 v[240:241], s[58:59], 0, v[200:201]
	global_load_lds_dwordx4 v[220:221], off
	s_mov_b32 m0, s44
	s_nop 0
	global_load_lds_dwordx4 v[240:241], off
	s_mov_b32 m0, s45
	s_nop 0
	global_load_lds_dwordx4 v[242:243], off
	v_lshl_add_u64 v[242:243], s[14:15], 0, v[200:201]
	s_mov_b32 m0, s66
	s_nop 0
	global_load_lds_dwordx4 v[242:243], off
	s_waitcnt vmcnt(8)
	s_waitcnt lgkmcnt(0)
	s_barrier
	s_setprio 1
	s_waitcnt lgkmcnt(0)
	v_mfma_f32_16x16x32_bf16 v[126:129], v[130:133], v[162:165], v[126:129]
	v_mfma_f32_16x16x32_bf16 v[122:125], v[138:141], v[162:165], v[122:125]
	v_mfma_f32_16x16x32_bf16 v[110:113], v[130:133], v[170:173], v[110:113]
	v_mfma_f32_16x16x32_bf16 v[106:109], v[138:141], v[170:173], v[106:109]
	v_mfma_f32_16x16x32_bf16 v[94:97], v[130:133], v[178:181], v[94:97]
	v_mfma_f32_16x16x32_bf16 v[90:93], v[138:141], v[178:181], v[90:93]
	v_mfma_f32_16x16x32_bf16 v[78:81], v[130:133], v[208:211], v[78:81]
	v_mfma_f32_16x16x32_bf16 v[74:77], v[138:141], v[208:211], v[74:77]
	v_mfma_f32_16x16x32_bf16 v[126:129], v[134:137], v[166:169], v[126:129]
	v_mfma_f32_16x16x32_bf16 v[122:125], v[142:145], v[166:169], v[122:125]
	v_mfma_f32_16x16x32_bf16 v[110:113], v[134:137], v[174:177], v[110:113]
	v_mfma_f32_16x16x32_bf16 v[106:109], v[142:145], v[174:177], v[106:109]
	v_mfma_f32_16x16x32_bf16 v[94:97], v[134:137], v[182:185], v[94:97]
	v_mfma_f32_16x16x32_bf16 v[90:93], v[142:145], v[182:185], v[90:93]
	v_mfma_f32_16x16x32_bf16 v[78:81], v[134:137], v[212:215], v[78:81]
	v_mfma_f32_16x16x32_bf16 v[74:77], v[142:145], v[212:215], v[74:77]
	s_setprio 0
	s_setprio 1
	v_mfma_f32_16x16x32_bf16 v[118:121], v[146:149], v[162:165], v[118:121]
	v_mfma_f32_16x16x32_bf16 v[114:117], v[154:157], v[162:165], v[114:117]
	v_mfma_f32_16x16x32_bf16 v[102:105], v[146:149], v[170:173], v[102:105]
	v_mfma_f32_16x16x32_bf16 v[98:101], v[154:157], v[170:173], v[98:101]
	v_mfma_f32_16x16x32_bf16 v[86:89], v[146:149], v[178:181], v[86:89]
	v_mfma_f32_16x16x32_bf16 v[82:85], v[154:157], v[178:181], v[82:85]
	v_mfma_f32_16x16x32_bf16 v[70:73], v[146:149], v[208:211], v[70:73]
	v_mfma_f32_16x16x32_bf16 v[66:69], v[154:157], v[208:211], v[66:69]
	v_mfma_f32_16x16x32_bf16 v[118:121], v[150:153], v[166:169], v[118:121]
	v_mfma_f32_16x16x32_bf16 v[114:117], v[158:161], v[166:169], v[114:117]
	v_mfma_f32_16x16x32_bf16 v[102:105], v[150:153], v[174:177], v[102:105]
	v_mfma_f32_16x16x32_bf16 v[98:101], v[158:161], v[174:177], v[98:101]
	v_mfma_f32_16x16x32_bf16 v[86:89], v[150:153], v[182:185], v[86:89]
	v_mfma_f32_16x16x32_bf16 v[82:85], v[158:161], v[182:185], v[82:85]
	v_mfma_f32_16x16x32_bf16 v[70:73], v[150:153], v[212:215], v[70:73]
	v_mfma_f32_16x16x32_bf16 v[66:69], v[158:161], v[212:215], v[66:69]
	s_setprio 0
	s_barrier
; #define PG8_STAGE(bufoff, gbase, voff) do { _Pragma("unroll") for (int _i = 0; _i < 2; ++_i) \
;         __builtin_amdgcn_global_load_lds((const unsigned*)((const char*)(gbase) + (voff)[_i]), (LAS unsigned*)(lds + (bufoff) + ldsw + _i * 8192), 16, 0, 0); } while (0)
; #define PG8_LDA(dst, b, h) do { _Pragma("unroll") for (int m = 0; m < 4; ++m) _Pragma("unroll") for (int k = 0; k < 2; ++k) dst[m][k] = *(const LAS bf16x8*)(lds + PG8_SA(b, h) + aoff + m * 2048 + k * 1024); } while (0)
; #define PG8_MMA(ai, bj, At, Bt) do { __builtin_amdgcn_s_setprio(1); _Pragma("unroll") for (int m = 0; m < 4; ++m) _Pragma("unroll") for (int n = 0; n < 2; ++n) _Pragma("unroll") for (int k = 0; k < 2; ++k) \
;         acc[ai][bj][m][n] = __builtin_amdgcn_mfma_f32_16x16x32_bf16(Bt[n][k], At[m][k], acc[ai][bj][m][n], 0, 0, 0); __builtin_amdgcn_s_setprio(0); } while (0)
; #define PG8_WAIT_V(n) asm volatile("s_waitcnt vmcnt(" #n ")" ::: "memory")
; #define PG8_WAIT_L(n) asm volatile("s_waitcnt lgkmcnt(" #n ")" ::: "memory")
; #define PG8_BAR __builtin_amdgcn_s_barrier()
; #define PG8_SCHED __builtin_amdgcn_sched_barrier(0)
; template <class Epi, class Sched, bool ALIGN_EPI = false, bool SP2 = false>
; __device__ __forceinline__ void gemm_phase(LAS unsigned char* lds, const Gemm g, const Sched& S, const Epi& E) {
;     ...
;             PG8_LDA(At, 1, 1); PG8_STAGE(PG8_SB(1, 0), b3, voffB); PG8_STAGE(PG8_SB(1, 1), b3 + hstep, voffB); PG8_STAGE(PG8_SA(1, 0), a3, voffA);
;             PG8_WAIT_V(8); PG8_WAIT_L(0); PG8_BAR; PG8_MMA(1, 0, At, B0); PG8_MMA(1, 1, At, B1); PG8_BAR; PG8_SCHED;
	s_add_i32 s14, s20, s4
	v_lshl_add_u64 v[216:217], v[216:217], 0, s[18:19]
	s_mov_b32 m0, s14
	ds_read_b128 v[162:165], v238 offset:49152
	ds_read_b128 v[166:169], v238 offset:50176
	ds_read_b128 v[170:173], v238 offset:51200
	ds_read_b128 v[174:177], v238 offset:52224
	ds_read_b128 v[178:181], v238 offset:53248
	ds_read_b128 v[182:185], v238 offset:54272
	ds_read_b128 v[208:211], v238 offset:55296
	ds_read_b128 v[212:215], v238 offset:56320
	global_load_lds_dwordx4 v[216:217], off
	s_add_i32 m0, s14, 0x2000
	s_add_u32 s14, s46, 0x80080
	v_lshl_add_u64 v[216:217], v[218:219], 0, s[18:19]
	s_addc_u32 s15, s47, 0
	s_add_i32 s20, s21, s4
	global_load_lds_dwordx4 v[216:217], off
	v_lshl_add_u64 v[216:217], s[14:15], 0, v[0:1]
	s_mov_b32 m0, s20
	s_nop 0
	global_load_lds_dwordx4 v[216:217], off
	v_lshl_add_u64 v[216:217], s[14:15], 0, v[198:199]
	s_add_i32 m0, s20, 0x2000
	s_nop 0
	global_load_lds_dwordx4 v[216:217], off
	v_lshl_add_u64 v[216:217], v[220:221], 0, s[18:19]
	s_mov_b32 m0, s67
	s_nop 0
	global_load_lds_dwordx4 v[216:217], off
	v_lshl_add_u64 v[216:217], v[240:241], 0, s[18:19]
	s_mov_b32 m0, s68
	s_nop 0
	global_load_lds_dwordx4 v[216:217], off
	s_waitcnt vmcnt(8)
	s_waitcnt lgkmcnt(0)
	s_barrier
	s_setprio 1
	s_waitcnt lgkmcnt(0)
	v_mfma_f32_16x16x32_bf16 v[62:65], v[130:133], v[162:165], v[62:65]
	v_mfma_f32_16x16x32_bf16 v[58:61], v[138:141], v[162:165], v[58:61]
	v_mfma_f32_16x16x32_bf16 v[46:49], v[130:133], v[170:173], v[46:49]
	v_mfma_f32_16x16x32_bf16 v[42:45], v[138:141], v[170:173], v[42:45]
	v_mfma_f32_16x16x32_bf16 v[30:33], v[130:133], v[178:181], v[30:33]
	v_mfma_f32_16x16x32_bf16 v[26:29], v[138:141], v[178:181], v[26:29]
	v_mfma_f32_16x16x32_bf16 v[14:17], v[130:133], v[208:211], v[14:17]
	v_mfma_f32_16x16x32_bf16 v[10:13], v[138:141], v[208:211], v[10:13]
	v_mfma_f32_16x16x32_bf16 v[62:65], v[134:137], v[166:169], v[62:65]
	v_mfma_f32_16x16x32_bf16 v[58:61], v[142:145], v[166:169], v[58:61]
	v_mfma_f32_16x16x32_bf16 v[46:49], v[134:137], v[174:177], v[46:49]
	v_mfma_f32_16x16x32_bf16 v[42:45], v[142:145], v[174:177], v[42:45]
	v_mfma_f32_16x16x32_bf16 v[30:33], v[134:137], v[182:185], v[30:33]
	v_mfma_f32_16x16x32_bf16 v[26:29], v[142:145], v[182:185], v[26:29]
	v_mfma_f32_16x16x32_bf16 v[14:17], v[134:137], v[212:215], v[14:17]
	v_mfma_f32_16x16x32_bf16 v[10:13], v[142:145], v[212:215], v[10:13]
	s_setprio 0
	s_setprio 1
	v_mfma_f32_16x16x32_bf16 v[54:57], v[146:149], v[162:165], v[54:57]
	v_mfma_f32_16x16x32_bf16 v[50:53], v[154:157], v[162:165], v[50:53]
	v_mfma_f32_16x16x32_bf16 v[38:41], v[146:149], v[170:173], v[38:41]
	v_mfma_f32_16x16x32_bf16 v[34:37], v[154:157], v[170:173], v[34:37]
	v_mfma_f32_16x16x32_bf16 v[22:25], v[146:149], v[178:181], v[22:25]
	v_mfma_f32_16x16x32_bf16 v[18:21], v[154:157], v[178:181], v[18:21]
	v_mfma_f32_16x16x32_bf16 v[6:9], v[146:149], v[208:211], v[6:9]
	v_mfma_f32_16x16x32_bf16 v[2:5], v[154:157], v[208:211], v[2:5]
	v_mfma_f32_16x16x32_bf16 v[54:57], v[150:153], v[166:169], v[54:57]
	v_mfma_f32_16x16x32_bf16 v[50:53], v[158:161], v[166:169], v[50:53]
	v_mfma_f32_16x16x32_bf16 v[38:41], v[150:153], v[174:177], v[38:41]
	v_mfma_f32_16x16x32_bf16 v[34:37], v[158:161], v[174:177], v[34:37]
	v_mfma_f32_16x16x32_bf16 v[22:25], v[150:153], v[182:185], v[22:25]
	v_mfma_f32_16x16x32_bf16 v[18:21], v[158:161], v[182:185], v[18:21]
	v_mfma_f32_16x16x32_bf16 v[6:9], v[150:153], v[212:215], v[6:9]
	v_mfma_f32_16x16x32_bf16 v[2:5], v[158:161], v[212:215], v[2:5]
	s_setprio 0
	s_barrier
	s_add_i32 s73, s73, 2
	s_add_u32 s42, s42, 0x100
	s_addc_u32 s43, s43, 0
	s_add_u32 s71, s71, 0x100
	s_addc_u32 s72, s72, 0
	s_cmp_gt_u32 s73, 29
	s_cbranch_scc0 .LBB0_429
	s_and_b64 vcc, exec, s[6:7]
	s_cbranch_vccz .LBB0_432
	s_barrier

; #define PG8_STAGE(bufoff, gbase, voff) do { _Pragma("unroll") for (int _i = 0; _i < 2; ++_i) \
;         __builtin_amdgcn_global_load_lds((const unsigned*)((const char*)(gbase) + (voff)[_i]), (LAS unsigned*)(lds + (bufoff) + ldsw + _i * 8192), 16, 0, 0); } while (0)
; #define PG8_LDA(dst, b, h) do { _Pragma("unroll") for (int m = 0; m < 4; ++m) _Pragma("unroll") for (int k = 0; k < 2; ++k) dst[m][k] = *(const LAS bf16x8*)(lds + PG8_SA(b, h) + aoff + m * 2048 + k * 1024); } while (0)
; #define PG8_LDB(dst, b, h) do { _Pragma("unroll") for (int n = 0; n < 2; ++n) _Pragma("unroll") for (int k = 0; k < 2; ++k) dst[n][k] = *(const LAS bf16x8*)(lds + PG8_SB(b, h) + boff + n * 2048 + k * 1024); } while (0)
; #define PG8_MMA(ai, bj, At, Bt) do { __builtin_amdgcn_s_setprio(1); _Pragma("unroll") for (int m = 0; m < 4; ++m) _Pragma("unroll") for (int n = 0; n < 2; ++n) _Pragma("unroll") for (int k = 0; k < 2; ++k) \
;         acc[ai][bj][m][n] = __builtin_amdgcn_mfma_f32_16x16x32_bf16(Bt[n][k], At[m][k], acc[ai][bj][m][n], 0, 0, 0); __builtin_amdgcn_s_setprio(0); } while (0)
; #define PG8_WAIT_V(n) asm volatile("s_waitcnt vmcnt(" #n ")" ::: "memory")
; #define PG8_WAIT_L(n) asm volatile("s_waitcnt lgkmcnt(" #n ")" ::: "memory")
; #define PG8_BAR __builtin_amdgcn_s_barrier()
; template <class Epi, class Sched, bool ALIGN_EPI = false, bool SP2 = false>
; __device__ __forceinline__ void gemm_phase(LAS unsigned char* lds, const Gemm g, const Sched& S, const Epi& E) {
;     ...
;             const bool last = (t == nt - 2);
;             const char* a1 = cA + (size_t)(t + 1) * kstep;
;             const char* a2 = last ? nA : cA + (size_t)(t + 2) * kstep; const char* b2 = last ? nB : cB + (size_t)(t + 2) * kstep;
;             const char* a3 = a2 + kstep; const char* b3 = b2 + kstep;
;             if (last && has_next) S.a_ready(nxt);
;             if constexpr (SP2) {
;             PG8_LDB(B0, 0, 0); PG8_LDB(B1, 0, 1); PG8_SCHED; PG8_LDA(At, 0, 0); PG8_STAGE(PG8_SA(1, 1), a1 + hstep, voffA);
;             PG8_WAIT_V(8); PG8_WAIT_L(0); PG8_BAR; PG8_MMA(0, 0, At, B0); PG8_MMA(0, 1, At, B1); PG8_BAR; PG8_SCHED;
;             PG8_LDA(At, 0, 1); PG8_STAGE(PG8_SB(0, 0), b2, voffB); PG8_STAGE(PG8_SB(0, 1), b2 + hstep, voffB); PG8_STAGE(PG8_SA(0, 0), a2, voffA);
;             PG8_WAIT_V(8); PG8_WAIT_L(0); PG8_BAR; PG8_MMA(1, 0, At, B0); PG8_MMA(1, 1, At, B1); PG8_BAR; PG8_SCHED;
.LBB0_504:
	s_add_u32 s58, s46, 0x100
	s_addc_u32 s59, s47, 0
	s_add_i32 s14, 0, 0x10000
	s_cmp_eq_u32 s96, 28
	s_cselect_b32 s69, s33, s59
	s_cselect_b32 s68, s35, s58
	s_cselect_b32 s67, s31, s95
	s_cselect_b32 s66, s72, s73
	s_add_i32 s20, 0, 0x14000
	v_add_u32_e32 v142, s14, v181
	v_add_u32_e32 v158, s20, v181
	ds_read_b128 v[130:133], v142
	ds_read_b128 v[134:137], v142 offset:1024
	ds_read_b128 v[138:141], v142 offset:2048
	ds_read_b128 v[142:145], v142 offset:3072
	ds_read_b128 v[146:149], v158
	ds_read_b128 v[150:153], v158 offset:1024
	ds_read_b128 v[154:157], v158 offset:2048
	ds_read_b128 v[158:161], v158 offset:3072
	v_lshl_add_u64 v[184:185], s[46:47], 0, v[164:165]
	s_add_i32 m0, s27, 0xc000
	ds_read_b128 v[168:171], v183
	ds_read_b128 v[172:175], v183 offset:1024
	ds_read_b128 v[176:179], v183 offset:2048
	ds_read_b128 v[198:201], v183 offset:3072
	ds_read_b128 v[202:205], v183 offset:4096
	ds_read_b128 v[206:209], v183 offset:5120
	ds_read_b128 v[210:213], v183 offset:6144
	ds_read_b128 v[214:217], v183 offset:7168
	global_load_lds_dwordx4 v[184:185], off
	v_lshl_add_u64 v[184:185], s[46:47], 0, v[166:167]
	s_add_i32 m0, s27, 0xe000
	s_nop 0
	global_load_lds_dwordx4 v[184:185], off
	s_waitcnt vmcnt(8)
	s_waitcnt lgkmcnt(0)
	s_barrier
	s_setprio 1
	s_waitcnt lgkmcnt(0)
	v_mfma_f32_16x16x32_bf16 v[110:113], v[130:133], v[168:171], v[110:113]
	v_mfma_f32_16x16x32_bf16 v[106:109], v[138:141], v[168:171], v[106:109]
	v_mfma_f32_16x16x32_bf16 v[126:129], v[130:133], v[176:179], v[126:129]
	v_mfma_f32_16x16x32_bf16 v[122:125], v[138:141], v[176:179], v[122:125]
	v_mfma_f32_16x16x32_bf16 v[94:97], v[130:133], v[202:205], v[94:97]
	v_mfma_f32_16x16x32_bf16 v[90:93], v[138:141], v[202:205], v[90:93]
	v_mfma_f32_16x16x32_bf16 v[78:81], v[130:133], v[210:213], v[78:81]
	v_mfma_f32_16x16x32_bf16 v[74:77], v[138:141], v[210:213], v[74:77]
	v_mfma_f32_16x16x32_bf16 v[110:113], v[134:137], v[172:175], v[110:113]
	v_mfma_f32_16x16x32_bf16 v[106:109], v[142:145], v[172:175], v[106:109]
	v_mfma_f32_16x16x32_bf16 v[126:129], v[134:137], v[198:201], v[126:129]
	v_mfma_f32_16x16x32_bf16 v[122:125], v[142:145], v[198:201], v[122:125]
	v_mfma_f32_16x16x32_bf16 v[94:97], v[134:137], v[206:209], v[94:97]
	v_mfma_f32_16x16x32_bf16 v[90:93], v[142:145], v[206:209], v[90:93]
	v_mfma_f32_16x16x32_bf16 v[78:81], v[134:137], v[214:217], v[78:81]
	v_mfma_f32_16x16x32_bf16 v[74:77], v[142:145], v[214:217], v[74:77]
	s_setprio 0
	s_setprio 1
	v_mfma_f32_16x16x32_bf16 v[102:105], v[146:149], v[168:171], v[102:105]
	v_mfma_f32_16x16x32_bf16 v[98:101], v[154:157], v[168:171], v[98:101]
	v_mfma_f32_16x16x32_bf16 v[118:121], v[146:149], v[176:179], v[118:121]
	v_mfma_f32_16x16x32_bf16 v[114:117], v[154:157], v[176:179], v[114:117]
	v_mfma_f32_16x16x32_bf16 v[86:89], v[146:149], v[202:205], v[86:89]
	v_mfma_f32_16x16x32_bf16 v[82:85], v[154:157], v[202:205], v[82:85]
	v_mfma_f32_16x16x32_bf16 v[70:73], v[146:149], v[210:213], v[70:73]
	v_mfma_f32_16x16x32_bf16 v[66:69], v[154:157], v[210:213], v[66:69]
	v_mfma_f32_16x16x32_bf16 v[102:105], v[150:153], v[172:175], v[102:105]
	v_mfma_f32_16x16x32_bf16 v[98:101], v[158:161], v[172:175], v[98:101]
	v_mfma_f32_16x16x32_bf16 v[118:121], v[150:153], v[198:201], v[118:121]
	v_mfma_f32_16x16x32_bf16 v[114:117], v[158:161], v[198:201], v[114:117]
	v_mfma_f32_16x16x32_bf16 v[86:89], v[150:153], v[206:209], v[86:89]
	v_mfma_f32_16x16x32_bf16 v[82:85], v[158:161], v[206:209], v[82:85]
	v_mfma_f32_16x16x32_bf16 v[70:73], v[150:153], v[214:217], v[70:73]
	v_mfma_f32_16x16x32_bf16 v[66:69], v[158:161], v[214:217], v[66:69]
	s_setprio 0
	s_barrier
	s_add_i32 s14, s14, s4
	v_lshl_add_u64 v[184:185], s[66:67], 0, v[0:1]
	s_mov_b32 m0, s14
	ds_read_b128 v[168:171], v183 offset:16384
	ds_read_b128 v[172:175], v183 offset:17408
	ds_read_b128 v[176:179], v183 offset:18432
	ds_read_b128 v[198:201], v183 offset:19456
	ds_read_b128 v[202:205], v183 offset:20480
	ds_read_b128 v[206:209], v183 offset:21504
	ds_read_b128 v[210:213], v183 offset:22528
	ds_read_b128 v[214:217], v183 offset:23552
	global_load_lds_dwordx4 v[184:185], off
	s_add_i32 m0, s14, 0x2000
	s_add_u32 s14, s66, 0x80000
	v_lshl_add_u64 v[186:187], s[66:67], 0, v[162:163]
	s_addc_u32 s15, s67, 0
	s_add_i32 s20, s20, s4
	global_load_lds_dwordx4 v[186:187], off
	v_lshl_add_u64 v[218:219], s[14:15], 0, v[0:1]
	s_mov_b32 m0, s20
	global_load_lds_dwordx4 v[218:219], off
	v_lshl_add_u64 v[218:219], s[14:15], 0, v[162:163]
	s_add_i32 m0, s20, 0x2000
	s_nop 0
	global_load_lds_dwordx4 v[218:219], off
	s_waitcnt vmcnt(6)
	s_waitcnt lgkmcnt(0)
	s_barrier
; #define PG8_STAGE(bufoff, gbase, voff) do { _Pragma("unroll") for (int _i = 0; _i < 2; ++_i) \
;         __builtin_amdgcn_global_load_lds((const unsigned*)((const char*)(gbase) + (voff)[_i]), (LAS unsigned*)(lds + (bufoff) + ldsw + _i * 8192), 16, 0, 0); } while (0)
; #define PG8_LDA(dst, b, h) do { _Pragma("unroll") for (int m = 0; m < 4; ++m) _Pragma("unroll") for (int k = 0; k < 2; ++k) dst[m][k] = *(const LAS bf16x8*)(lds + PG8_SA(b, h) + aoff + m * 2048 + k * 1024); } while (0)
; #define PG8_LDB(dst, b, h) do { _Pragma("unroll") for (int n = 0; n < 2; ++n) _Pragma("unroll") for (int k = 0; k < 2; ++k) dst[n][k] = *(const LAS bf16x8*)(lds + PG8_SB(b, h) + boff + n * 2048 + k * 1024); } while (0)
; #define PG8_MMA(ai, bj, At, Bt) do { __builtin_amdgcn_s_setprio(1); _Pragma("unroll") for (int m = 0; m < 4; ++m) _Pragma("unroll") for (int n = 0; n < 2; ++n) _Pragma("unroll") for (int k = 0; k < 2; ++k) \
;         acc[ai][bj][m][n] = __builtin_amdgcn_mfma_f32_16x16x32_bf16(Bt[n][k], At[m][k], acc[ai][bj][m][n], 0, 0, 0); __builtin_amdgcn_s_setprio(0); } while (0)
; #define PG8_WAIT_V(n) asm volatile("s_waitcnt vmcnt(" #n ")" ::: "memory")
; #define PG8_WAIT_L(n) asm volatile("s_waitcnt lgkmcnt(" #n ")" ::: "memory")
; #define PG8_BAR __builtin_amdgcn_s_barrier()
; #define PG8_SCHED __builtin_amdgcn_sched_barrier(0)
; template <class Epi, class Sched, bool ALIGN_EPI = false, bool SP2 = false>
; __device__ __forceinline__ void gemm_phase(LAS unsigned char* lds, const Gemm g, const Sched& S, const Epi& E) {
;     ...
;             PG8_WAIT_V(8); PG8_WAIT_L(0); PG8_BAR; PG8_MMA(1, 0, At, B0); PG8_MMA(1, 1, At, B1); PG8_BAR; PG8_SCHED;
;             PG8_LDB(B0, 1, 0); PG8_LDB(B1, 1, 1); PG8_SCHED; PG8_LDA(At, 1, 0); PG8_STAGE(PG8_SA(0, 1), a2 + hstep, voffA);
;             PG8_WAIT_V(8); PG8_WAIT_L(0); PG8_BAR; PG8_MMA(0, 0, At, B0); PG8_MMA(0, 1, At, B1); PG8_BAR; PG8_SCHED;
	s_setprio 1
	s_waitcnt lgkmcnt(0)
	v_mfma_f32_16x16x32_bf16 v[62:65], v[130:133], v[168:171], v[62:65]
	v_mfma_f32_16x16x32_bf16 v[58:61], v[138:141], v[168:171], v[58:61]
	v_mfma_f32_16x16x32_bf16 v[54:57], v[130:133], v[176:179], v[54:57]
	v_mfma_f32_16x16x32_bf16 v[42:45], v[138:141], v[176:179], v[42:45]
	v_mfma_f32_16x16x32_bf16 v[38:41], v[130:133], v[202:205], v[38:41]
	v_mfma_f32_16x16x32_bf16 v[26:29], v[138:141], v[202:205], v[26:29]
	v_mfma_f32_16x16x32_bf16 v[18:21], v[130:133], v[210:213], v[18:21]
	v_mfma_f32_16x16x32_bf16 v[10:13], v[138:141], v[210:213], v[10:13]
	v_mfma_f32_16x16x32_bf16 v[62:65], v[134:137], v[172:175], v[62:65]
	v_mfma_f32_16x16x32_bf16 v[58:61], v[142:145], v[172:175], v[58:61]
	v_mfma_f32_16x16x32_bf16 v[54:57], v[134:137], v[198:201], v[54:57]
	v_mfma_f32_16x16x32_bf16 v[42:45], v[142:145], v[198:201], v[42:45]
	v_mfma_f32_16x16x32_bf16 v[38:41], v[134:137], v[206:209], v[38:41]
	v_mfma_f32_16x16x32_bf16 v[26:29], v[142:145], v[206:209], v[26:29]
	v_mfma_f32_16x16x32_bf16 v[18:21], v[134:137], v[214:217], v[18:21]
	v_mfma_f32_16x16x32_bf16 v[10:13], v[142:145], v[214:217], v[10:13]
	s_setprio 0
	s_setprio 1
	v_mfma_f32_16x16x32_bf16 v[50:53], v[146:149], v[168:171], v[50:53]
	v_mfma_f32_16x16x32_bf16 v[46:49], v[154:157], v[168:171], v[46:49]
	v_mfma_f32_16x16x32_bf16 v[34:37], v[146:149], v[176:179], v[34:37]
	v_mfma_f32_16x16x32_bf16 v[30:33], v[154:157], v[176:179], v[30:33]
	v_mfma_f32_16x16x32_bf16 v[22:25], v[146:149], v[202:205], v[22:25]
	v_mfma_f32_16x16x32_bf16 v[14:17], v[154:157], v[202:205], v[14:17]
	v_mfma_f32_16x16x32_bf16 v[6:9], v[146:149], v[210:213], v[6:9]
	v_mfma_f32_16x16x32_bf16 v[2:5], v[154:157], v[210:213], v[2:5]
	v_mfma_f32_16x16x32_bf16 v[50:53], v[150:153], v[172:175], v[50:53]
	v_mfma_f32_16x16x32_bf16 v[46:49], v[158:161], v[172:175], v[46:49]
	v_mfma_f32_16x16x32_bf16 v[34:37], v[150:153], v[198:201], v[34:37]
	v_mfma_f32_16x16x32_bf16 v[30:33], v[158:161], v[198:201], v[30:33]
	v_mfma_f32_16x16x32_bf16 v[22:25], v[150:153], v[206:209], v[22:25]
	v_mfma_f32_16x16x32_bf16 v[14:17], v[158:161], v[206:209], v[14:17]
	v_mfma_f32_16x16x32_bf16 v[6:9], v[150:153], v[214:217], v[6:9]
	v_mfma_f32_16x16x32_bf16 v[2:5], v[158:161], v[214:217], v[2:5]
	s_setprio 0
	s_barrier
	s_add_i32 s20, 0, 0x18000
	s_add_i32 s21, 0, 0x1c000
	v_add_u32_e32 v142, s20, v181
	v_add_u32_e32 v158, s21, v181
	ds_read_b128 v[130:133], v142
	ds_read_b128 v[134:137], v142 offset:1024
	ds_read_b128 v[138:141], v142 offset:2048
	ds_read_b128 v[142:145], v142 offset:3072
	ds_read_b128 v[146:149], v158
	ds_read_b128 v[150:153], v158 offset:1024
	ds_read_b128 v[154:157], v158 offset:2048
	ds_read_b128 v[158:161], v158 offset:3072
	s_add_u32 s14, s68, 0x80000
	s_addc_u32 s15, s69, 0
	s_mov_b32 m0, s45
	v_lshl_add_u64 v[236:237], s[14:15], 0, v[0:1]
	ds_read_b128 v[168:171], v183 offset:32768
	ds_read_b128 v[172:175], v183 offset:33792
	ds_read_b128 v[176:179], v183 offset:34816
	ds_read_b128 v[198:201], v183 offset:35840
	ds_read_b128 v[202:205], v183 offset:36864
	ds_read_b128 v[206:209], v183 offset:37888
	ds_read_b128 v[210:213], v183 offset:38912
	ds_read_b128 v[214:217], v183 offset:39936
	v_lshl_add_u64 v[218:219], s[68:69], 0, v[0:1]
	s_mov_b32 m0, s27
	v_lshl_add_u64 v[220:221], s[68:69], 0, v[162:163]
	global_load_lds_dwordx4 v[218:219], off
	s_mov_b32 m0, s44
	s_nop 0
	global_load_lds_dwordx4 v[220:221], off
	s_mov_b32 m0, s45
	s_nop 0
	global_load_lds_dwordx4 v[236:237], off
	v_lshl_add_u64 v[236:237], s[14:15], 0, v[162:163]
	s_mov_b32 m0, s70
	s_nop 0
	global_load_lds_dwordx4 v[236:237], off
	s_waitcnt vmcnt(8)
	s_waitcnt lgkmcnt(0)
	s_barrier
	s_setprio 1
	s_waitcnt lgkmcnt(0)
	v_mfma_f32_16x16x32_bf16 v[110:113], v[130:133], v[168:171], v[110:113]
	v_mfma_f32_16x16x32_bf16 v[106:109], v[138:141], v[168:171], v[106:109]
	v_mfma_f32_16x16x32_bf16 v[126:129], v[130:133], v[176:179], v[126:129]
	v_mfma_f32_16x16x32_bf16 v[122:125], v[138:141], v[176:179], v[122:125]
	v_mfma_f32_16x16x32_bf16 v[94:97], v[130:133], v[202:205], v[94:97]
	v_mfma_f32_16x16x32_bf16 v[90:93], v[138:141], v[202:205], v[90:93]
	v_mfma_f32_16x16x32_bf16 v[78:81], v[130:133], v[210:213], v[78:81]
	v_mfma_f32_16x16x32_bf16 v[74:77], v[138:141], v[210:213], v[74:77]
	v_mfma_f32_16x16x32_bf16 v[110:113], v[134:137], v[172:175], v[110:113]
	v_mfma_f32_16x16x32_bf16 v[106:109], v[142:145], v[172:175], v[106:109]
	v_mfma_f32_16x16x32_bf16 v[126:129], v[134:137], v[198:201], v[126:129]
	v_mfma_f32_16x16x32_bf16 v[122:125], v[142:145], v[198:201], v[122:125]
	v_mfma_f32_16x16x32_bf16 v[94:97], v[134:137], v[206:209], v[94:97]
	v_mfma_f32_16x16x32_bf16 v[90:93], v[142:145], v[206:209], v[90:93]
	v_mfma_f32_16x16x32_bf16 v[78:81], v[134:137], v[214:217], v[78:81]
	v_mfma_f32_16x16x32_bf16 v[74:77], v[142:145], v[214:217], v[74:77]
	s_setprio 0
	s_setprio 1
	v_mfma_f32_16x16x32_bf16 v[102:105], v[146:149], v[168:171], v[102:105]
	v_mfma_f32_16x16x32_bf16 v[98:101], v[154:157], v[168:171], v[98:101]
	v_mfma_f32_16x16x32_bf16 v[118:121], v[146:149], v[176:179], v[118:121]
	v_mfma_f32_16x16x32_bf16 v[114:117], v[154:157], v[176:179], v[114:117]
	v_mfma_f32_16x16x32_bf16 v[86:89], v[146:149], v[202:205], v[86:89]
	v_mfma_f32_16x16x32_bf16 v[82:85], v[154:157], v[202:205], v[82:85]
	v_mfma_f32_16x16x32_bf16 v[70:73], v[146:149], v[210:213], v[70:73]
	v_mfma_f32_16x16x32_bf16 v[66:69], v[154:157], v[210:213], v[66:69]
	v_mfma_f32_16x16x32_bf16 v[102:105], v[150:153], v[172:175], v[102:105]
	v_mfma_f32_16x16x32_bf16 v[98:101], v[158:161], v[172:175], v[98:101]
	v_mfma_f32_16x16x32_bf16 v[118:121], v[150:153], v[198:201], v[118:121]
	v_mfma_f32_16x16x32_bf16 v[114:117], v[158:161], v[198:201], v[114:117]
	v_mfma_f32_16x16x32_bf16 v[86:89], v[150:153], v[206:209], v[86:89]
	v_mfma_f32_16x16x32_bf16 v[82:85], v[158:161], v[206:209], v[82:85]
	v_mfma_f32_16x16x32_bf16 v[70:73], v[150:153], v[214:217], v[70:73]
	v_mfma_f32_16x16x32_bf16 v[66:69], v[158:161], v[214:217], v[66:69]
	s_setprio 0
	s_barrier
; #define PG8_STAGE(bufoff, gbase, voff) do { _Pragma("unroll") for (int _i = 0; _i < 2; ++_i) \
;         __builtin_amdgcn_global_load_lds((const unsigned*)((const char*)(gbase) + (voff)[_i]), (LAS unsigned*)(lds + (bufoff) + ldsw + _i * 8192), 16, 0, 0); } while (0)
; #define PG8_LDA(dst, b, h) do { _Pragma("unroll") for (int m = 0; m < 4; ++m) _Pragma("unroll") for (int k = 0; k < 2; ++k) dst[m][k] = *(const LAS bf16x8*)(lds + PG8_SA(b, h) + aoff + m * 2048 + k * 1024); } while (0)
; #define PG8_MMA(ai, bj, At, Bt) do { __builtin_amdgcn_s_setprio(1); _Pragma("unroll") for (int m = 0; m < 4; ++m) _Pragma("unroll") for (int n = 0; n < 2; ++n) _Pragma("unroll") for (int k = 0; k < 2; ++k) \
;         acc[ai][bj][m][n] = __builtin_amdgcn_mfma_f32_16x16x32_bf16(Bt[n][k], At[m][k], acc[ai][bj][m][n], 0, 0, 0); __builtin_amdgcn_s_setprio(0); } while (0)
; #define PG8_WAIT_V(n) asm volatile("s_waitcnt vmcnt(" #n ")" ::: "memory")
; #define PG8_WAIT_L(n) asm volatile("s_waitcnt lgkmcnt(" #n ")" ::: "memory")
; #define PG8_BAR __builtin_amdgcn_s_barrier()
; #define PG8_SCHED __builtin_amdgcn_sched_barrier(0)
; template <class Epi, class Sched, bool ALIGN_EPI = false, bool SP2 = false>
; __device__ __forceinline__ void gemm_phase(LAS unsigned char* lds, const Gemm g, const Sched& S, const Epi& E) {
;     ...
;             PG8_LDA(At, 1, 1); PG8_STAGE(PG8_SB(1, 0), b3, voffB); PG8_STAGE(PG8_SB(1, 1), b3 + hstep, voffB); PG8_STAGE(PG8_SA(1, 0), a3, voffA);
;             PG8_WAIT_V(8); PG8_WAIT_L(0); PG8_BAR; PG8_MMA(1, 0, At, B0); PG8_MMA(1, 1, At, B1); PG8_BAR; PG8_SCHED;
	s_add_i32 s14, s20, s4
	v_lshl_add_u64 v[184:185], v[184:185], 0, s[18:19]
	s_mov_b32 m0, s14
	ds_read_b128 v[168:171], v183 offset:49152
	ds_read_b128 v[172:175], v183 offset:50176
	ds_read_b128 v[176:179], v183 offset:51200
	ds_read_b128 v[198:201], v183 offset:52224
	ds_read_b128 v[202:205], v183 offset:53248
	ds_read_b128 v[206:209], v183 offset:54272
	ds_read_b128 v[210:213], v183 offset:55296
	ds_read_b128 v[214:217], v183 offset:56320
	global_load_lds_dwordx4 v[184:185], off
	s_add_i32 m0, s14, 0x2000
	s_add_u32 s14, s66, 0x80080
	v_lshl_add_u64 v[184:185], v[186:187], 0, s[18:19]
	s_addc_u32 s15, s67, 0
	s_add_i32 s20, s21, s4
	global_load_lds_dwordx4 v[184:185], off
	v_lshl_add_u64 v[184:185], s[14:15], 0, v[0:1]
	s_mov_b32 m0, s20
	s_nop 0
	global_load_lds_dwordx4 v[184:185], off
	v_lshl_add_u64 v[184:185], s[14:15], 0, v[162:163]
	s_add_i32 m0, s20, 0x2000
	s_nop 0
	global_load_lds_dwordx4 v[184:185], off
	v_lshl_add_u64 v[184:185], v[218:219], 0, s[18:19]
	s_mov_b32 m0, s71
	s_nop 0
	global_load_lds_dwordx4 v[184:185], off
	v_lshl_add_u64 v[184:185], v[220:221], 0, s[18:19]
	s_mov_b32 m0, s93
	s_nop 0
	global_load_lds_dwordx4 v[184:185], off
	s_waitcnt vmcnt(8)
	s_waitcnt lgkmcnt(0)
	s_barrier
	s_setprio 1
	s_waitcnt lgkmcnt(0)
	v_mfma_f32_16x16x32_bf16 v[62:65], v[130:133], v[168:171], v[62:65]
	v_mfma_f32_16x16x32_bf16 v[58:61], v[138:141], v[168:171], v[58:61]
	v_mfma_f32_16x16x32_bf16 v[54:57], v[130:133], v[176:179], v[54:57]
	v_mfma_f32_16x16x32_bf16 v[42:45], v[138:141], v[176:179], v[42:45]
	v_mfma_f32_16x16x32_bf16 v[38:41], v[130:133], v[202:205], v[38:41]
	v_mfma_f32_16x16x32_bf16 v[26:29], v[138:141], v[202:205], v[26:29]
	v_mfma_f32_16x16x32_bf16 v[18:21], v[130:133], v[210:213], v[18:21]
	v_mfma_f32_16x16x32_bf16 v[10:13], v[138:141], v[210:213], v[10:13]
	v_mfma_f32_16x16x32_bf16 v[62:65], v[134:137], v[172:175], v[62:65]
	v_mfma_f32_16x16x32_bf16 v[58:61], v[142:145], v[172:175], v[58:61]
	v_mfma_f32_16x16x32_bf16 v[54:57], v[134:137], v[198:201], v[54:57]
	v_mfma_f32_16x16x32_bf16 v[42:45], v[142:145], v[198:201], v[42:45]
	v_mfma_f32_16x16x32_bf16 v[38:41], v[134:137], v[206:209], v[38:41]
	v_mfma_f32_16x16x32_bf16 v[26:29], v[142:145], v[206:209], v[26:29]
	v_mfma_f32_16x16x32_bf16 v[18:21], v[134:137], v[214:217], v[18:21]
	v_mfma_f32_16x16x32_bf16 v[10:13], v[142:145], v[214:217], v[10:13]
	s_setprio 0
	s_setprio 1
	v_mfma_f32_16x16x32_bf16 v[50:53], v[146:149], v[168:171], v[50:53]
	v_mfma_f32_16x16x32_bf16 v[46:49], v[154:157], v[168:171], v[46:49]
	v_mfma_f32_16x16x32_bf16 v[34:37], v[146:149], v[176:179], v[34:37]
	v_mfma_f32_16x16x32_bf16 v[30:33], v[154:157], v[176:179], v[30:33]
	v_mfma_f32_16x16x32_bf16 v[22:25], v[146:149], v[202:205], v[22:25]
	v_mfma_f32_16x16x32_bf16 v[14:17], v[154:157], v[202:205], v[14:17]
	v_mfma_f32_16x16x32_bf16 v[6:9], v[146:149], v[210:213], v[6:9]
	v_mfma_f32_16x16x32_bf16 v[2:5], v[154:157], v[210:213], v[2:5]
	v_mfma_f32_16x16x32_bf16 v[50:53], v[150:153], v[172:175], v[50:53]
	v_mfma_f32_16x16x32_bf16 v[46:49], v[158:161], v[172:175], v[46:49]
	v_mfma_f32_16x16x32_bf16 v[34:37], v[150:153], v[198:201], v[34:37]
	v_mfma_f32_16x16x32_bf16 v[30:33], v[158:161], v[198:201], v[30:33]
	v_mfma_f32_16x16x32_bf16 v[22:25], v[150:153], v[206:209], v[22:25]
	v_mfma_f32_16x16x32_bf16 v[14:17], v[158:161], v[206:209], v[14:17]
	v_mfma_f32_16x16x32_bf16 v[6:9], v[150:153], v[214:217], v[6:9]
	v_mfma_f32_16x16x32_bf16 v[2:5], v[158:161], v[214:217], v[2:5]
	s_setprio 0
	s_barrier
	s_add_i32 s96, s96, 2
	s_add_u32 s73, s73, 0x100
	s_addc_u32 s95, s95, 0
	s_cmp_gt_u32 s96, 29
	s_mov_b64 s[46:47], s[58:59]
	s_cbranch_scc0 .LBB0_504
	s_and_b64 vcc, exec, s[8:9]
	s_cbranch_vccz .LBB0_507
	s_barrier

; #define PG8_STAGE(bufoff, gbase, voff) do { _Pragma("unroll") for (int _i = 0; _i < 2; ++_i) \
;         __builtin_amdgcn_global_load_lds((const unsigned*)((const char*)(gbase) + (voff)[_i]), (LAS unsigned*)(lds + (bufoff) + ldsw + _i * 8192), 16, 0, 0); } while (0)
; #define PG8_LDA(dst, b, h) do { _Pragma("unroll") for (int m = 0; m < 4; ++m) _Pragma("unroll") for (int k = 0; k < 2; ++k) dst[m][k] = *(const LAS bf16x8*)(lds + PG8_SA(b, h) + aoff + m * 2048 + k * 1024); } while (0)
; #define PG8_LDB(dst, b, h) do { _Pragma("unroll") for (int n = 0; n < 2; ++n) _Pragma("unroll") for (int k = 0; k < 2; ++k) dst[n][k] = *(const LAS bf16x8*)(lds + PG8_SB(b, h) + boff + n * 2048 + k * 1024); } while (0)
; #define PG8_MMA(ai, bj, At, Bt) do { __builtin_amdgcn_s_setprio(1); _Pragma("unroll") for (int m = 0; m < 4; ++m) _Pragma("unroll") for (int n = 0; n < 2; ++n) _Pragma("unroll") for (int k = 0; k < 2; ++k) \
;         acc[ai][bj][m][n] = __builtin_amdgcn_mfma_f32_16x16x32_bf16(Bt[n][k], At[m][k], acc[ai][bj][m][n], 0, 0, 0); __builtin_amdgcn_s_setprio(0); } while (0)
; #define PG8_WAIT_V(n) asm volatile("s_waitcnt vmcnt(" #n ")" ::: "memory")
; #define PG8_WAIT_L(n) asm volatile("s_waitcnt lgkmcnt(" #n ")" ::: "memory")
; #define PG8_BAR __builtin_amdgcn_s_barrier()
; #define PG8_SCHED __builtin_amdgcn_sched_barrier(0)
; template <class Epi, class Sched, bool ALIGN_EPI = false, bool SP2 = false>
; __device__ __forceinline__ void gemm_phase(LAS unsigned char* lds, const Gemm g, const Sched& S, const Epi& E) {
;     ...
;             const bool last = (t == nt - 2);
;             const char* a1 = cA + (size_t)(t + 1) * kstep;
;             const char* a2 = last ? nA : cA + (size_t)(t + 2) * kstep; const char* b2 = last ? nB : cB + (size_t)(t + 2) * kstep;
;             const char* a3 = a2 + kstep; const char* b3 = b2 + kstep;
;             if (last && has_next) S.a_ready(nxt);
;             if constexpr (SP2) {
;             PG8_LDB(B0, 0, 0); PG8_LDB(B1, 0, 1); PG8_SCHED; PG8_LDA(At, 0, 0); PG8_STAGE(PG8_SA(1, 1), a1 + hstep, voffA);
;             PG8_WAIT_V(8); PG8_WAIT_L(0); PG8_BAR; PG8_MMA(0, 0, At, B0); PG8_MMA(0, 1, At, B1); PG8_BAR; PG8_SCHED;
;             PG8_LDA(At, 0, 1); PG8_STAGE(PG8_SB(0, 0), b2, voffB); PG8_STAGE(PG8_SB(0, 1), b2 + hstep, voffB); PG8_STAGE(PG8_SA(0, 0), a2, voffA);
.LBB0_631:
	s_add_u32 s14, s42, 0xfff80080
	s_addc_u32 s15, s43, -1
	s_add_i32 s20, 0, 0x10000
	s_cmp_eq_u32 s73, 28
	s_cselect_b32 s59, s31, s15
	s_cselect_b32 s58, s69, s14
	s_cselect_b32 s47, s9, s72
	s_cselect_b32 s46, s70, s71
	s_add_i32 s21, 0, 0x14000
	v_add_u32_e32 v156, s20, v141
	v_add_u32_e32 v172, s21, v141
	ds_read_b128 v[144:147], v156
	ds_read_b128 v[148:151], v156 offset:1024
	ds_read_b128 v[152:155], v156 offset:2048
	ds_read_b128 v[156:159], v156 offset:3072
	ds_read_b128 v[160:163], v172
	ds_read_b128 v[164:167], v172 offset:1024
	ds_read_b128 v[168:171], v172 offset:2048
	ds_read_b128 v[172:175], v172 offset:3072
	v_lshl_add_u64 v[184:185], s[42:43], 0, v[136:137]
	s_add_i32 m0, s13, 0xc000
	ds_read_b128 v[176:179], v143
	ds_read_b128 v[180:183], v143 offset:1024
	ds_read_b128 v[198:201], v143 offset:2048
	ds_read_b128 v[202:205], v143 offset:3072
	ds_read_b128 v[206:209], v143 offset:4096
	ds_read_b128 v[210:213], v143 offset:5120
	ds_read_b128 v[214:217], v143 offset:6144
	ds_read_b128 v[218:221], v143 offset:7168
	global_load_lds_dwordx4 v[184:185], off
	v_lshl_add_u64 v[184:185], s[42:43], 0, v[138:139]
	s_add_i32 m0, s13, 0xe000
	s_nop 0
	global_load_lds_dwordx4 v[184:185], off
	s_waitcnt vmcnt(8)
	s_waitcnt lgkmcnt(0)
	s_barrier
	s_setprio 1
	s_waitcnt lgkmcnt(0)
	v_mfma_f32_16x16x32_bf16 v[126:129], v[144:147], v[176:179], v[126:129]
	v_mfma_f32_16x16x32_bf16 v[122:125], v[152:155], v[176:179], v[122:125]
	v_mfma_f32_16x16x32_bf16 v[118:121], v[144:147], v[198:201], v[118:121]
	v_mfma_f32_16x16x32_bf16 v[114:117], v[152:155], v[198:201], v[114:117]
	v_mfma_f32_16x16x32_bf16 v[102:105], v[144:147], v[206:209], v[102:105]
	v_mfma_f32_16x16x32_bf16 v[98:101], v[152:155], v[206:209], v[98:101]
	v_mfma_f32_16x16x32_bf16 v[86:89], v[144:147], v[214:217], v[86:89]
	v_mfma_f32_16x16x32_bf16 v[82:85], v[152:155], v[214:217], v[82:85]
	v_mfma_f32_16x16x32_bf16 v[126:129], v[148:151], v[180:183], v[126:129]
	v_mfma_f32_16x16x32_bf16 v[122:125], v[156:159], v[180:183], v[122:125]
	v_mfma_f32_16x16x32_bf16 v[118:121], v[148:151], v[202:205], v[118:121]
	v_mfma_f32_16x16x32_bf16 v[114:117], v[156:159], v[202:205], v[114:117]
	v_mfma_f32_16x16x32_bf16 v[102:105], v[148:151], v[210:213], v[102:105]
	v_mfma_f32_16x16x32_bf16 v[98:101], v[156:159], v[210:213], v[98:101]
	v_mfma_f32_16x16x32_bf16 v[86:89], v[148:151], v[218:221], v[86:89]
	v_mfma_f32_16x16x32_bf16 v[82:85], v[156:159], v[218:221], v[82:85]
	s_setprio 0
	s_setprio 1
	v_mfma_f32_16x16x32_bf16 v[110:113], v[160:163], v[176:179], v[110:113]
	v_mfma_f32_16x16x32_bf16 v[106:109], v[168:171], v[176:179], v[106:109]
	v_mfma_f32_16x16x32_bf16 v[94:97], v[160:163], v[198:201], v[94:97]
	v_mfma_f32_16x16x32_bf16 v[90:93], v[168:171], v[198:201], v[90:93]
	v_mfma_f32_16x16x32_bf16 v[78:81], v[160:163], v[206:209], v[78:81]
	v_mfma_f32_16x16x32_bf16 v[74:77], v[168:171], v[206:209], v[74:77]
	v_mfma_f32_16x16x32_bf16 v[70:73], v[160:163], v[214:217], v[70:73]
	v_mfma_f32_16x16x32_bf16 v[66:69], v[168:171], v[214:217], v[66:69]
	v_mfma_f32_16x16x32_bf16 v[110:113], v[164:167], v[180:183], v[110:113]
	v_mfma_f32_16x16x32_bf16 v[106:109], v[172:175], v[180:183], v[106:109]
	v_mfma_f32_16x16x32_bf16 v[94:97], v[164:167], v[202:205], v[94:97]
	v_mfma_f32_16x16x32_bf16 v[90:93], v[172:175], v[202:205], v[90:93]
	v_mfma_f32_16x16x32_bf16 v[78:81], v[164:167], v[210:213], v[78:81]
	v_mfma_f32_16x16x32_bf16 v[74:77], v[172:175], v[210:213], v[74:77]
	v_mfma_f32_16x16x32_bf16 v[70:73], v[164:167], v[218:221], v[70:73]
	v_mfma_f32_16x16x32_bf16 v[66:69], v[172:175], v[218:221], v[66:69]
	s_setprio 0
	s_barrier
	s_add_i32 s14, s20, s4
	v_lshl_add_u64 v[184:185], s[46:47], 0, v[0:1]
	s_mov_b32 m0, s14
	ds_read_b128 v[176:179], v143 offset:16384
	ds_read_b128 v[180:183], v143 offset:17408
	ds_read_b128 v[198:201], v143 offset:18432
	ds_read_b128 v[202:205], v143 offset:19456
	ds_read_b128 v[206:209], v143 offset:20480
	ds_read_b128 v[210:213], v143 offset:21504
	ds_read_b128 v[214:217], v143 offset:22528
	ds_read_b128 v[218:221], v143 offset:23552
	global_load_lds_dwordx4 v[184:185], off
	s_add_i32 m0, s14, 0x2000
	s_add_u32 s14, s46, 0x80000
	v_lshl_add_u64 v[186:187], s[46:47], 0, v[130:131]
	s_addc_u32 s15, s47, 0
	s_add_i32 s20, s21, s4
	global_load_lds_dwordx4 v[186:187], off
	v_lshl_add_u64 v[236:237], s[14:15], 0, v[0:1]
	s_mov_b32 m0, s20
	global_load_lds_dwordx4 v[236:237], off
	v_lshl_add_u64 v[236:237], s[14:15], 0, v[130:131]
	s_add_i32 m0, s20, 0x2000
	s_nop 0
	global_load_lds_dwordx4 v[236:237], off
	s_waitcnt vmcnt(6)
	s_waitcnt lgkmcnt(0)
	s_barrier
; #define PG8_STAGE(bufoff, gbase, voff) do { _Pragma("unroll") for (int _i = 0; _i < 2; ++_i) \
;         __builtin_amdgcn_global_load_lds((const unsigned*)((const char*)(gbase) + (voff)[_i]), (LAS unsigned*)(lds + (bufoff) + ldsw + _i * 8192), 16, 0, 0); } while (0)
; #define PG8_LDA(dst, b, h) do { _Pragma("unroll") for (int m = 0; m < 4; ++m) _Pragma("unroll") for (int k = 0; k < 2; ++k) dst[m][k] = *(const LAS bf16x8*)(lds + PG8_SA(b, h) + aoff + m * 2048 + k * 1024); } while (0)
; #define PG8_LDB(dst, b, h) do { _Pragma("unroll") for (int n = 0; n < 2; ++n) _Pragma("unroll") for (int k = 0; k < 2; ++k) dst[n][k] = *(const LAS bf16x8*)(lds + PG8_SB(b, h) + boff + n * 2048 + k * 1024); } while (0)
; #define PG8_MMA(ai, bj, At, Bt) do { __builtin_amdgcn_s_setprio(1); _Pragma("unroll") for (int m = 0; m < 4; ++m) _Pragma("unroll") for (int n = 0; n < 2; ++n) _Pragma("unroll") for (int k = 0; k < 2; ++k) \
;         acc[ai][bj][m][n] = __builtin_amdgcn_mfma_f32_16x16x32_bf16(Bt[n][k], At[m][k], acc[ai][bj][m][n], 0, 0, 0); __builtin_amdgcn_s_setprio(0); } while (0)
; #define PG8_WAIT_V(n) asm volatile("s_waitcnt vmcnt(" #n ")" ::: "memory")
; #define PG8_WAIT_L(n) asm volatile("s_waitcnt lgkmcnt(" #n ")" ::: "memory")
; #define PG8_BAR __builtin_amdgcn_s_barrier()
; #define PG8_SCHED __builtin_amdgcn_sched_barrier(0)
; template <class Epi, class Sched, bool ALIGN_EPI = false, bool SP2 = false>
; __device__ __forceinline__ void gemm_phase(LAS unsigned char* lds, const Gemm g, const Sched& S, const Epi& E) {
;     ...
;             PG8_WAIT_V(8); PG8_WAIT_L(0); PG8_BAR; PG8_MMA(1, 0, At, B0); PG8_MMA(1, 1, At, B1); PG8_BAR; PG8_SCHED;
;             PG8_LDB(B0, 1, 0); PG8_LDB(B1, 1, 1); PG8_SCHED; PG8_LDA(At, 1, 0); PG8_STAGE(PG8_SA(0, 1), a2 + hstep, voffA);
	s_setprio 1
	s_waitcnt lgkmcnt(0)
	v_mfma_f32_16x16x32_bf16 v[62:65], v[144:147], v[176:179], v[62:65]
	v_mfma_f32_16x16x32_bf16 v[58:61], v[152:155], v[176:179], v[58:61]
	v_mfma_f32_16x16x32_bf16 v[54:57], v[144:147], v[198:201], v[54:57]
	v_mfma_f32_16x16x32_bf16 v[50:53], v[152:155], v[198:201], v[50:53]
	v_mfma_f32_16x16x32_bf16 v[38:41], v[144:147], v[206:209], v[38:41]
	v_mfma_f32_16x16x32_bf16 v[34:37], v[152:155], v[206:209], v[34:37]
	v_mfma_f32_16x16x32_bf16 v[22:25], v[144:147], v[214:217], v[22:25]
	v_mfma_f32_16x16x32_bf16 v[18:21], v[152:155], v[214:217], v[18:21]
	v_mfma_f32_16x16x32_bf16 v[62:65], v[148:151], v[180:183], v[62:65]
	v_mfma_f32_16x16x32_bf16 v[58:61], v[156:159], v[180:183], v[58:61]
	v_mfma_f32_16x16x32_bf16 v[54:57], v[148:151], v[202:205], v[54:57]
	v_mfma_f32_16x16x32_bf16 v[50:53], v[156:159], v[202:205], v[50:53]
	v_mfma_f32_16x16x32_bf16 v[38:41], v[148:151], v[210:213], v[38:41]
	v_mfma_f32_16x16x32_bf16 v[34:37], v[156:159], v[210:213], v[34:37]
	v_mfma_f32_16x16x32_bf16 v[22:25], v[148:151], v[218:221], v[22:25]
	v_mfma_f32_16x16x32_bf16 v[18:21], v[156:159], v[218:221], v[18:21]
	s_setprio 0
	s_setprio 1
	v_mfma_f32_16x16x32_bf16 v[46:49], v[160:163], v[176:179], v[46:49]
	v_mfma_f32_16x16x32_bf16 v[42:45], v[168:171], v[176:179], v[42:45]
	v_mfma_f32_16x16x32_bf16 v[30:33], v[160:163], v[198:201], v[30:33]
	v_mfma_f32_16x16x32_bf16 v[26:29], v[168:171], v[198:201], v[26:29]
	v_mfma_f32_16x16x32_bf16 v[14:17], v[160:163], v[206:209], v[14:17]
	v_mfma_f32_16x16x32_bf16 v[10:13], v[168:171], v[206:209], v[10:13]
	v_mfma_f32_16x16x32_bf16 v[6:9], v[160:163], v[214:217], v[6:9]
	v_mfma_f32_16x16x32_bf16 v[2:5], v[168:171], v[214:217], v[2:5]
	v_mfma_f32_16x16x32_bf16 v[46:49], v[164:167], v[180:183], v[46:49]
	v_mfma_f32_16x16x32_bf16 v[42:45], v[172:175], v[180:183], v[42:45]
	v_mfma_f32_16x16x32_bf16 v[30:33], v[164:167], v[202:205], v[30:33]
	v_mfma_f32_16x16x32_bf16 v[26:29], v[172:175], v[202:205], v[26:29]
	v_mfma_f32_16x16x32_bf16 v[14:17], v[164:167], v[210:213], v[14:17]
	v_mfma_f32_16x16x32_bf16 v[10:13], v[172:175], v[210:213], v[10:13]
	v_mfma_f32_16x16x32_bf16 v[6:9], v[164:167], v[218:221], v[6:9]
	v_mfma_f32_16x16x32_bf16 v[2:5], v[172:175], v[218:221], v[2:5]
	s_setprio 0
	s_barrier
	s_add_i32 s20, 0, 0x18000
	s_add_i32 s21, 0, 0x1c000
	v_add_u32_e32 v156, s20, v141
	v_add_u32_e32 v172, s21, v141
	ds_read_b128 v[144:147], v156
	ds_read_b128 v[148:151], v156 offset:1024
	ds_read_b128 v[152:155], v156 offset:2048
	ds_read_b128 v[156:159], v156 offset:3072
	ds_read_b128 v[160:163], v172
	ds_read_b128 v[164:167], v172 offset:1024
	ds_read_b128 v[168:171], v172 offset:2048
	ds_read_b128 v[172:175], v172 offset:3072
	s_add_u32 s14, s58, 0x80000
	s_addc_u32 s15, s59, 0
	s_mov_b32 m0, s33
	v_lshl_add_u64 v[240:241], s[14:15], 0, v[134:135]
	ds_read_b128 v[176:179], v143 offset:32768
	ds_read_b128 v[180:183], v143 offset:33792
	ds_read_b128 v[198:201], v143 offset:34816
	ds_read_b128 v[202:205], v143 offset:35840
	ds_read_b128 v[206:209], v143 offset:36864
	ds_read_b128 v[210:213], v143 offset:37888
	ds_read_b128 v[214:217], v143 offset:38912
	ds_read_b128 v[218:221], v143 offset:39936
	v_lshl_add_u64 v[236:237], s[58:59], 0, v[134:135]
	s_mov_b32 m0, s13
	v_lshl_add_u64 v[238:239], s[58:59], 0, v[132:133]
	global_load_lds_dwordx4 v[236:237], off
	s_mov_b32 m0, s27
	s_nop 0
	global_load_lds_dwordx4 v[238:239], off
	s_mov_b32 m0, s33
	s_nop 0
	global_load_lds_dwordx4 v[240:241], off
	v_lshl_add_u64 v[240:241], s[14:15], 0, v[132:133]
	s_mov_b32 m0, s44
	s_nop 0
	global_load_lds_dwordx4 v[240:241], off
	s_waitcnt vmcnt(8)
	s_waitcnt lgkmcnt(0)
	s_barrier
	s_setprio 1
	s_waitcnt lgkmcnt(0)
	v_mfma_f32_16x16x32_bf16 v[126:129], v[144:147], v[176:179], v[126:129]
	v_mfma_f32_16x16x32_bf16 v[122:125], v[152:155], v[176:179], v[122:125]
	v_mfma_f32_16x16x32_bf16 v[118:121], v[144:147], v[198:201], v[118:121]
	v_mfma_f32_16x16x32_bf16 v[114:117], v[152:155], v[198:201], v[114:117]
	v_mfma_f32_16x16x32_bf16 v[102:105], v[144:147], v[206:209], v[102:105]
	v_mfma_f32_16x16x32_bf16 v[98:101], v[152:155], v[206:209], v[98:101]
	v_mfma_f32_16x16x32_bf16 v[86:89], v[144:147], v[214:217], v[86:89]
	v_mfma_f32_16x16x32_bf16 v[82:85], v[152:155], v[214:217], v[82:85]
	v_mfma_f32_16x16x32_bf16 v[126:129], v[148:151], v[180:183], v[126:129]
	v_mfma_f32_16x16x32_bf16 v[122:125], v[156:159], v[180:183], v[122:125]
	v_mfma_f32_16x16x32_bf16 v[118:121], v[148:151], v[202:205], v[118:121]
	v_mfma_f32_16x16x32_bf16 v[114:117], v[156:159], v[202:205], v[114:117]
	v_mfma_f32_16x16x32_bf16 v[102:105], v[148:151], v[210:213], v[102:105]
	v_mfma_f32_16x16x32_bf16 v[98:101], v[156:159], v[210:213], v[98:101]
	v_mfma_f32_16x16x32_bf16 v[86:89], v[148:151], v[218:221], v[86:89]
	v_mfma_f32_16x16x32_bf16 v[82:85], v[156:159], v[218:221], v[82:85]
	s_setprio 0
	s_setprio 1
	v_mfma_f32_16x16x32_bf16 v[110:113], v[160:163], v[176:179], v[110:113]
	v_mfma_f32_16x16x32_bf16 v[106:109], v[168:171], v[176:179], v[106:109]
	v_mfma_f32_16x16x32_bf16 v[94:97], v[160:163], v[198:201], v[94:97]
	v_mfma_f32_16x16x32_bf16 v[90:93], v[168:171], v[198:201], v[90:93]
	v_mfma_f32_16x16x32_bf16 v[78:81], v[160:163], v[206:209], v[78:81]
	v_mfma_f32_16x16x32_bf16 v[74:77], v[168:171], v[206:209], v[74:77]
	v_mfma_f32_16x16x32_bf16 v[70:73], v[160:163], v[214:217], v[70:73]
	v_mfma_f32_16x16x32_bf16 v[66:69], v[168:171], v[214:217], v[66:69]
	v_mfma_f32_16x16x32_bf16 v[110:113], v[164:167], v[180:183], v[110:113]
	v_mfma_f32_16x16x32_bf16 v[106:109], v[172:175], v[180:183], v[106:109]
	v_mfma_f32_16x16x32_bf16 v[94:97], v[164:167], v[202:205], v[94:97]
	v_mfma_f32_16x16x32_bf16 v[90:93], v[172:175], v[202:205], v[90:93]
	v_mfma_f32_16x16x32_bf16 v[78:81], v[164:167], v[210:213], v[78:81]
	v_mfma_f32_16x16x32_bf16 v[74:77], v[172:175], v[210:213], v[74:77]
	v_mfma_f32_16x16x32_bf16 v[70:73], v[164:167], v[218:221], v[70:73]
	v_mfma_f32_16x16x32_bf16 v[66:69], v[172:175], v[218:221], v[66:69]
	s_setprio 0
	s_barrier
; #define PG8_STAGE(bufoff, gbase, voff) do { _Pragma("unroll") for (int _i = 0; _i < 2; ++_i) \
;         __builtin_amdgcn_global_load_lds((const unsigned*)((const char*)(gbase) + (voff)[_i]), (LAS unsigned*)(lds + (bufoff) + ldsw + _i * 8192), 16, 0, 0); } while (0)
; #define PG8_LDA(dst, b, h) do { _Pragma("unroll") for (int m = 0; m < 4; ++m) _Pragma("unroll") for (int k = 0; k < 2; ++k) dst[m][k] = *(const LAS bf16x8*)(lds + PG8_SA(b, h) + aoff + m * 2048 + k * 1024); } while (0)
; #define PG8_MMA(ai, bj, At, Bt) do { __builtin_amdgcn_s_setprio(1); _Pragma("unroll") for (int m = 0; m < 4; ++m) _Pragma("unroll") for (int n = 0; n < 2; ++n) _Pragma("unroll") for (int k = 0; k < 2; ++k) \
;         acc[ai][bj][m][n] = __builtin_amdgcn_mfma_f32_16x16x32_bf16(Bt[n][k], At[m][k], acc[ai][bj][m][n], 0, 0, 0); __builtin_amdgcn_s_setprio(0); } while (0)
; #define PG8_WAIT_V(n) asm volatile("s_waitcnt vmcnt(" #n ")" ::: "memory")
; #define PG8_WAIT_L(n) asm volatile("s_waitcnt lgkmcnt(" #n ")" ::: "memory")
; #define PG8_BAR __builtin_amdgcn_s_barrier()
; #define PG8_SCHED __builtin_amdgcn_sched_barrier(0)
; template <class Epi, class Sched, bool ALIGN_EPI = false, bool SP2 = false>
; __device__ __forceinline__ void gemm_phase(LAS unsigned char* lds, const Gemm g, const Sched& S, const Epi& E) {
;     ...
;             PG8_LDA(At, 1, 1); PG8_STAGE(PG8_SB(1, 0), b3, voffB); PG8_STAGE(PG8_SB(1, 1), b3 + hstep, voffB); PG8_STAGE(PG8_SA(1, 0), a3, voffA);
;             PG8_WAIT_V(8); PG8_WAIT_L(0); PG8_BAR; PG8_MMA(1, 0, At, B0); PG8_MMA(1, 1, At, B1); PG8_BAR; PG8_SCHED;
;     ...
;         if constexpr (ALIGN_EPI) { if (wr == 0) PG8_BAR; }
	s_add_i32 s14, s20, s4
	v_lshl_add_u64 v[184:185], v[184:185], 0, s[18:19]
	s_mov_b32 m0, s14
	ds_read_b128 v[176:179], v143 offset:49152
	ds_read_b128 v[180:183], v143 offset:50176
	ds_read_b128 v[198:201], v143 offset:51200
	ds_read_b128 v[202:205], v143 offset:52224
	ds_read_b128 v[206:209], v143 offset:53248
	ds_read_b128 v[210:213], v143 offset:54272
	ds_read_b128 v[214:217], v143 offset:55296
	ds_read_b128 v[218:221], v143 offset:56320
	global_load_lds_dwordx4 v[184:185], off
	s_add_i32 m0, s14, 0x2000
	s_add_u32 s14, s46, 0x80080
	v_lshl_add_u64 v[184:185], v[186:187], 0, s[18:19]
	s_addc_u32 s15, s47, 0
	s_add_i32 s20, s21, s4
	global_load_lds_dwordx4 v[184:185], off
	v_lshl_add_u64 v[184:185], s[14:15], 0, v[0:1]
	s_mov_b32 m0, s20
	s_nop 0
	global_load_lds_dwordx4 v[184:185], off
	v_lshl_add_u64 v[184:185], s[14:15], 0, v[130:131]
	s_add_i32 m0, s20, 0x2000
	s_nop 0
	global_load_lds_dwordx4 v[184:185], off
	v_lshl_add_u64 v[184:185], v[236:237], 0, s[18:19]
	s_mov_b32 m0, s45
	s_nop 0
	global_load_lds_dwordx4 v[184:185], off
	v_lshl_add_u64 v[184:185], v[238:239], 0, s[18:19]
	s_mov_b32 m0, s66
	s_nop 0
	global_load_lds_dwordx4 v[184:185], off
	s_waitcnt vmcnt(8)
	s_waitcnt lgkmcnt(0)
	s_barrier
	s_setprio 1
	s_waitcnt lgkmcnt(0)
	v_mfma_f32_16x16x32_bf16 v[62:65], v[144:147], v[176:179], v[62:65]
	v_mfma_f32_16x16x32_bf16 v[58:61], v[152:155], v[176:179], v[58:61]
	v_mfma_f32_16x16x32_bf16 v[54:57], v[144:147], v[198:201], v[54:57]
	v_mfma_f32_16x16x32_bf16 v[50:53], v[152:155], v[198:201], v[50:53]
	v_mfma_f32_16x16x32_bf16 v[38:41], v[144:147], v[206:209], v[38:41]
	v_mfma_f32_16x16x32_bf16 v[34:37], v[152:155], v[206:209], v[34:37]
	v_mfma_f32_16x16x32_bf16 v[22:25], v[144:147], v[214:217], v[22:25]
	v_mfma_f32_16x16x32_bf16 v[18:21], v[152:155], v[214:217], v[18:21]
	v_mfma_f32_16x16x32_bf16 v[62:65], v[148:151], v[180:183], v[62:65]
	v_mfma_f32_16x16x32_bf16 v[58:61], v[156:159], v[180:183], v[58:61]
	v_mfma_f32_16x16x32_bf16 v[54:57], v[148:151], v[202:205], v[54:57]
	v_mfma_f32_16x16x32_bf16 v[50:53], v[156:159], v[202:205], v[50:53]
	v_mfma_f32_16x16x32_bf16 v[38:41], v[148:151], v[210:213], v[38:41]
	v_mfma_f32_16x16x32_bf16 v[34:37], v[156:159], v[210:213], v[34:37]
	v_mfma_f32_16x16x32_bf16 v[22:25], v[148:151], v[218:221], v[22:25]
	v_mfma_f32_16x16x32_bf16 v[18:21], v[156:159], v[218:221], v[18:21]
	s_setprio 0
	s_setprio 1
	v_mfma_f32_16x16x32_bf16 v[46:49], v[160:163], v[176:179], v[46:49]
	v_mfma_f32_16x16x32_bf16 v[42:45], v[168:171], v[176:179], v[42:45]
	v_mfma_f32_16x16x32_bf16 v[30:33], v[160:163], v[198:201], v[30:33]
	v_mfma_f32_16x16x32_bf16 v[26:29], v[168:171], v[198:201], v[26:29]
	v_mfma_f32_16x16x32_bf16 v[14:17], v[160:163], v[206:209], v[14:17]
	v_mfma_f32_16x16x32_bf16 v[10:13], v[168:171], v[206:209], v[10:13]
	v_mfma_f32_16x16x32_bf16 v[6:9], v[160:163], v[214:217], v[6:9]
	v_mfma_f32_16x16x32_bf16 v[2:5], v[168:171], v[214:217], v[2:5]
	v_mfma_f32_16x16x32_bf16 v[46:49], v[164:167], v[180:183], v[46:49]
	v_mfma_f32_16x16x32_bf16 v[42:45], v[172:175], v[180:183], v[42:45]
	v_mfma_f32_16x16x32_bf16 v[30:33], v[164:167], v[202:205], v[30:33]
	v_mfma_f32_16x16x32_bf16 v[26:29], v[172:175], v[202:205], v[26:29]
	v_mfma_f32_16x16x32_bf16 v[14:17], v[164:167], v[210:213], v[14:17]
	v_mfma_f32_16x16x32_bf16 v[10:13], v[172:175], v[210:213], v[10:13]
	v_mfma_f32_16x16x32_bf16 v[6:9], v[164:167], v[218:221], v[6:9]
	v_mfma_f32_16x16x32_bf16 v[2:5], v[172:175], v[218:221], v[2:5]
	s_setprio 0
	s_barrier
	s_add_i32 s73, s73, 2
	s_add_u32 s42, s42, 0x100
	s_addc_u32 s43, s43, 0
	s_add_u32 s71, s71, 0x100
	s_addc_u32 s72, s72, 0
	s_cmp_gt_u32 s73, 29
	s_cbranch_scc0 .LBB0_631
	s_and_b64 vcc, exec, s[6:7]
	s_cbranch_vccz .LBB0_634
	s_barrier

; #define PG8_STAGE(bufoff, gbase, voff) do { _Pragma("unroll") for (int _i = 0; _i < 2; ++_i) \
;         __builtin_amdgcn_global_load_lds((const unsigned*)((const char*)(gbase) + (voff)[_i]), (LAS unsigned*)(lds + (bufoff) + ldsw + _i * 8192), 16, 0, 0); } while (0)
; #define PG8_LDA(dst, b, h) do { _Pragma("unroll") for (int m = 0; m < 4; ++m) _Pragma("unroll") for (int k = 0; k < 2; ++k) dst[m][k] = *(const LAS bf16x8*)(lds + PG8_SA(b, h) + aoff + m * 2048 + k * 1024); } while (0)
; #define PG8_LDB(dst, b, h) do { _Pragma("unroll") for (int n = 0; n < 2; ++n) _Pragma("unroll") for (int k = 0; k < 2; ++k) dst[n][k] = *(const LAS bf16x8*)(lds + PG8_SB(b, h) + boff + n * 2048 + k * 1024); } while (0)
; #define PG8_MMA(ai, bj, At, Bt) do { __builtin_amdgcn_s_setprio(1); _Pragma("unroll") for (int m = 0; m < 4; ++m) _Pragma("unroll") for (int n = 0; n < 2; ++n) _Pragma("unroll") for (int k = 0; k < 2; ++k) \
;         acc[ai][bj][m][n] = __builtin_amdgcn_mfma_f32_16x16x32_bf16(Bt[n][k], At[m][k], acc[ai][bj][m][n], 0, 0, 0); __builtin_amdgcn_s_setprio(0); } while (0)
; #define PG8_WAIT_V(n) asm volatile("s_waitcnt vmcnt(" #n ")" ::: "memory")
; #define PG8_WAIT_L(n) asm volatile("s_waitcnt lgkmcnt(" #n ")" ::: "memory")
; #define PG8_BAR __builtin_amdgcn_s_barrier()
; #define PG8_SCHED __builtin_amdgcn_sched_barrier(0)
; template <class Epi, class Sched, bool ALIGN_EPI = false, bool SP2 = false>
; __device__ __forceinline__ void gemm_phase(LAS unsigned char* lds, const Gemm g, const Sched& S, const Epi& E) {
;     ...
;             const bool last = (t == nt - 2);
;             const char* a1 = cA + (size_t)(t + 1) * kstep;
;             const char* a2 = last ? nA : cA + (size_t)(t + 2) * kstep; const char* b2 = last ? nB : cB + (size_t)(t + 2) * kstep;
;             const char* a3 = a2 + kstep; const char* b3 = b2 + kstep;
;             if (last && has_next) S.a_ready(nxt);
;             if constexpr (SP2) {
;             PG8_LDB(B0, 0, 0); PG8_LDB(B1, 0, 1); PG8_SCHED; PG8_LDA(At, 0, 0); PG8_STAGE(PG8_SA(1, 1), a1 + hstep, voffA);
;             PG8_WAIT_V(8); PG8_WAIT_L(0); PG8_BAR; PG8_MMA(0, 0, At, B0); PG8_MMA(0, 1, At, B1); PG8_BAR; PG8_SCHED;
;             PG8_LDA(At, 0, 1); PG8_STAGE(PG8_SB(0, 0), b2, voffB); PG8_STAGE(PG8_SB(0, 1), b2 + hstep, voffB); PG8_STAGE(PG8_SA(0, 0), a2, voffA);
.LBB0_768:
	s_add_u32 s38, s34, 0x100
	s_addc_u32 s39, s35, 0
	s_add_i32 s14, 0, 0x10000
	s_cmpk_eq_i32 s69, 0x54
	s_cselect_b32 s43, s1, s39
	s_cselect_b32 s42, s0, s38
	s_cselect_b32 s41, s31, s68
	s_cselect_b32 s40, s30, s67
	s_add_i32 s20, 0, 0x14000
	v_add_u32_e32 v142, s14, v183
	v_add_u32_e32 v158, s20, v183
	ds_read_b128 v[130:133], v142
	ds_read_b128 v[134:137], v142 offset:1024
	ds_read_b128 v[138:141], v142 offset:2048
	ds_read_b128 v[142:145], v142 offset:3072
	ds_read_b128 v[146:149], v158
	ds_read_b128 v[150:153], v158 offset:1024
	ds_read_b128 v[154:157], v158 offset:2048
	ds_read_b128 v[158:161], v158 offset:3072
	v_lshl_add_u64 v[180:181], s[34:35], 0, v[164:165]
	s_add_i32 m0, s27, 0xc000
	ds_read_b128 v[168:171], v185
	ds_read_b128 v[172:175], v185 offset:1024
	ds_read_b128 v[176:179], v185 offset:2048
	ds_read_b128 v[198:201], v185 offset:3072
	ds_read_b128 v[202:205], v185 offset:4096
	ds_read_b128 v[206:209], v185 offset:5120
	ds_read_b128 v[210:213], v185 offset:6144
	ds_read_b128 v[214:217], v185 offset:7168
	global_load_lds_dwordx4 v[180:181], off
	v_lshl_add_u64 v[180:181], s[34:35], 0, v[166:167]
	s_add_i32 m0, s27, 0xe000
	s_nop 0
	global_load_lds_dwordx4 v[180:181], off
	s_waitcnt vmcnt(8)
	s_waitcnt lgkmcnt(0)
	s_barrier
	s_setprio 1
	s_waitcnt lgkmcnt(0)
	v_mfma_f32_16x16x32_bf16 v[114:117], v[130:133], v[168:171], v[114:117]
	v_mfma_f32_16x16x32_bf16 v[106:109], v[138:141], v[168:171], v[106:109]
	v_mfma_f32_16x16x32_bf16 v[126:129], v[130:133], v[176:179], v[126:129]
	v_mfma_f32_16x16x32_bf16 v[122:125], v[138:141], v[176:179], v[122:125]
	v_mfma_f32_16x16x32_bf16 v[94:97], v[130:133], v[202:205], v[94:97]
	v_mfma_f32_16x16x32_bf16 v[90:93], v[138:141], v[202:205], v[90:93]
	v_mfma_f32_16x16x32_bf16 v[78:81], v[130:133], v[210:213], v[78:81]
	v_mfma_f32_16x16x32_bf16 v[74:77], v[138:141], v[210:213], v[74:77]
	v_mfma_f32_16x16x32_bf16 v[114:117], v[134:137], v[172:175], v[114:117]
	v_mfma_f32_16x16x32_bf16 v[106:109], v[142:145], v[172:175], v[106:109]
	v_mfma_f32_16x16x32_bf16 v[126:129], v[134:137], v[198:201], v[126:129]
	v_mfma_f32_16x16x32_bf16 v[122:125], v[142:145], v[198:201], v[122:125]
	v_mfma_f32_16x16x32_bf16 v[94:97], v[134:137], v[206:209], v[94:97]
	v_mfma_f32_16x16x32_bf16 v[90:93], v[142:145], v[206:209], v[90:93]
	v_mfma_f32_16x16x32_bf16 v[78:81], v[134:137], v[214:217], v[78:81]
	v_mfma_f32_16x16x32_bf16 v[74:77], v[142:145], v[214:217], v[74:77]
	s_setprio 0
	s_setprio 1
	v_mfma_f32_16x16x32_bf16 v[102:105], v[146:149], v[168:171], v[102:105]
	v_mfma_f32_16x16x32_bf16 v[98:101], v[154:157], v[168:171], v[98:101]
	v_mfma_f32_16x16x32_bf16 v[118:121], v[146:149], v[176:179], v[118:121]
	v_mfma_f32_16x16x32_bf16 v[110:113], v[154:157], v[176:179], v[110:113]
	v_mfma_f32_16x16x32_bf16 v[86:89], v[146:149], v[202:205], v[86:89]
	v_mfma_f32_16x16x32_bf16 v[82:85], v[154:157], v[202:205], v[82:85]
	v_mfma_f32_16x16x32_bf16 v[70:73], v[146:149], v[210:213], v[70:73]
	v_mfma_f32_16x16x32_bf16 v[66:69], v[154:157], v[210:213], v[66:69]
	v_mfma_f32_16x16x32_bf16 v[102:105], v[150:153], v[172:175], v[102:105]
	v_mfma_f32_16x16x32_bf16 v[98:101], v[158:161], v[172:175], v[98:101]
	v_mfma_f32_16x16x32_bf16 v[118:121], v[150:153], v[198:201], v[118:121]
	v_mfma_f32_16x16x32_bf16 v[110:113], v[158:161], v[198:201], v[110:113]
	v_mfma_f32_16x16x32_bf16 v[86:89], v[150:153], v[206:209], v[86:89]
	v_mfma_f32_16x16x32_bf16 v[82:85], v[158:161], v[206:209], v[82:85]
	v_mfma_f32_16x16x32_bf16 v[70:73], v[150:153], v[214:217], v[70:73]
	v_mfma_f32_16x16x32_bf16 v[66:69], v[158:161], v[214:217], v[66:69]
	s_setprio 0
	s_barrier
	s_add_i32 s14, s14, s4
	v_lshl_add_u64 v[180:181], s[40:41], 0, v[0:1]
	s_mov_b32 m0, s14
	ds_read_b128 v[168:171], v185 offset:16384
	ds_read_b128 v[172:175], v185 offset:17408
	ds_read_b128 v[176:179], v185 offset:18432
	ds_read_b128 v[198:201], v185 offset:19456
	ds_read_b128 v[202:205], v185 offset:20480
	ds_read_b128 v[206:209], v185 offset:21504
	ds_read_b128 v[210:213], v185 offset:22528
	ds_read_b128 v[214:217], v185 offset:23552
	global_load_lds_dwordx4 v[180:181], off
	s_add_i32 m0, s14, 0x2000
	s_add_u32 s14, s40, 0x160000
	v_lshl_add_u64 v[186:187], s[40:41], 0, v[162:163]
	s_addc_u32 s15, s41, 0
	s_add_i32 s20, s20, s4
	global_load_lds_dwordx4 v[186:187], off
	v_lshl_add_u64 v[218:219], s[14:15], 0, v[0:1]
	s_mov_b32 m0, s20
	global_load_lds_dwordx4 v[218:219], off
	v_lshl_add_u64 v[218:219], s[14:15], 0, v[162:163]
	s_add_i32 m0, s20, 0x2000
	s_nop 0
	global_load_lds_dwordx4 v[218:219], off
	s_waitcnt vmcnt(6)
	s_waitcnt lgkmcnt(0)
	s_barrier
; #define PG8_STAGE(bufoff, gbase, voff) do { _Pragma("unroll") for (int _i = 0; _i < 2; ++_i) \
;         __builtin_amdgcn_global_load_lds((const unsigned*)((const char*)(gbase) + (voff)[_i]), (LAS unsigned*)(lds + (bufoff) + ldsw + _i * 8192), 16, 0, 0); } while (0)
; #define PG8_LDA(dst, b, h) do { _Pragma("unroll") for (int m = 0; m < 4; ++m) _Pragma("unroll") for (int k = 0; k < 2; ++k) dst[m][k] = *(const LAS bf16x8*)(lds + PG8_SA(b, h) + aoff + m * 2048 + k * 1024); } while (0)
; #define PG8_LDB(dst, b, h) do { _Pragma("unroll") for (int n = 0; n < 2; ++n) _Pragma("unroll") for (int k = 0; k < 2; ++k) dst[n][k] = *(const LAS bf16x8*)(lds + PG8_SB(b, h) + boff + n * 2048 + k * 1024); } while (0)
; #define PG8_MMA(ai, bj, At, Bt) do { __builtin_amdgcn_s_setprio(1); _Pragma("unroll") for (int m = 0; m < 4; ++m) _Pragma("unroll") for (int n = 0; n < 2; ++n) _Pragma("unroll") for (int k = 0; k < 2; ++k) \
;         acc[ai][bj][m][n] = __builtin_amdgcn_mfma_f32_16x16x32_bf16(Bt[n][k], At[m][k], acc[ai][bj][m][n], 0, 0, 0); __builtin_amdgcn_s_setprio(0); } while (0)
; #define PG8_WAIT_V(n) asm volatile("s_waitcnt vmcnt(" #n ")" ::: "memory")
; #define PG8_WAIT_L(n) asm volatile("s_waitcnt lgkmcnt(" #n ")" ::: "memory")
; #define PG8_BAR __builtin_amdgcn_s_barrier()
; #define PG8_SCHED __builtin_amdgcn_sched_barrier(0)
; template <class Epi, class Sched, bool ALIGN_EPI = false, bool SP2 = false>
; __device__ __forceinline__ void gemm_phase(LAS unsigned char* lds, const Gemm g, const Sched& S, const Epi& E) {
;     ...
;             PG8_WAIT_V(8); PG8_WAIT_L(0); PG8_BAR; PG8_MMA(1, 0, At, B0); PG8_MMA(1, 1, At, B1); PG8_BAR; PG8_SCHED;
;             PG8_LDB(B0, 1, 0); PG8_LDB(B1, 1, 1); PG8_SCHED; PG8_LDA(At, 1, 0); PG8_STAGE(PG8_SA(0, 1), a2 + hstep, voffA);
	s_setprio 1
	s_waitcnt lgkmcnt(0)
	v_mfma_f32_16x16x32_bf16 v[62:65], v[130:133], v[168:171], v[62:65]
	v_mfma_f32_16x16x32_bf16 v[58:61], v[138:141], v[168:171], v[58:61]
	v_mfma_f32_16x16x32_bf16 v[46:49], v[130:133], v[176:179], v[46:49]
	v_mfma_f32_16x16x32_bf16 v[42:45], v[138:141], v[176:179], v[42:45]
	v_mfma_f32_16x16x32_bf16 v[34:37], v[130:133], v[202:205], v[34:37]
	v_mfma_f32_16x16x32_bf16 v[26:29], v[138:141], v[202:205], v[26:29]
	v_mfma_f32_16x16x32_bf16 v[18:21], v[130:133], v[210:213], v[18:21]
	v_mfma_f32_16x16x32_bf16 v[10:13], v[138:141], v[210:213], v[10:13]
	v_mfma_f32_16x16x32_bf16 v[62:65], v[134:137], v[172:175], v[62:65]
	v_mfma_f32_16x16x32_bf16 v[58:61], v[142:145], v[172:175], v[58:61]
	v_mfma_f32_16x16x32_bf16 v[46:49], v[134:137], v[198:201], v[46:49]
	v_mfma_f32_16x16x32_bf16 v[42:45], v[142:145], v[198:201], v[42:45]
	v_mfma_f32_16x16x32_bf16 v[34:37], v[134:137], v[206:209], v[34:37]
	v_mfma_f32_16x16x32_bf16 v[26:29], v[142:145], v[206:209], v[26:29]
	v_mfma_f32_16x16x32_bf16 v[18:21], v[134:137], v[214:217], v[18:21]
	v_mfma_f32_16x16x32_bf16 v[10:13], v[142:145], v[214:217], v[10:13]
	s_setprio 0
	s_setprio 1
	v_mfma_f32_16x16x32_bf16 v[54:57], v[146:149], v[168:171], v[54:57]
	v_mfma_f32_16x16x32_bf16 v[50:53], v[154:157], v[168:171], v[50:53]
	v_mfma_f32_16x16x32_bf16 v[38:41], v[146:149], v[176:179], v[38:41]
	v_mfma_f32_16x16x32_bf16 v[30:33], v[154:157], v[176:179], v[30:33]
	v_mfma_f32_16x16x32_bf16 v[22:25], v[146:149], v[202:205], v[22:25]
	v_mfma_f32_16x16x32_bf16 v[14:17], v[154:157], v[202:205], v[14:17]
	v_mfma_f32_16x16x32_bf16 v[6:9], v[146:149], v[210:213], v[6:9]
	v_mfma_f32_16x16x32_bf16 v[2:5], v[154:157], v[210:213], v[2:5]
	v_mfma_f32_16x16x32_bf16 v[54:57], v[150:153], v[172:175], v[54:57]
	v_mfma_f32_16x16x32_bf16 v[50:53], v[158:161], v[172:175], v[50:53]
	v_mfma_f32_16x16x32_bf16 v[38:41], v[150:153], v[198:201], v[38:41]
	v_mfma_f32_16x16x32_bf16 v[30:33], v[158:161], v[198:201], v[30:33]
	v_mfma_f32_16x16x32_bf16 v[22:25], v[150:153], v[206:209], v[22:25]
	v_mfma_f32_16x16x32_bf16 v[14:17], v[158:161], v[206:209], v[14:17]
	v_mfma_f32_16x16x32_bf16 v[6:9], v[150:153], v[214:217], v[6:9]
	v_mfma_f32_16x16x32_bf16 v[2:5], v[158:161], v[214:217], v[2:5]
	s_setprio 0
	s_barrier
	s_add_i32 s20, 0, 0x18000
	s_add_i32 s21, 0, 0x1c000
	v_add_u32_e32 v142, s20, v183
	v_add_u32_e32 v158, s21, v183
	ds_read_b128 v[130:133], v142
	ds_read_b128 v[134:137], v142 offset:1024
	ds_read_b128 v[138:141], v142 offset:2048
	ds_read_b128 v[142:145], v142 offset:3072
	ds_read_b128 v[146:149], v158
	ds_read_b128 v[150:153], v158 offset:1024
	ds_read_b128 v[154:157], v158 offset:2048
	ds_read_b128 v[158:161], v158 offset:3072
	s_add_u32 s14, s42, 0x160000
	s_addc_u32 s15, s43, 0
	s_mov_b32 m0, s45
	v_lshl_add_u64 v[236:237], s[14:15], 0, v[0:1]
	ds_read_b128 v[168:171], v185 offset:32768
	ds_read_b128 v[172:175], v185 offset:33792
	ds_read_b128 v[176:179], v185 offset:34816
	ds_read_b128 v[198:201], v185 offset:35840
	ds_read_b128 v[202:205], v185 offset:36864
	ds_read_b128 v[206:209], v185 offset:37888
	ds_read_b128 v[210:213], v185 offset:38912
	ds_read_b128 v[214:217], v185 offset:39936
	v_lshl_add_u64 v[218:219], s[42:43], 0, v[0:1]
	s_mov_b32 m0, s27
	v_lshl_add_u64 v[220:221], s[42:43], 0, v[162:163]
	global_load_lds_dwordx4 v[218:219], off
	s_mov_b32 m0, s44
	s_nop 0
	global_load_lds_dwordx4 v[220:221], off
	s_mov_b32 m0, s45
	s_nop 0
	global_load_lds_dwordx4 v[236:237], off
	v_lshl_add_u64 v[236:237], s[14:15], 0, v[162:163]
	s_mov_b32 m0, s46
	s_nop 0
	global_load_lds_dwordx4 v[236:237], off
	s_waitcnt vmcnt(8)
	s_waitcnt lgkmcnt(0)
	s_barrier
	s_setprio 1
	s_waitcnt lgkmcnt(0)
	v_mfma_f32_16x16x32_bf16 v[114:117], v[130:133], v[168:171], v[114:117]
	v_mfma_f32_16x16x32_bf16 v[106:109], v[138:141], v[168:171], v[106:109]
	v_mfma_f32_16x16x32_bf16 v[126:129], v[130:133], v[176:179], v[126:129]
	v_mfma_f32_16x16x32_bf16 v[122:125], v[138:141], v[176:179], v[122:125]
	v_mfma_f32_16x16x32_bf16 v[94:97], v[130:133], v[202:205], v[94:97]
	v_mfma_f32_16x16x32_bf16 v[90:93], v[138:141], v[202:205], v[90:93]
	v_mfma_f32_16x16x32_bf16 v[78:81], v[130:133], v[210:213], v[78:81]
	v_mfma_f32_16x16x32_bf16 v[74:77], v[138:141], v[210:213], v[74:77]
	v_mfma_f32_16x16x32_bf16 v[114:117], v[134:137], v[172:175], v[114:117]
	v_mfma_f32_16x16x32_bf16 v[106:109], v[142:145], v[172:175], v[106:109]
	v_mfma_f32_16x16x32_bf16 v[126:129], v[134:137], v[198:201], v[126:129]
	v_mfma_f32_16x16x32_bf16 v[122:125], v[142:145], v[198:201], v[122:125]
	v_mfma_f32_16x16x32_bf16 v[94:97], v[134:137], v[206:209], v[94:97]
	v_mfma_f32_16x16x32_bf16 v[90:93], v[142:145], v[206:209], v[90:93]
	v_mfma_f32_16x16x32_bf16 v[78:81], v[134:137], v[214:217], v[78:81]
	v_mfma_f32_16x16x32_bf16 v[74:77], v[142:145], v[214:217], v[74:77]
	s_setprio 0
	s_setprio 1
	v_mfma_f32_16x16x32_bf16 v[102:105], v[146:149], v[168:171], v[102:105]
	v_mfma_f32_16x16x32_bf16 v[98:101], v[154:157], v[168:171], v[98:101]
	v_mfma_f32_16x16x32_bf16 v[118:121], v[146:149], v[176:179], v[118:121]
	v_mfma_f32_16x16x32_bf16 v[110:113], v[154:157], v[176:179], v[110:113]
	v_mfma_f32_16x16x32_bf16 v[86:89], v[146:149], v[202:205], v[86:89]
	v_mfma_f32_16x16x32_bf16 v[82:85], v[154:157], v[202:205], v[82:85]
	v_mfma_f32_16x16x32_bf16 v[70:73], v[146:149], v[210:213], v[70:73]
	v_mfma_f32_16x16x32_bf16 v[66:69], v[154:157], v[210:213], v[66:69]
	v_mfma_f32_16x16x32_bf16 v[102:105], v[150:153], v[172:175], v[102:105]
	v_mfma_f32_16x16x32_bf16 v[98:101], v[158:161], v[172:175], v[98:101]
	v_mfma_f32_16x16x32_bf16 v[118:121], v[150:153], v[198:201], v[118:121]
	v_mfma_f32_16x16x32_bf16 v[110:113], v[158:161], v[198:201], v[110:113]
	v_mfma_f32_16x16x32_bf16 v[86:89], v[150:153], v[206:209], v[86:89]
	v_mfma_f32_16x16x32_bf16 v[82:85], v[158:161], v[206:209], v[82:85]
	v_mfma_f32_16x16x32_bf16 v[70:73], v[150:153], v[214:217], v[70:73]
	v_mfma_f32_16x16x32_bf16 v[66:69], v[158:161], v[214:217], v[66:69]
	s_setprio 0
	s_barrier
; #define PG8_STAGE(bufoff, gbase, voff) do { _Pragma("unroll") for (int _i = 0; _i < 2; ++_i) \
;         __builtin_amdgcn_global_load_lds((const unsigned*)((const char*)(gbase) + (voff)[_i]), (LAS unsigned*)(lds + (bufoff) + ldsw + _i * 8192), 16, 0, 0); } while (0)
; #define PG8_LDA(dst, b, h) do { _Pragma("unroll") for (int m = 0; m < 4; ++m) _Pragma("unroll") for (int k = 0; k < 2; ++k) dst[m][k] = *(const LAS bf16x8*)(lds + PG8_SA(b, h) + aoff + m * 2048 + k * 1024); } while (0)
; #define PG8_MMA(ai, bj, At, Bt) do { __builtin_amdgcn_s_setprio(1); _Pragma("unroll") for (int m = 0; m < 4; ++m) _Pragma("unroll") for (int n = 0; n < 2; ++n) _Pragma("unroll") for (int k = 0; k < 2; ++k) \
;         acc[ai][bj][m][n] = __builtin_amdgcn_mfma_f32_16x16x32_bf16(Bt[n][k], At[m][k], acc[ai][bj][m][n], 0, 0, 0); __builtin_amdgcn_s_setprio(0); } while (0)
; #define PG8_WAIT_V(n) asm volatile("s_waitcnt vmcnt(" #n ")" ::: "memory")
; #define PG8_WAIT_L(n) asm volatile("s_waitcnt lgkmcnt(" #n ")" ::: "memory")
; #define PG8_BAR __builtin_amdgcn_s_barrier()
; #define PG8_SCHED __builtin_amdgcn_sched_barrier(0)
; template <class Epi, class Sched, bool ALIGN_EPI = false, bool SP2 = false>
; __device__ __forceinline__ void gemm_phase(LAS unsigned char* lds, const Gemm g, const Sched& S, const Epi& E) {
;     ...
;             PG8_LDA(At, 1, 1); PG8_STAGE(PG8_SB(1, 0), b3, voffB); PG8_STAGE(PG8_SB(1, 1), b3 + hstep, voffB); PG8_STAGE(PG8_SA(1, 0), a3, voffA);
;             PG8_WAIT_V(8); PG8_WAIT_L(0); PG8_BAR; PG8_MMA(1, 0, At, B0); PG8_MMA(1, 1, At, B1); PG8_BAR; PG8_SCHED;
;     ...
;         if constexpr (ALIGN_EPI) { if (wr == 0) PG8_BAR; }
	s_add_i32 s14, s20, s4
	v_lshl_add_u64 v[180:181], v[180:181], 0, s[18:19]
	s_mov_b32 m0, s14
	ds_read_b128 v[168:171], v185 offset:49152
	ds_read_b128 v[172:175], v185 offset:50176
	ds_read_b128 v[176:179], v185 offset:51200
	ds_read_b128 v[198:201], v185 offset:52224
	ds_read_b128 v[202:205], v185 offset:53248
	ds_read_b128 v[206:209], v185 offset:54272
	ds_read_b128 v[210:213], v185 offset:55296
	ds_read_b128 v[214:217], v185 offset:56320
	global_load_lds_dwordx4 v[180:181], off
	s_add_i32 m0, s14, 0x2000
	s_add_u32 s14, s40, 0x160080
	v_lshl_add_u64 v[180:181], v[186:187], 0, s[18:19]
	s_addc_u32 s15, s41, 0
	s_add_i32 s20, s21, s4
	global_load_lds_dwordx4 v[180:181], off
	v_lshl_add_u64 v[180:181], s[14:15], 0, v[0:1]
	s_mov_b32 m0, s20
	s_nop 0
	global_load_lds_dwordx4 v[180:181], off
	v_lshl_add_u64 v[180:181], s[14:15], 0, v[162:163]
	s_add_i32 m0, s20, 0x2000
	s_nop 0
	global_load_lds_dwordx4 v[180:181], off
	v_lshl_add_u64 v[180:181], v[218:219], 0, s[18:19]
	s_mov_b32 m0, s13
	s_nop 0
	global_load_lds_dwordx4 v[180:181], off
	v_lshl_add_u64 v[180:181], v[220:221], 0, s[18:19]
	s_mov_b32 m0, s47
	s_nop 0
	global_load_lds_dwordx4 v[180:181], off
	s_waitcnt vmcnt(8)
	s_waitcnt lgkmcnt(0)
	s_barrier
	s_setprio 1
	s_waitcnt lgkmcnt(0)
	v_mfma_f32_16x16x32_bf16 v[62:65], v[130:133], v[168:171], v[62:65]
	v_mfma_f32_16x16x32_bf16 v[58:61], v[138:141], v[168:171], v[58:61]
	v_mfma_f32_16x16x32_bf16 v[46:49], v[130:133], v[176:179], v[46:49]
	v_mfma_f32_16x16x32_bf16 v[42:45], v[138:141], v[176:179], v[42:45]
	v_mfma_f32_16x16x32_bf16 v[34:37], v[130:133], v[202:205], v[34:37]
	v_mfma_f32_16x16x32_bf16 v[26:29], v[138:141], v[202:205], v[26:29]
	v_mfma_f32_16x16x32_bf16 v[18:21], v[130:133], v[210:213], v[18:21]
	v_mfma_f32_16x16x32_bf16 v[10:13], v[138:141], v[210:213], v[10:13]
	v_mfma_f32_16x16x32_bf16 v[62:65], v[134:137], v[172:175], v[62:65]
	v_mfma_f32_16x16x32_bf16 v[58:61], v[142:145], v[172:175], v[58:61]
	v_mfma_f32_16x16x32_bf16 v[46:49], v[134:137], v[198:201], v[46:49]
	v_mfma_f32_16x16x32_bf16 v[42:45], v[142:145], v[198:201], v[42:45]
	v_mfma_f32_16x16x32_bf16 v[34:37], v[134:137], v[206:209], v[34:37]
	v_mfma_f32_16x16x32_bf16 v[26:29], v[142:145], v[206:209], v[26:29]
	v_mfma_f32_16x16x32_bf16 v[18:21], v[134:137], v[214:217], v[18:21]
	v_mfma_f32_16x16x32_bf16 v[10:13], v[142:145], v[214:217], v[10:13]
	s_setprio 0
	s_setprio 1
	v_mfma_f32_16x16x32_bf16 v[54:57], v[146:149], v[168:171], v[54:57]
	v_mfma_f32_16x16x32_bf16 v[50:53], v[154:157], v[168:171], v[50:53]
	v_mfma_f32_16x16x32_bf16 v[38:41], v[146:149], v[176:179], v[38:41]
	v_mfma_f32_16x16x32_bf16 v[30:33], v[154:157], v[176:179], v[30:33]
	v_mfma_f32_16x16x32_bf16 v[22:25], v[146:149], v[202:205], v[22:25]
	v_mfma_f32_16x16x32_bf16 v[14:17], v[154:157], v[202:205], v[14:17]
	v_mfma_f32_16x16x32_bf16 v[6:9], v[146:149], v[210:213], v[6:9]
	v_mfma_f32_16x16x32_bf16 v[2:5], v[154:157], v[210:213], v[2:5]
	v_mfma_f32_16x16x32_bf16 v[54:57], v[150:153], v[172:175], v[54:57]
	v_mfma_f32_16x16x32_bf16 v[50:53], v[158:161], v[172:175], v[50:53]
	v_mfma_f32_16x16x32_bf16 v[38:41], v[150:153], v[198:201], v[38:41]
	v_mfma_f32_16x16x32_bf16 v[30:33], v[158:161], v[198:201], v[30:33]
	v_mfma_f32_16x16x32_bf16 v[22:25], v[150:153], v[206:209], v[22:25]
	v_mfma_f32_16x16x32_bf16 v[14:17], v[158:161], v[206:209], v[14:17]
	v_mfma_f32_16x16x32_bf16 v[6:9], v[150:153], v[214:217], v[6:9]
	v_mfma_f32_16x16x32_bf16 v[2:5], v[158:161], v[214:217], v[2:5]
	s_setprio 0
	s_barrier
	s_add_i32 s69, s69, 2
	s_add_u32 s67, s67, 0x100
	s_addc_u32 s68, s68, 0
	s_cmpk_gt_u32 s69, 0x55
	s_mov_b64 s[34:35], s[38:39]
	s_cbranch_scc0 .LBB0_768
	s_and_b64 vcc, exec, s[8:9]
	s_cbranch_vccz .LBB0_771
	s_barrier
